# prompt DSA path: QK tiles unrolled with 2-tile K prefetch and parallel bias epilogue, branch-free candidate push, prune search skips empty registers and compaction preloads ids
# speedup vs baseline: 1.0654x; 1.0283x over previous
; #define DSA_LOADK(KT) do { const int kt_ = (KT); if (kt_ < ntiles) { _Pragma("unroll") for (int t_ = 0; t_ < 4; ++t_) { const h16* p_ = key_row(ws, s, (kt_ + t_) * 16 + fr, C_KI, WS_CKI, 64); \
;         nK[t_][0] = __builtin_bit_cast(h16x8, *(const u32x4*)(p_ + fq * 8)); nK[t_][1] = __builtin_bit_cast(h16x8, *(const u32x4*)(p_ + 32 + fq * 8)); } } } while (0)
; __device__ __forceinline__ void dsa_unit(int wv, const Args& A, LAS unsigned char* lds, int s, int qt) {
;     ...
;     for (int kt0 = 0; kt0 < ntiles; kt0 += 32) {
;         const int kt = kt0 + 4 * w;
;         h16x8 kc[4][2];
; #pragma unroll
;         for (int t = 0; t < 4; ++t) { kc[t][0] = nK[t][0]; kc[t][1] = nK[t][1]; }
;         DSA_LOADK(kt + 32);
;         if (kt < ntiles) {
;             f32x4 sc[4];
; #pragma unroll
;             for (int t = 0; t < 4; ++t) sc[t] = (f32x4){0.f, 0.f, 0.f, 0.f};
; #pragma unroll 2
;             for (int hh = 0; hh < 16; ++hh) {
;                 const h16x8 q0 = __builtin_bit_cast(h16x8, Ql[(hh * 2) * 64 + lane]), q1 = __builtin_bit_cast(h16x8, Ql[(hh * 2 + 1) * 64 + lane]);
;                 const float wh = wql[hh * 16 + fr];
;                 f32x4 a[4];
; #pragma unroll
;                 for (int t = 0; t < 4; ++t) a[t] = __builtin_amdgcn_mfma_f32_16x16x32_f16(kc[t][0], q0, (f32x4){0.f, 0.f, 0.f, 0.f}, 0, 0, 0);
; #pragma unroll
;                 for (int t = 0; t < 4; ++t) a[t] = __builtin_amdgcn_mfma_f32_16x16x32_f16(kc[t][1], q1, a[t], 0, 0, 0);
; #pragma unroll
;                 for (int t = 0; t < 4; ++t)
; #pragma unroll
;                     for (int r = 0; r < 4; ++r) sc[t][r] += wh * fabsf(a[t][r]);
;             }
.LBB0_934:
	s_cmp_ge_i32 s70, s81
	s_cbranch_scc1 .LBB0_1001
	v_mov_b32_e32 v66, 0
	v_mov_b32_e32 v67, 0
	v_mov_b32_e32 v68, 0
	v_mov_b32_e32 v69, 0
	v_mov_b32_e32 v70, 0
	v_mov_b32_e32 v71, 0
	v_mov_b32_e32 v72, 0
	v_mov_b32_e32 v73, 0
	v_mov_b32_e32 v74, 0
	v_mov_b32_e32 v75, 0
	v_mov_b32_e32 v76, 0
	v_mov_b32_e32 v77, 0
	v_mov_b32_e32 v78, 0
	v_mov_b32_e32 v79, 0
	v_mov_b32_e32 v80, 0
	v_mov_b32_e32 v81, 0
	v_add_u32_e32 v145, 0x25480, v109
	ds_read_b128 v[178:181], v112
	ds_read_b128 v[182:185], v112 offset:1024
	ds_read_b32 v186, v145
	ds_read_b128 v[188:191], v112 offset:2048
	ds_read_b128 v[192:195], v112 offset:3072
	ds_read_b32 v196, v145 offset:64
	s_waitcnt lgkmcnt(5)
	v_mfma_f32_16x16x32_f16 v[208:211], v[58:61], v[178:181], 0
	v_mfma_f32_16x16x32_f16 v[212:215], v[62:65], v[178:181], 0
	v_mfma_f32_16x16x32_f16 v[216:219], v[46:49], v[178:181], 0
	v_mfma_f32_16x16x32_f16 v[220:223], v[42:45], v[178:181], 0
	s_waitcnt lgkmcnt(4)
	v_mfma_f32_16x16x32_f16 v[208:211], v[54:57], v[182:185], v[208:211]
	v_mfma_f32_16x16x32_f16 v[212:215], v[50:53], v[182:185], v[212:215]
	v_mfma_f32_16x16x32_f16 v[216:219], v[38:41], v[182:185], v[216:219]
	v_mfma_f32_16x16x32_f16 v[220:223], v[34:37], v[182:185], v[220:223]
	ds_read_b128 v[198:201], v112 offset:4096
	ds_read_b128 v[202:205], v112 offset:5120
	ds_read_b32 v206, v145 offset:128
	s_waitcnt lgkmcnt(3)
	v_mfma_f32_16x16x32_f16 v[224:227], v[58:61], v[188:191], 0
	v_fma_f32 v74, |v208|, v186, v74
	v_fma_f32 v75, |v209|, v186, v75
	v_mfma_f32_16x16x32_f16 v[228:231], v[62:65], v[188:191], 0
	v_fma_f32 v76, |v210|, v186, v76
	v_fma_f32 v77, |v211|, v186, v77
	v_mfma_f32_16x16x32_f16 v[232:235], v[46:49], v[188:191], 0
	v_fma_f32 v78, |v212|, v186, v78
	v_fma_f32 v79, |v213|, v186, v79
	v_mfma_f32_16x16x32_f16 v[240:243], v[42:45], v[188:191], 0
	v_fma_f32 v80, |v214|, v186, v80
	v_fma_f32 v81, |v215|, v186, v81
	v_mfma_f32_16x16x32_f16 v[224:227], v[54:57], v[192:195], v[224:227]
	v_fma_f32 v70, |v216|, v186, v70
	v_fma_f32 v71, |v217|, v186, v71
	v_mfma_f32_16x16x32_f16 v[228:231], v[50:53], v[192:195], v[228:231]
	v_fma_f32 v72, |v218|, v186, v72
	v_fma_f32 v73, |v219|, v186, v73
	v_mfma_f32_16x16x32_f16 v[232:235], v[38:41], v[192:195], v[232:235]
	v_fma_f32 v66, |v220|, v186, v66
	v_fma_f32 v67, |v221|, v186, v67
	v_mfma_f32_16x16x32_f16 v[240:243], v[34:37], v[192:195], v[240:243]
	v_fma_f32 v68, |v222|, v186, v68
	v_fma_f32 v69, |v223|, v186, v69
	ds_read_b128 v[178:181], v112 offset:6144
	ds_read_b128 v[182:185], v112 offset:7168
	ds_read_b32 v186, v145 offset:192
	s_waitcnt lgkmcnt(3)
	v_mfma_f32_16x16x32_f16 v[208:211], v[58:61], v[198:201], 0
	v_fma_f32 v74, |v224|, v196, v74
	v_fma_f32 v75, |v225|, v196, v75
	v_mfma_f32_16x16x32_f16 v[212:215], v[62:65], v[198:201], 0
	v_fma_f32 v76, |v226|, v196, v76
	v_fma_f32 v77, |v227|, v196, v77
	v_mfma_f32_16x16x32_f16 v[216:219], v[46:49], v[198:201], 0
	v_fma_f32 v78, |v228|, v196, v78
	v_fma_f32 v79, |v229|, v196, v79
	v_mfma_f32_16x16x32_f16 v[220:223], v[42:45], v[198:201], 0
	v_fma_f32 v80, |v230|, v196, v80
	v_fma_f32 v81, |v231|, v196, v81
	v_mfma_f32_16x16x32_f16 v[208:211], v[54:57], v[202:205], v[208:211]
	v_fma_f32 v70, |v232|, v196, v70
	v_fma_f32 v71, |v233|, v196, v71
	v_mfma_f32_16x16x32_f16 v[212:215], v[50:53], v[202:205], v[212:215]
	v_fma_f32 v72, |v234|, v196, v72
	v_fma_f32 v73, |v235|, v196, v73
	v_mfma_f32_16x16x32_f16 v[216:219], v[38:41], v[202:205], v[216:219]
	v_fma_f32 v66, |v240|, v196, v66
	v_fma_f32 v67, |v241|, v196, v67
	v_mfma_f32_16x16x32_f16 v[220:223], v[34:37], v[202:205], v[220:223]
	v_fma_f32 v68, |v242|, v196, v68
	v_fma_f32 v69, |v243|, v196, v69
	ds_read_b128 v[188:191], v112 offset:8192
	ds_read_b128 v[192:195], v112 offset:9216
	ds_read_b32 v196, v145 offset:256
	s_waitcnt lgkmcnt(3)
	v_mfma_f32_16x16x32_f16 v[224:227], v[58:61], v[178:181], 0
	v_fma_f32 v74, |v208|, v206, v74
	v_fma_f32 v75, |v209|, v206, v75
	v_mfma_f32_16x16x32_f16 v[228:231], v[62:65], v[178:181], 0
	v_fma_f32 v76, |v210|, v206, v76
	v_fma_f32 v77, |v211|, v206, v77
	v_mfma_f32_16x16x32_f16 v[232:235], v[46:49], v[178:181], 0
	v_fma_f32 v78, |v212|, v206, v78
	v_fma_f32 v79, |v213|, v206, v79
	v_mfma_f32_16x16x32_f16 v[240:243], v[42:45], v[178:181], 0
	v_fma_f32 v80, |v214|, v206, v80
	v_fma_f32 v81, |v215|, v206, v81
	v_mfma_f32_16x16x32_f16 v[224:227], v[54:57], v[182:185], v[224:227]
	v_fma_f32 v70, |v216|, v206, v70
	v_fma_f32 v71, |v217|, v206, v71
	v_mfma_f32_16x16x32_f16 v[228:231], v[50:53], v[182:185], v[228:231]
	v_fma_f32 v72, |v218|, v206, v72
	v_fma_f32 v73, |v219|, v206, v73
	v_mfma_f32_16x16x32_f16 v[232:235], v[38:41], v[182:185], v[232:235]
	v_fma_f32 v66, |v220|, v206, v66
	v_fma_f32 v67, |v221|, v206, v67
	v_mfma_f32_16x16x32_f16 v[240:243], v[34:37], v[182:185], v[240:243]
	v_fma_f32 v68, |v222|, v206, v68
	v_fma_f32 v69, |v223|, v206, v69
	ds_read_b128 v[198:201], v112 offset:10240
	ds_read_b128 v[202:205], v112 offset:11264
	ds_read_b32 v206, v145 offset:320
	s_waitcnt lgkmcnt(3)
	v_mfma_f32_16x16x32_f16 v[208:211], v[58:61], v[188:191], 0
	v_fma_f32 v74, |v224|, v186, v74
	v_fma_f32 v75, |v225|, v186, v75
	v_mfma_f32_16x16x32_f16 v[212:215], v[62:65], v[188:191], 0
	v_fma_f32 v76, |v226|, v186, v76
	v_fma_f32 v77, |v227|, v186, v77
	v_mfma_f32_16x16x32_f16 v[216:219], v[46:49], v[188:191], 0
	v_fma_f32 v78, |v228|, v186, v78
	v_fma_f32 v79, |v229|, v186, v79
	v_mfma_f32_16x16x32_f16 v[220:223], v[42:45], v[188:191], 0
	v_fma_f32 v80, |v230|, v186, v80
	v_fma_f32 v81, |v231|, v186, v81
	v_mfma_f32_16x16x32_f16 v[208:211], v[54:57], v[192:195], v[208:211]
	v_fma_f32 v70, |v232|, v186, v70
	v_fma_f32 v71, |v233|, v186, v71
	v_mfma_f32_16x16x32_f16 v[212:215], v[50:53], v[192:195], v[212:215]
	v_fma_f32 v72, |v234|, v186, v72
	v_fma_f32 v73, |v235|, v186, v73
	v_mfma_f32_16x16x32_f16 v[216:219], v[38:41], v[192:195], v[216:219]
	v_fma_f32 v66, |v240|, v186, v66
	v_fma_f32 v67, |v241|, v186, v67
	v_mfma_f32_16x16x32_f16 v[220:223], v[34:37], v[192:195], v[220:223]
	v_fma_f32 v68, |v242|, v186, v68
	v_fma_f32 v69, |v243|, v186, v69
	ds_read_b128 v[178:181], v112 offset:12288
	ds_read_b128 v[182:185], v112 offset:13312
	ds_read_b32 v186, v145 offset:384
	s_waitcnt lgkmcnt(3)
; __device__ __forceinline__ void dsa_unit(int wv, const Args& A, LAS unsigned char* lds, int s, int qt) {
;     ...
;             for (int hh = 0; hh < 16; ++hh) {
;                 const h16x8 q0 = __builtin_bit_cast(h16x8, Ql[(hh * 2) * 64 + lane]), q1 = __builtin_bit_cast(h16x8, Ql[(hh * 2 + 1) * 64 + lane]);
;                 const float wh = wql[hh * 16 + fr];
;                 f32x4 a[4];
; #pragma unroll
;                 for (int t = 0; t < 4; ++t) a[t] = __builtin_amdgcn_mfma_f32_16x16x32_f16(kc[t][0], q0, (f32x4){0.f, 0.f, 0.f, 0.f}, 0, 0, 0);
; #pragma unroll
;                 for (int t = 0; t < 4; ++t) a[t] = __builtin_amdgcn_mfma_f32_16x16x32_f16(kc[t][1], q1, a[t], 0, 0, 0);
; #pragma unroll
;                 for (int t = 0; t < 4; ++t)
; #pragma unroll
;                     for (int r = 0; r < 4; ++r) sc[t][r] += wh * fabsf(a[t][r]);
;             }
	v_mfma_f32_16x16x32_f16 v[224:227], v[58:61], v[198:201], 0
	v_fma_f32 v74, |v208|, v196, v74
	v_fma_f32 v75, |v209|, v196, v75
	v_mfma_f32_16x16x32_f16 v[228:231], v[62:65], v[198:201], 0
	v_fma_f32 v76, |v210|, v196, v76
	v_fma_f32 v77, |v211|, v196, v77
	v_mfma_f32_16x16x32_f16 v[232:235], v[46:49], v[198:201], 0
	v_fma_f32 v78, |v212|, v196, v78
	v_fma_f32 v79, |v213|, v196, v79
	v_mfma_f32_16x16x32_f16 v[240:243], v[42:45], v[198:201], 0
	v_fma_f32 v80, |v214|, v196, v80
	v_fma_f32 v81, |v215|, v196, v81
	v_mfma_f32_16x16x32_f16 v[224:227], v[54:57], v[202:205], v[224:227]
	v_fma_f32 v70, |v216|, v196, v70
	v_fma_f32 v71, |v217|, v196, v71
	v_mfma_f32_16x16x32_f16 v[228:231], v[50:53], v[202:205], v[228:231]
	v_fma_f32 v72, |v218|, v196, v72
	v_fma_f32 v73, |v219|, v196, v73
	v_mfma_f32_16x16x32_f16 v[232:235], v[38:41], v[202:205], v[232:235]
	v_fma_f32 v66, |v220|, v196, v66
	v_fma_f32 v67, |v221|, v196, v67
	v_mfma_f32_16x16x32_f16 v[240:243], v[34:37], v[202:205], v[240:243]
	v_fma_f32 v68, |v222|, v196, v68
	v_fma_f32 v69, |v223|, v196, v69
	ds_read_b128 v[188:191], v112 offset:14336
	ds_read_b128 v[192:195], v112 offset:15360
	ds_read_b32 v196, v145 offset:448
	s_waitcnt lgkmcnt(3)
	v_mfma_f32_16x16x32_f16 v[208:211], v[58:61], v[178:181], 0
	v_fma_f32 v74, |v224|, v206, v74
	v_fma_f32 v75, |v225|, v206, v75
	v_mfma_f32_16x16x32_f16 v[212:215], v[62:65], v[178:181], 0
	v_fma_f32 v76, |v226|, v206, v76
	v_fma_f32 v77, |v227|, v206, v77
	v_mfma_f32_16x16x32_f16 v[216:219], v[46:49], v[178:181], 0
	v_fma_f32 v78, |v228|, v206, v78
	v_fma_f32 v79, |v229|, v206, v79
	v_mfma_f32_16x16x32_f16 v[220:223], v[42:45], v[178:181], 0
	v_fma_f32 v80, |v230|, v206, v80
	v_fma_f32 v81, |v231|, v206, v81
	v_mfma_f32_16x16x32_f16 v[208:211], v[54:57], v[182:185], v[208:211]
	v_fma_f32 v70, |v232|, v206, v70
	v_fma_f32 v71, |v233|, v206, v71
	v_mfma_f32_16x16x32_f16 v[212:215], v[50:53], v[182:185], v[212:215]
	v_fma_f32 v72, |v234|, v206, v72
	v_fma_f32 v73, |v235|, v206, v73
	v_mfma_f32_16x16x32_f16 v[216:219], v[38:41], v[182:185], v[216:219]
	v_fma_f32 v66, |v240|, v206, v66
	v_fma_f32 v67, |v241|, v206, v67
	v_mfma_f32_16x16x32_f16 v[220:223], v[34:37], v[182:185], v[220:223]
	v_fma_f32 v68, |v242|, v206, v68
	v_fma_f32 v69, |v243|, v206, v69
	ds_read_b128 v[198:201], v112 offset:16384
	ds_read_b128 v[202:205], v112 offset:17408
	ds_read_b32 v206, v145 offset:512
	s_waitcnt lgkmcnt(3)
	v_mfma_f32_16x16x32_f16 v[224:227], v[58:61], v[188:191], 0
	v_fma_f32 v74, |v208|, v186, v74
	v_fma_f32 v75, |v209|, v186, v75
	v_mfma_f32_16x16x32_f16 v[228:231], v[62:65], v[188:191], 0
	v_fma_f32 v76, |v210|, v186, v76
	v_fma_f32 v77, |v211|, v186, v77
	v_mfma_f32_16x16x32_f16 v[232:235], v[46:49], v[188:191], 0
	v_fma_f32 v78, |v212|, v186, v78
	v_fma_f32 v79, |v213|, v186, v79
	v_mfma_f32_16x16x32_f16 v[240:243], v[42:45], v[188:191], 0
	v_fma_f32 v80, |v214|, v186, v80
	v_fma_f32 v81, |v215|, v186, v81
	v_mfma_f32_16x16x32_f16 v[224:227], v[54:57], v[192:195], v[224:227]
	v_fma_f32 v70, |v216|, v186, v70
	v_fma_f32 v71, |v217|, v186, v71
	v_mfma_f32_16x16x32_f16 v[228:231], v[50:53], v[192:195], v[228:231]
	v_fma_f32 v72, |v218|, v186, v72
	v_fma_f32 v73, |v219|, v186, v73
	v_mfma_f32_16x16x32_f16 v[232:235], v[38:41], v[192:195], v[232:235]
	v_fma_f32 v66, |v220|, v186, v66
	v_fma_f32 v67, |v221|, v186, v67
	v_mfma_f32_16x16x32_f16 v[240:243], v[34:37], v[192:195], v[240:243]
	v_fma_f32 v68, |v222|, v186, v68
	v_fma_f32 v69, |v223|, v186, v69
	ds_read_b128 v[178:181], v112 offset:18432
	ds_read_b128 v[182:185], v112 offset:19456
	ds_read_b32 v186, v145 offset:576
	s_waitcnt lgkmcnt(3)
	v_mfma_f32_16x16x32_f16 v[208:211], v[58:61], v[198:201], 0
	v_fma_f32 v74, |v224|, v196, v74
	v_fma_f32 v75, |v225|, v196, v75
	v_mfma_f32_16x16x32_f16 v[212:215], v[62:65], v[198:201], 0
	v_fma_f32 v76, |v226|, v196, v76
	v_fma_f32 v77, |v227|, v196, v77
	v_mfma_f32_16x16x32_f16 v[216:219], v[46:49], v[198:201], 0
	v_fma_f32 v78, |v228|, v196, v78
	v_fma_f32 v79, |v229|, v196, v79
	v_mfma_f32_16x16x32_f16 v[220:223], v[42:45], v[198:201], 0
	v_fma_f32 v80, |v230|, v196, v80
	v_fma_f32 v81, |v231|, v196, v81
	v_mfma_f32_16x16x32_f16 v[208:211], v[54:57], v[202:205], v[208:211]
	v_fma_f32 v70, |v232|, v196, v70
	v_fma_f32 v71, |v233|, v196, v71
	v_mfma_f32_16x16x32_f16 v[212:215], v[50:53], v[202:205], v[212:215]
	v_fma_f32 v72, |v234|, v196, v72
	v_fma_f32 v73, |v235|, v196, v73
	v_mfma_f32_16x16x32_f16 v[216:219], v[38:41], v[202:205], v[216:219]
	v_fma_f32 v66, |v240|, v196, v66
	v_fma_f32 v67, |v241|, v196, v67
	v_mfma_f32_16x16x32_f16 v[220:223], v[34:37], v[202:205], v[220:223]
	v_fma_f32 v68, |v242|, v196, v68
	v_fma_f32 v69, |v243|, v196, v69
	ds_read_b128 v[188:191], v112 offset:20480
	ds_read_b128 v[192:195], v112 offset:21504
	ds_read_b32 v196, v145 offset:640
	s_waitcnt lgkmcnt(3)
	v_mfma_f32_16x16x32_f16 v[224:227], v[58:61], v[178:181], 0
	v_fma_f32 v74, |v208|, v206, v74
	v_fma_f32 v75, |v209|, v206, v75
	v_mfma_f32_16x16x32_f16 v[228:231], v[62:65], v[178:181], 0
	v_fma_f32 v76, |v210|, v206, v76
	v_fma_f32 v77, |v211|, v206, v77
	v_mfma_f32_16x16x32_f16 v[232:235], v[46:49], v[178:181], 0
	v_fma_f32 v78, |v212|, v206, v78
	v_fma_f32 v79, |v213|, v206, v79
	v_mfma_f32_16x16x32_f16 v[240:243], v[42:45], v[178:181], 0
	v_fma_f32 v80, |v214|, v206, v80
	v_fma_f32 v81, |v215|, v206, v81
	v_mfma_f32_16x16x32_f16 v[224:227], v[54:57], v[182:185], v[224:227]
	v_fma_f32 v70, |v216|, v206, v70
	v_fma_f32 v71, |v217|, v206, v71
	v_mfma_f32_16x16x32_f16 v[228:231], v[50:53], v[182:185], v[228:231]
	v_fma_f32 v72, |v218|, v206, v72
	v_fma_f32 v73, |v219|, v206, v73
	v_mfma_f32_16x16x32_f16 v[232:235], v[38:41], v[182:185], v[232:235]
	v_fma_f32 v66, |v220|, v206, v66
	v_fma_f32 v67, |v221|, v206, v67
	v_mfma_f32_16x16x32_f16 v[240:243], v[34:37], v[182:185], v[240:243]
	v_fma_f32 v68, |v222|, v206, v68
	v_fma_f32 v69, |v223|, v206, v69
	ds_read_b128 v[198:201], v112 offset:22528
	ds_read_b128 v[202:205], v112 offset:23552
	ds_read_b32 v206, v145 offset:704
	s_waitcnt lgkmcnt(3)
; __device__ __forceinline__ void dsa_unit(int wv, const Args& A, LAS unsigned char* lds, int s, int qt) {
;     ...
;             for (int hh = 0; hh < 16; ++hh) {
;                 const h16x8 q0 = __builtin_bit_cast(h16x8, Ql[(hh * 2) * 64 + lane]), q1 = __builtin_bit_cast(h16x8, Ql[(hh * 2 + 1) * 64 + lane]);
;                 const float wh = wql[hh * 16 + fr];
;                 f32x4 a[4];
; #pragma unroll
;                 for (int t = 0; t < 4; ++t) a[t] = __builtin_amdgcn_mfma_f32_16x16x32_f16(kc[t][0], q0, (f32x4){0.f, 0.f, 0.f, 0.f}, 0, 0, 0);
; #pragma unroll
;                 for (int t = 0; t < 4; ++t) a[t] = __builtin_amdgcn_mfma_f32_16x16x32_f16(kc[t][1], q1, a[t], 0, 0, 0);
; #pragma unroll
;                 for (int t = 0; t < 4; ++t)
; #pragma unroll
;                     for (int r = 0; r < 4; ++r) sc[t][r] += wh * fabsf(a[t][r]);
;             }
	v_mfma_f32_16x16x32_f16 v[208:211], v[58:61], v[188:191], 0
	v_fma_f32 v74, |v224|, v186, v74
	v_fma_f32 v75, |v225|, v186, v75
	v_mfma_f32_16x16x32_f16 v[212:215], v[62:65], v[188:191], 0
	v_fma_f32 v76, |v226|, v186, v76
	v_fma_f32 v77, |v227|, v186, v77
	v_mfma_f32_16x16x32_f16 v[216:219], v[46:49], v[188:191], 0
	v_fma_f32 v78, |v228|, v186, v78
	v_fma_f32 v79, |v229|, v186, v79
	v_mfma_f32_16x16x32_f16 v[220:223], v[42:45], v[188:191], 0
	v_fma_f32 v80, |v230|, v186, v80
	v_fma_f32 v81, |v231|, v186, v81
	v_mfma_f32_16x16x32_f16 v[208:211], v[54:57], v[192:195], v[208:211]
	v_fma_f32 v70, |v232|, v186, v70
	v_fma_f32 v71, |v233|, v186, v71
	v_mfma_f32_16x16x32_f16 v[212:215], v[50:53], v[192:195], v[212:215]
	v_fma_f32 v72, |v234|, v186, v72
	v_fma_f32 v73, |v235|, v186, v73
	v_mfma_f32_16x16x32_f16 v[216:219], v[38:41], v[192:195], v[216:219]
	v_fma_f32 v66, |v240|, v186, v66
	v_fma_f32 v67, |v241|, v186, v67
	v_mfma_f32_16x16x32_f16 v[220:223], v[34:37], v[192:195], v[220:223]
	v_fma_f32 v68, |v242|, v186, v68
	v_fma_f32 v69, |v243|, v186, v69
	ds_read_b128 v[178:181], v112 offset:24576
	ds_read_b128 v[182:185], v112 offset:25600
	ds_read_b32 v186, v145 offset:768
	s_waitcnt lgkmcnt(3)
	v_mfma_f32_16x16x32_f16 v[224:227], v[58:61], v[198:201], 0
	v_fma_f32 v74, |v208|, v196, v74
	v_fma_f32 v75, |v209|, v196, v75
	v_mfma_f32_16x16x32_f16 v[228:231], v[62:65], v[198:201], 0
	v_fma_f32 v76, |v210|, v196, v76
	v_fma_f32 v77, |v211|, v196, v77
	v_mfma_f32_16x16x32_f16 v[232:235], v[46:49], v[198:201], 0
	v_fma_f32 v78, |v212|, v196, v78
	v_fma_f32 v79, |v213|, v196, v79
	v_mfma_f32_16x16x32_f16 v[240:243], v[42:45], v[198:201], 0
	v_fma_f32 v80, |v214|, v196, v80
	v_fma_f32 v81, |v215|, v196, v81
	v_mfma_f32_16x16x32_f16 v[224:227], v[54:57], v[202:205], v[224:227]
	v_fma_f32 v70, |v216|, v196, v70
	v_fma_f32 v71, |v217|, v196, v71
	v_mfma_f32_16x16x32_f16 v[228:231], v[50:53], v[202:205], v[228:231]
	v_fma_f32 v72, |v218|, v196, v72
	v_fma_f32 v73, |v219|, v196, v73
	v_mfma_f32_16x16x32_f16 v[232:235], v[38:41], v[202:205], v[232:235]
	v_fma_f32 v66, |v220|, v196, v66
	v_fma_f32 v67, |v221|, v196, v67
	v_mfma_f32_16x16x32_f16 v[240:243], v[34:37], v[202:205], v[240:243]
	v_fma_f32 v68, |v222|, v196, v68
	v_fma_f32 v69, |v223|, v196, v69
	ds_read_b128 v[188:191], v112 offset:26624
	ds_read_b128 v[192:195], v112 offset:27648
	ds_read_b32 v196, v145 offset:832
	s_waitcnt lgkmcnt(3)
	v_mfma_f32_16x16x32_f16 v[208:211], v[58:61], v[178:181], 0
	v_fma_f32 v74, |v224|, v206, v74
	v_fma_f32 v75, |v225|, v206, v75
	v_mfma_f32_16x16x32_f16 v[212:215], v[62:65], v[178:181], 0
	v_fma_f32 v76, |v226|, v206, v76
	v_fma_f32 v77, |v227|, v206, v77
	v_mfma_f32_16x16x32_f16 v[216:219], v[46:49], v[178:181], 0
	v_fma_f32 v78, |v228|, v206, v78
	v_fma_f32 v79, |v229|, v206, v79
	v_mfma_f32_16x16x32_f16 v[220:223], v[42:45], v[178:181], 0
	v_fma_f32 v80, |v230|, v206, v80
	v_fma_f32 v81, |v231|, v206, v81
	v_mfma_f32_16x16x32_f16 v[208:211], v[54:57], v[182:185], v[208:211]
	v_fma_f32 v70, |v232|, v206, v70
	v_fma_f32 v71, |v233|, v206, v71
	v_mfma_f32_16x16x32_f16 v[212:215], v[50:53], v[182:185], v[212:215]
	v_fma_f32 v72, |v234|, v206, v72
	v_fma_f32 v73, |v235|, v206, v73
	v_mfma_f32_16x16x32_f16 v[216:219], v[38:41], v[182:185], v[216:219]
	v_fma_f32 v66, |v240|, v206, v66
	v_fma_f32 v67, |v241|, v206, v67
	v_mfma_f32_16x16x32_f16 v[220:223], v[34:37], v[182:185], v[220:223]
	v_fma_f32 v68, |v242|, v206, v68
	v_fma_f32 v69, |v243|, v206, v69
	ds_read_b128 v[198:201], v112 offset:28672
	ds_read_b128 v[202:205], v112 offset:29696
	ds_read_b32 v206, v145 offset:896
	s_waitcnt lgkmcnt(3)
	v_mfma_f32_16x16x32_f16 v[224:227], v[58:61], v[188:191], 0
	v_fma_f32 v74, |v208|, v186, v74
	v_fma_f32 v75, |v209|, v186, v75
	v_mfma_f32_16x16x32_f16 v[228:231], v[62:65], v[188:191], 0
	v_fma_f32 v76, |v210|, v186, v76
	v_fma_f32 v77, |v211|, v186, v77
	v_mfma_f32_16x16x32_f16 v[232:235], v[46:49], v[188:191], 0
	v_fma_f32 v78, |v212|, v186, v78
	v_fma_f32 v79, |v213|, v186, v79
	v_mfma_f32_16x16x32_f16 v[240:243], v[42:45], v[188:191], 0
	v_fma_f32 v80, |v214|, v186, v80
	v_fma_f32 v81, |v215|, v186, v81
	v_mfma_f32_16x16x32_f16 v[224:227], v[54:57], v[192:195], v[224:227]
	v_fma_f32 v70, |v216|, v186, v70
	v_fma_f32 v71, |v217|, v186, v71
	v_mfma_f32_16x16x32_f16 v[228:231], v[50:53], v[192:195], v[228:231]
	v_fma_f32 v72, |v218|, v186, v72
	v_fma_f32 v73, |v219|, v186, v73
	v_mfma_f32_16x16x32_f16 v[232:235], v[38:41], v[192:195], v[232:235]
	v_fma_f32 v66, |v220|, v186, v66
	v_fma_f32 v67, |v221|, v186, v67
	v_mfma_f32_16x16x32_f16 v[240:243], v[34:37], v[192:195], v[240:243]
	v_fma_f32 v68, |v222|, v186, v68
	v_fma_f32 v69, |v223|, v186, v69
	ds_read_b128 v[178:181], v112 offset:30720
	ds_read_b128 v[182:185], v112 offset:31744
	ds_read_b32 v186, v145 offset:960
	s_waitcnt lgkmcnt(3)
	v_mfma_f32_16x16x32_f16 v[208:211], v[58:61], v[198:201], 0
	v_fma_f32 v74, |v224|, v196, v74
	v_fma_f32 v75, |v225|, v196, v75
	v_mfma_f32_16x16x32_f16 v[212:215], v[62:65], v[198:201], 0
	v_fma_f32 v76, |v226|, v196, v76
	v_fma_f32 v77, |v227|, v196, v77
	v_mfma_f32_16x16x32_f16 v[216:219], v[46:49], v[198:201], 0
	v_fma_f32 v78, |v228|, v196, v78
	v_fma_f32 v79, |v229|, v196, v79
	v_mfma_f32_16x16x32_f16 v[220:223], v[42:45], v[198:201], 0
	v_fma_f32 v80, |v230|, v196, v80
	v_fma_f32 v81, |v231|, v196, v81
	v_mfma_f32_16x16x32_f16 v[208:211], v[54:57], v[202:205], v[208:211]
	v_fma_f32 v70, |v232|, v196, v70
	v_fma_f32 v71, |v233|, v196, v71
	v_mfma_f32_16x16x32_f16 v[212:215], v[50:53], v[202:205], v[212:215]
	v_fma_f32 v72, |v234|, v196, v72
	v_fma_f32 v73, |v235|, v196, v73
	v_mfma_f32_16x16x32_f16 v[216:219], v[38:41], v[202:205], v[216:219]
	v_fma_f32 v66, |v240|, v196, v66
	v_fma_f32 v67, |v241|, v196, v67
	v_mfma_f32_16x16x32_f16 v[220:223], v[34:37], v[202:205], v[220:223]
	v_fma_f32 v68, |v242|, v196, v68
	v_fma_f32 v69, |v243|, v196, v69
	ds_read_b128 v[146:149], v112 offset:32768
	ds_read_b128 v[158:161], v112 offset:33792
	s_waitcnt lgkmcnt(2)
; __device__ __forceinline__ void dsa_unit(int wv, const Args& A, LAS unsigned char* lds, int s, int qt) {
;     ...
; #pragma unroll
;                 for (int t = 0; t < 4; ++t)
; #pragma unroll
;                     for (int r = 0; r < 4; ++r) sc[t][r] += wh * fabsf(a[t][r]);
;             }
;             { const h16x8 q0 = __builtin_bit_cast(h16x8, Ql[32 * 64 + lane]), q1 = __builtin_bit_cast(h16x8, Ql[33 * 64 + lane]);
; #pragma unroll
;                 for (int t = 0; t < 4; ++t) { sc[t] = __builtin_amdgcn_mfma_f32_16x16x32_f16(kc[t][0], q0, sc[t], 0, 0, 0); sc[t] = __builtin_amdgcn_mfma_f32_16x16x32_f16(kc[t][1], q1, sc[t], 0, 0, 0); } }
;             int c = 0;
; #pragma unroll
;             for (int t = 0; t < 4; ++t)
; #pragma unroll
;                 for (int r = 0; r < 4; ++r) c += (sc[t][r] > th) ? 1 : 0;
;             if (c) { unsigned pos = __hip_atomic_fetch_add((unsigned*)(cnt + fr), (unsigned)c, __ATOMIC_RELAXED, __HIP_MEMORY_SCOPE_WORKGROUP);
	v_mfma_f32_16x16x32_f16 v[224:227], v[58:61], v[178:181], 0
	v_fma_f32 v74, |v208|, v206, v74
	v_fma_f32 v75, |v209|, v206, v75
	v_mfma_f32_16x16x32_f16 v[228:231], v[62:65], v[178:181], 0
	v_fma_f32 v76, |v210|, v206, v76
	v_fma_f32 v77, |v211|, v206, v77
	v_mfma_f32_16x16x32_f16 v[232:235], v[46:49], v[178:181], 0
	v_fma_f32 v78, |v212|, v206, v78
	v_fma_f32 v79, |v213|, v206, v79
	v_mfma_f32_16x16x32_f16 v[240:243], v[42:45], v[178:181], 0
	v_fma_f32 v80, |v214|, v206, v80
	v_fma_f32 v81, |v215|, v206, v81
	v_mfma_f32_16x16x32_f16 v[224:227], v[54:57], v[182:185], v[224:227]
	v_fma_f32 v70, |v216|, v206, v70
	v_fma_f32 v71, |v217|, v206, v71
	v_mfma_f32_16x16x32_f16 v[228:231], v[50:53], v[182:185], v[228:231]
	v_fma_f32 v72, |v218|, v206, v72
	v_fma_f32 v73, |v219|, v206, v73
	v_mfma_f32_16x16x32_f16 v[232:235], v[38:41], v[182:185], v[232:235]
	v_fma_f32 v66, |v220|, v206, v66
	v_fma_f32 v67, |v221|, v206, v67
	v_mfma_f32_16x16x32_f16 v[240:243], v[34:37], v[182:185], v[240:243]
	v_fma_f32 v68, |v222|, v206, v68
	v_fma_f32 v69, |v223|, v206, v69
	v_fma_f32 v74, |v224|, v186, v74
	v_fma_f32 v75, |v225|, v186, v75
	v_fma_f32 v76, |v226|, v186, v76
	v_fma_f32 v77, |v227|, v186, v77
	v_fma_f32 v78, |v228|, v186, v78
	v_fma_f32 v79, |v229|, v186, v79
	v_fma_f32 v80, |v230|, v186, v80
	v_fma_f32 v81, |v231|, v186, v81
	v_fma_f32 v70, |v232|, v186, v70
	v_fma_f32 v71, |v233|, v186, v71
	v_fma_f32 v72, |v234|, v186, v72
	v_fma_f32 v73, |v235|, v186, v73
	v_fma_f32 v66, |v240|, v186, v66
	v_fma_f32 v67, |v241|, v186, v67
	v_fma_f32 v68, |v242|, v186, v68
	v_fma_f32 v69, |v243|, v186, v69
	s_waitcnt lgkmcnt(0)
	v_mfma_f32_16x16x32_f16 v[58:61], v[58:61], v[146:149], v[74:77]
	v_mfma_f32_16x16x32_f16 v[62:65], v[62:65], v[146:149], v[78:81]
	v_mfma_f32_16x16x32_f16 v[54:57], v[54:57], v[158:161], v[58:61]
	v_mfma_f32_16x16x32_f16 v[46:49], v[46:49], v[146:149], v[70:73]
	v_mfma_f32_16x16x32_f16 v[50:53], v[50:53], v[158:161], v[62:65]
	s_nop 5
	v_cmp_gt_f32_e64 s[38:39], v55, v119
	v_cmp_gt_f32_e64 s[40:41], v54, v119
	v_cmp_gt_f32_e64 s[36:37], v56, v119
	v_mfma_f32_16x16x32_f16 v[42:45], v[42:45], v[146:149], v[66:69]
	v_cndmask_b32_e64 v58, 0, 1, s[38:39]
	v_cmp_gt_f32_e64 s[34:35], v57, v119
	v_cndmask_b32_e64 v59, 0, 1, s[36:37]
	v_mfma_f32_16x16x32_f16 v[38:41], v[38:41], v[158:161], v[46:49]
	v_cmp_gt_f32_e64 s[30:31], v50, v119
	v_addc_co_u32_e64 v58, vcc, 0, v58, s[40:41]
	v_mfma_f32_16x16x32_f16 v[34:37], v[34:37], v[158:161], v[42:45]
	v_addc_co_u32_e64 v58, vcc, v58, v59, s[34:35]
	v_cndmask_b32_e64 v59, 0, 1, s[30:31]
	v_cmp_gt_f32_e64 s[28:29], v51, v119
	v_cmp_gt_f32_e64 s[26:27], v52, v119
	v_cmp_gt_f32_e64 s[24:25], v53, v119
	v_addc_co_u32_e64 v58, vcc, v58, v59, s[28:29]
	v_cndmask_b32_e64 v46, 0, 1, s[26:27]
	v_cmp_gt_f32_e64 s[22:23], v38, v119
	v_addc_co_u32_e64 v46, vcc, v58, v46, s[24:25]
	s_nop 0
	v_cndmask_b32_e64 v42, 0, 1, s[22:23]
	v_cmp_gt_f32_e64 s[20:21], v39, v119
	v_cmp_gt_f32_e64 s[18:19], v40, v119
	v_cmp_gt_f32_e64 s[16:17], v41, v119
	v_addc_co_u32_e64 v42, vcc, v46, v42, s[20:21]
	v_cndmask_b32_e64 v43, 0, 1, s[18:19]
	v_cmp_gt_f32_e64 s[14:15], v34, v119
	v_addc_co_u32_e64 v42, vcc, v42, v43, s[16:17]
	s_nop 0
	v_cndmask_b32_e64 v43, 0, 1, s[14:15]
	v_cmp_gt_f32_e64 s[12:13], v35, v119
	v_cmp_gt_f32_e64 s[10:11], v36, v119
	s_nop 0
	v_addc_co_u32_e64 v42, vcc, v42, v43, s[12:13]
	v_cndmask_b32_e64 v43, 0, 1, s[10:11]
	v_cmp_gt_f32_e32 vcc, v37, v119
	s_nop 1
	v_addc_co_u32_e64 v42, s[42:43], v42, v43, vcc
	v_cmp_ne_u32_e64 s[42:43], 0, v42
	s_and_saveexec_b64 s[90:91], s[42:43]
	s_cbranch_execz .LBB0_1000
	ds_add_rtn_u32 v43, v110, v42
	s_waitcnt lgkmcnt(0)
	v_add_u32_e32 v178, v43, v42
	v_cmp_lt_u32_e64 s[92:93], s71, v178
	v_lshl_or_b32 v42, s70, 4, v114
	v_add_u32_e32 v179, v43, v113
	v_lshlrev_b32_e32 v180, 1, v179
	s_cmp_lg_u64 s[92:93], 0
	s_cbranch_scc1 .Lpush_slow
; __device__ __forceinline__ void dsa_unit(int wv, const Args& A, LAS unsigned char* lds, int s, int qt) {
;     ...
;             if (c) { unsigned pos = __hip_atomic_fetch_add((unsigned*)(cnt + fr), (unsigned)c, __ATOMIC_RELAXED, __HIP_MEMORY_SCOPE_WORKGROUP);
; #pragma unroll
;                 for (int t = 0; t < 4; ++t)
; #pragma unroll
;                     for (int r = 0; r < 4; ++r) if (sc[t][r] > th) { if (pos < (unsigned)CAP) { cs[fr * CAP + pos] = f2ord(sc[t][r]); ci[fr * CAP + pos] = (unsigned short)((kt + t) * 16 + fq * 4 + r); } ++pos; } }
	v_lshlrev_b32_e32 v179, 2, v179
	v_add_u32_e32 v180, 0x13000, v180
	s_mov_b64 exec, s[40:41]
	v_ashrrev_i32_e32 v181, 31, v54
	v_or_b32_e32 v181, v156, v181
	v_xor_b32_e32 v181, v181, v54
	ds_write_b32 v179, v181
	ds_write_b16 v180, v42
	v_add_u32_e32 v179, 4, v179
	v_add_u32_e32 v180, 2, v180
	s_mov_b64 exec, s[38:39]
	v_ashrrev_i32_e32 v183, 31, v55
	v_or_b32_e32 v183, v156, v183
	v_xor_b32_e32 v183, v183, v55
	ds_write_b32 v179, v183
	v_or_b32_e32 v184, 1, v42
	ds_write_b16 v180, v184
	v_add_u32_e32 v179, 4, v179
	v_add_u32_e32 v180, 2, v180
	s_mov_b64 exec, s[36:37]
	v_ashrrev_i32_e32 v181, 31, v56
	v_or_b32_e32 v181, v156, v181
	v_xor_b32_e32 v181, v181, v56
	ds_write_b32 v179, v181
	v_or_b32_e32 v182, 2, v42
	ds_write_b16 v180, v182
	v_add_u32_e32 v179, 4, v179
	v_add_u32_e32 v180, 2, v180
	s_mov_b64 exec, s[34:35]
	v_ashrrev_i32_e32 v183, 31, v57
	v_or_b32_e32 v183, v156, v183
	v_xor_b32_e32 v183, v183, v57
	ds_write_b32 v179, v183
	v_or_b32_e32 v184, 3, v42
	ds_write_b16 v180, v184
	v_add_u32_e32 v179, 4, v179
	v_add_u32_e32 v180, 2, v180
	s_mov_b64 exec, s[30:31]
	v_ashrrev_i32_e32 v181, 31, v50
	v_or_b32_e32 v181, v156, v181
	v_xor_b32_e32 v181, v181, v50
	ds_write_b32 v179, v181
	v_or_b32_e32 v182, 16, v42
	ds_write_b16 v180, v182
	v_add_u32_e32 v179, 4, v179
	v_add_u32_e32 v180, 2, v180
	s_mov_b64 exec, s[28:29]
	v_ashrrev_i32_e32 v183, 31, v51
	v_or_b32_e32 v183, v156, v183
	v_xor_b32_e32 v183, v183, v51
	ds_write_b32 v179, v183
	v_or_b32_e32 v184, 17, v42
	ds_write_b16 v180, v184
	v_add_u32_e32 v179, 4, v179
	v_add_u32_e32 v180, 2, v180
	s_mov_b64 exec, s[26:27]
	v_ashrrev_i32_e32 v181, 31, v52
	v_or_b32_e32 v181, v156, v181
	v_xor_b32_e32 v181, v181, v52
	ds_write_b32 v179, v181
	v_or_b32_e32 v182, 18, v42
	ds_write_b16 v180, v182
	v_add_u32_e32 v179, 4, v179
	v_add_u32_e32 v180, 2, v180
	s_mov_b64 exec, s[24:25]
	v_ashrrev_i32_e32 v183, 31, v53
	v_or_b32_e32 v183, v156, v183
	v_xor_b32_e32 v183, v183, v53
	ds_write_b32 v179, v183
	v_or_b32_e32 v184, 19, v42
	ds_write_b16 v180, v184
	v_add_u32_e32 v179, 4, v179
	v_add_u32_e32 v180, 2, v180
	s_mov_b64 exec, s[22:23]
	v_ashrrev_i32_e32 v181, 31, v38
	v_or_b32_e32 v181, v156, v181
	v_xor_b32_e32 v181, v181, v38
	ds_write_b32 v179, v181
	v_or_b32_e32 v182, 32, v42
	ds_write_b16 v180, v182
	v_add_u32_e32 v179, 4, v179
	v_add_u32_e32 v180, 2, v180
	s_mov_b64 exec, s[20:21]
	v_ashrrev_i32_e32 v183, 31, v39
	v_or_b32_e32 v183, v156, v183
	v_xor_b32_e32 v183, v183, v39
	ds_write_b32 v179, v183
	v_or_b32_e32 v184, 33, v42
	ds_write_b16 v180, v184
	v_add_u32_e32 v179, 4, v179
	v_add_u32_e32 v180, 2, v180
	s_mov_b64 exec, s[18:19]
	v_ashrrev_i32_e32 v181, 31, v40
	v_or_b32_e32 v181, v156, v181
	v_xor_b32_e32 v181, v181, v40
	ds_write_b32 v179, v181
	v_or_b32_e32 v182, 34, v42
	ds_write_b16 v180, v182
	v_add_u32_e32 v179, 4, v179
	v_add_u32_e32 v180, 2, v180
	s_mov_b64 exec, s[16:17]
	v_ashrrev_i32_e32 v183, 31, v41
	v_or_b32_e32 v183, v156, v183
	v_xor_b32_e32 v183, v183, v41
	ds_write_b32 v179, v183
	v_or_b32_e32 v184, 35, v42
	ds_write_b16 v180, v184
	v_add_u32_e32 v179, 4, v179
	v_add_u32_e32 v180, 2, v180
	s_mov_b64 exec, s[14:15]
	v_ashrrev_i32_e32 v181, 31, v34
	v_or_b32_e32 v181, v156, v181
	v_xor_b32_e32 v181, v181, v34
	ds_write_b32 v179, v181
	v_or_b32_e32 v182, 48, v42
	ds_write_b16 v180, v182
	v_add_u32_e32 v179, 4, v179
	v_add_u32_e32 v180, 2, v180
	s_mov_b64 exec, s[12:13]
	v_ashrrev_i32_e32 v183, 31, v35
	v_or_b32_e32 v183, v156, v183
	v_xor_b32_e32 v183, v183, v35
	ds_write_b32 v179, v183
	v_or_b32_e32 v184, 49, v42
	ds_write_b16 v180, v184
	v_add_u32_e32 v179, 4, v179
	v_add_u32_e32 v180, 2, v180
	s_mov_b64 exec, s[10:11]
	v_ashrrev_i32_e32 v181, 31, v36
	v_or_b32_e32 v181, v156, v181
	v_xor_b32_e32 v181, v181, v36
	ds_write_b32 v179, v181
	v_or_b32_e32 v182, 50, v42
	ds_write_b16 v180, v182
	v_add_u32_e32 v179, 4, v179
	v_add_u32_e32 v180, 2, v180
	s_mov_b64 exec, vcc
	v_ashrrev_i32_e32 v183, 31, v37
	v_or_b32_e32 v183, v156, v183
	v_xor_b32_e32 v183, v183, v37
	ds_write_b32 v179, v183
	v_or_b32_e32 v184, 51, v42
	ds_write_b16 v180, v184
	s_branch .LBB0_1000
.Lpush_slow:
	s_and_saveexec_b64 s[42:43], s[40:41]
	s_cbranch_execz .LBB0_967
	s_waitcnt lgkmcnt(0)
	v_cmp_gt_u32_e64 s[40:41], s71, v43
	s_and_saveexec_b64 s[92:93], s[40:41]
	s_cbranch_execz .LBB0_941
	v_cmp_lt_i32_e64 s[40:41], -1, v54
	v_add_u32_e32 v45, v43, v113
	v_lshl_add_u32 v46, v45, 2, 0
	v_cndmask_b32_e64 v44, -1, v156, s[40:41]
	v_xor_b32_e32 v44, v44, v54
	ds_write_b32 v46, v44
	v_lshl_add_u32 v44, v45, 1, 0
	v_add_u32_e32 v44, 0x13000, v44
	ds_write_b16 v44, v42

; #define LAS __attribute__((address_space(3)))
; template <bool FINAL>
; __device__ __forceinline__ void dsa_prune(LAS unsigned* cs, LAS unsigned short* ci, LAS unsigned* cnt, LAS float* thr, int q, int lane) {
;     const int n = __builtin_amdgcn_readfirstlane((int)cnt[q]);
;     if (n <= 256) return;
;     LAS unsigned* c = cs + q * CAP; LAS unsigned short* ix = ci + q * CAP;
;     constexpr int NE = CAP / 64;
;     unsigned x[NE];
; #pragma unroll
;     for (int i = 0; i < NE; ++i) { const int e = i * 64 + lane; x[i] = e < n ? c[e] : 0u; }
;     unsigned prefix = 0u; int kp = n;
.LBB0_1001:
	s_waitcnt lgkmcnt(0)
	s_barrier
	ds_read_b32 v34, v110
	s_waitcnt lgkmcnt(0)
	v_cmp_lt_u32_e32 vcc, s75, v34
	s_cmp_lg_u64 vcc, 0
	s_cselect_b64 s[42:43], -1, 0
	s_cbranch_vccz .LBB0_1214
	v_mov_b32_e32 v34, s66
	ds_read_b32 v34, v34
	s_waitcnt lgkmcnt(0)
	v_readfirstlane_b32 s73, v34
	s_cmpk_lt_i32 s73, 0x101
	s_cbranch_scc1 .LBB0_1108
	ds_read2st64_b32 v[36:37], v108 offset1:1
	ds_read2st64_b32 v[34:35], v108 offset0:2 offset1:3
	v_cmp_gt_u32_e64 s[40:41], s73, v106
	v_mov_b32_e32 v51, 0
	v_mov_b32_e32 v52, 0
	s_and_saveexec_b64 s[10:11], s[40:41]
	ds_read_b32 v52, v108 offset:1024
	s_or_b64 exec, exec, s[10:11]
	v_cmp_gt_u32_e64 s[38:39], s73, v105
	s_and_saveexec_b64 s[10:11], s[38:39]
	ds_read_b32 v51, v108 offset:1280
	s_or_b64 exec, exec, s[10:11]
	v_cmp_gt_u32_e64 s[36:37], s73, v104
	v_mov_b32_e32 v49, 0
	v_mov_b32_e32 v50, 0
	s_and_saveexec_b64 s[10:11], s[36:37]
	ds_read_b32 v50, v108 offset:1536
	s_or_b64 exec, exec, s[10:11]
	v_cmp_gt_u32_e64 s[34:35], s73, v103
	s_and_saveexec_b64 s[10:11], s[34:35]
	ds_read_b32 v49, v108 offset:1792
	s_or_b64 exec, exec, s[10:11]
	v_cmp_gt_u32_e64 s[30:31], s73, v102
	v_mov_b32_e32 v47, 0
	v_mov_b32_e32 v48, 0
	s_and_saveexec_b64 s[10:11], s[30:31]
	ds_read_b32 v48, v108 offset:2048
	s_or_b64 exec, exec, s[10:11]
	v_cmp_gt_u32_e64 s[28:29], s73, v101
	s_and_saveexec_b64 s[10:11], s[28:29]
	ds_read_b32 v47, v108 offset:2304
	s_or_b64 exec, exec, s[10:11]
	v_cmp_gt_u32_e64 s[26:27], s73, v100
	v_mov_b32_e32 v45, 0
	v_mov_b32_e32 v46, 0
	s_and_saveexec_b64 s[10:11], s[26:27]
	ds_read_b32 v46, v108 offset:2560
	s_or_b64 exec, exec, s[10:11]
	v_cmp_gt_u32_e64 s[24:25], s73, v99
	s_and_saveexec_b64 s[10:11], s[24:25]
	ds_read_b32 v45, v108 offset:2816
	s_or_b64 exec, exec, s[10:11]
	v_cmp_gt_u32_e64 s[22:23], s73, v98
	v_mov_b32_e32 v43, 0
	v_mov_b32_e32 v44, 0
	s_and_saveexec_b64 s[10:11], s[22:23]
	ds_read_b32 v44, v108 offset:3072
	s_or_b64 exec, exec, s[10:11]
	v_cmp_gt_u32_e64 s[20:21], s73, v97
	s_and_saveexec_b64 s[10:11], s[20:21]
	ds_read_b32 v43, v108 offset:3328
	s_or_b64 exec, exec, s[10:11]
	v_cmp_gt_u32_e64 s[18:19], s73, v96
	v_mov_b32_e32 v41, 0
	v_mov_b32_e32 v42, 0
	s_and_saveexec_b64 s[10:11], s[18:19]
	ds_read_b32 v42, v108 offset:3584
	s_or_b64 exec, exec, s[10:11]
	v_cmp_gt_u32_e64 s[16:17], s73, v93
	s_and_saveexec_b64 s[10:11], s[16:17]
	ds_read_b32 v41, v108 offset:3840
	s_or_b64 exec, exec, s[10:11]
	v_cmp_gt_u32_e64 s[14:15], s73, v92
	v_mov_b32_e32 v39, 0
	v_mov_b32_e32 v40, 0
	s_and_saveexec_b64 s[10:11], s[14:15]
	ds_read_b32 v40, v108 offset:4096
	s_or_b64 exec, exec, s[10:11]
	v_cmp_gt_u32_e64 s[12:13], s73, v91
	s_and_saveexec_b64 s[10:11], s[12:13]
	ds_read_b32 v39, v108 offset:4352
	s_or_b64 exec, exec, s[10:11]
	v_cmp_gt_u32_e64 s[10:11], s73, v89
	v_mov_b32_e32 v38, 0
	s_and_saveexec_b64 s[90:91], s[10:11]
	ds_read_b32 v38, v108 offset:4608
	s_or_b64 exec, exec, s[90:91]
	s_mov_b32 s99, s73
	s_mov_b32 s92, 31
	s_mov_b32 s70, 0
	s_branch .LBB0_1035

; #define LDS_WAIT() asm volatile("s_waitcnt lgkmcnt(0)" ::: "memory")
; template <bool FINAL>
; __device__ __forceinline__ void dsa_prune(LAS unsigned* cs, LAS unsigned short* ci, LAS unsigned* cnt, LAS float* thr, int q, int lane) {
;     ...
; #pragma unroll
;         for (int i = 0; i < NE; ++i) k += __popcll(__ballot(x[i] >= trial));
;         if (k >= 256) { prefix = trial; kp = k; }
;         if (kp == 256 || (!FINAL && bit <= 16 && kp <= 320)) break; }
;     int base = 0;
; #pragma unroll
;     for (int i = 0; i < NE; ++i) { const int e = i * 64 + lane; const unsigned short id = e < n ? ix[e] : (unsigned short)0;
;         const bool keep = x[i] >= prefix; const unsigned long long mask = __ballot(keep);
;         const int pos = base + (int)__builtin_amdgcn_mbcnt_hi((unsigned)(mask >> 32), __builtin_amdgcn_mbcnt_lo((unsigned)mask, 0u));
;         LDS_WAIT();
;         if (keep) { c[pos] = x[i]; ix[pos] = id; }
;         base += __popcll(mask); }
;     if (lane == 0) { cnt[q] = (unsigned)base; thr[q] = ord2f(prefix); }
.LBB0_1035:
	s_lshl_b32 s78, 1, s92
	s_or_b32 s78, s78, s70
	s_waitcnt lgkmcnt(0)
	v_cmp_le_u32_e32 vcc, s78, v36
	s_bcnt1_i32_b64 s79, vcc
	v_cmp_le_u32_e32 vcc, s78, v37
	s_bcnt1_i32_b64 s32, vcc
	s_add_i32 s79, s79, s32
	v_cmp_le_u32_e32 vcc, s78, v34
	s_bcnt1_i32_b64 s32, vcc
	s_add_i32 s79, s79, s32
	v_cmp_le_u32_e32 vcc, s78, v35
	s_bcnt1_i32_b64 s32, vcc
	s_add_i32 s79, s79, s32
	v_cmp_le_u32_e32 vcc, s78, v52
	s_bcnt1_i32_b64 s32, vcc
	s_add_i32 s79, s79, s32
	s_cmpk_le_u32 s99, 320
	s_cbranch_scc1 .Lps_done_a
	v_cmp_le_u32_e32 vcc, s78, v51
	s_bcnt1_i32_b64 s32, vcc
	s_add_i32 s79, s79, s32
	v_cmp_le_u32_e32 vcc, s78, v50
	s_bcnt1_i32_b64 s32, vcc
	s_add_i32 s79, s79, s32
	v_cmp_le_u32_e32 vcc, s78, v49
	s_bcnt1_i32_b64 s32, vcc
	s_add_i32 s79, s79, s32
	s_cmpk_le_u32 s99, 512
	s_cbranch_scc1 .Lps_done_a
	v_cmp_le_u32_e32 vcc, s78, v48
	s_bcnt1_i32_b64 s32, vcc
	s_add_i32 s79, s79, s32
	v_cmp_le_u32_e32 vcc, s78, v47
	s_bcnt1_i32_b64 s32, vcc
	s_add_i32 s79, s79, s32
	v_cmp_le_u32_e32 vcc, s78, v46
	s_bcnt1_i32_b64 s32, vcc
	s_add_i32 s79, s79, s32
	v_cmp_le_u32_e32 vcc, s78, v45
	s_bcnt1_i32_b64 s32, vcc
	s_add_i32 s79, s79, s32
	s_cmpk_le_u32 s99, 768
	s_cbranch_scc1 .Lps_done_a
	v_cmp_le_u32_e32 vcc, s78, v44
	s_bcnt1_i32_b64 s32, vcc
	s_add_i32 s79, s79, s32
	v_cmp_le_u32_e32 vcc, s78, v43
	s_bcnt1_i32_b64 s32, vcc
	s_add_i32 s79, s79, s32
	v_cmp_le_u32_e32 vcc, s78, v42
	s_bcnt1_i32_b64 s32, vcc
	s_add_i32 s79, s79, s32
	s_cmpk_le_u32 s99, 960
	s_cbranch_scc1 .Lps_done_a
	v_cmp_le_u32_e32 vcc, s78, v41
	s_bcnt1_i32_b64 s32, vcc
	s_add_i32 s79, s79, s32
	v_cmp_le_u32_e32 vcc, s78, v40
	s_bcnt1_i32_b64 s32, vcc
	s_add_i32 s79, s79, s32
	v_cmp_le_u32_e32 vcc, s78, v39
	s_bcnt1_i32_b64 s32, vcc
	s_add_i32 s79, s79, s32
	v_cmp_le_u32_e32 vcc, s78, v38
	s_bcnt1_i32_b64 s32, vcc
	s_add_i32 s79, s79, s32
.Lps_done_a:
	s_cmpk_gt_u32 s79, 0xff
	s_cselect_b32 s73, s79, s73
	s_cselect_b32 s70, s78, s70
	s_cmpk_eq_i32 s73, 0x100
	s_mov_b64 s[90:91], -1
	s_cbranch_scc1 .LBB0_1034
	s_cmp_lt_u32 s92, 17
	s_cselect_b64 s[90:91], -1, 0
	s_cmpk_lt_i32 s73, 0x141
	s_cselect_b64 vcc, -1, 0
	s_and_b64 s[90:91], s[90:91], vcc
	v_sub_co_u32_e64 v53, vcc, s92, 1
	s_nop 0
	v_readfirstlane_b32 s92, v53
	s_or_b64 s[90:91], vcc, s[90:91]
	s_branch .LBB0_1034
.LBB0_1037:
	ds_read_u16 v208, v107
	ds_read_u16 v209, v107 offset:128
	ds_read_u16 v210, v107 offset:256
	ds_read_u16 v211, v107 offset:384
	ds_read_u16 v212, v107 offset:512
	ds_read_u16 v213, v107 offset:640
	ds_read_u16 v214, v107 offset:768
	ds_read_u16 v215, v107 offset:896
	ds_read_u16 v216, v107 offset:1024
	ds_read_u16 v217, v107 offset:1152
	ds_read_u16 v218, v107 offset:1280
	ds_read_u16 v219, v107 offset:1408
	ds_read_u16 v220, v107 offset:1536
	ds_read_u16 v221, v107 offset:1664
	ds_read_u16 v222, v107 offset:1792
	ds_read_u16 v223, v107 offset:1920
	ds_read_u16 v224, v107 offset:2048
	ds_read_u16 v225, v107 offset:2176
	ds_read_u16 v226, v107 offset:2304
	s_waitcnt lgkmcnt(0)
	v_mov_b32_e32 v53, v208
	v_cmp_le_u32_e32 vcc, s70, v36
	s_and_saveexec_b64 s[90:91], vcc
	s_cbranch_execz .LBB0_1039
	v_mbcnt_lo_u32_b32 v54, vcc_lo, 0
	v_mbcnt_hi_u32_b32 v54, vcc_hi, v54
	v_lshl_add_u32 v55, v54, 2, s67
	ds_write_b32 v55, v36
	v_lshl_add_u32 v36, v54, 1, s80
	s_waitcnt lgkmcnt(1)
	ds_write_b16 v36, v53
.LBB0_1039:
	s_or_b64 exec, exec, s[90:91]
	v_mov_b32_e32 v36, v209
	s_bcnt1_i32_b64 s73, vcc
	v_cmp_le_u32_e32 vcc, s70, v37
	s_and_saveexec_b64 s[90:91], vcc
	s_cbranch_execz .LBB0_1041
	s_waitcnt lgkmcnt(1)
	v_mbcnt_lo_u32_b32 v53, vcc_lo, 0
	v_mbcnt_hi_u32_b32 v53, vcc_hi, v53
	v_add_u32_e32 v53, s73, v53
	v_lshl_add_u32 v54, v53, 2, s67
	ds_write_b32 v54, v37
	v_lshl_add_u32 v37, v53, 1, s80
	s_waitcnt lgkmcnt(1)
	ds_write_b16 v37, v36
.LBB0_1041:
	s_or_b64 exec, exec, s[90:91]
	s_waitcnt lgkmcnt(0)
	v_mov_b32_e32 v36, v210
	s_bcnt1_i32_b64 s78, vcc
	s_add_i32 s73, s78, s73
	v_cmp_le_u32_e32 vcc, s70, v34
	s_and_saveexec_b64 s[90:91], vcc
	s_cbranch_execz .LBB0_1043
	v_mbcnt_lo_u32_b32 v37, vcc_lo, 0
	v_mbcnt_hi_u32_b32 v37, vcc_hi, v37
	v_add_u32_e32 v37, s73, v37
	v_lshl_add_u32 v53, v37, 2, s67
	ds_write_b32 v53, v34
	v_lshl_add_u32 v34, v37, 1, s80
	s_waitcnt lgkmcnt(1)
	ds_write_b16 v34, v36
.LBB0_1043:
	s_or_b64 exec, exec, s[90:91]
	v_mov_b32_e32 v34, v211
	s_bcnt1_i32_b64 s78, vcc
	s_add_i32 s73, s73, s78
	v_cmp_le_u32_e32 vcc, s70, v35
	s_and_saveexec_b64 s[90:91], vcc
	s_cbranch_execz .LBB0_1045
	s_waitcnt lgkmcnt(1)
	v_mbcnt_lo_u32_b32 v36, vcc_lo, 0
	v_mbcnt_hi_u32_b32 v36, vcc_hi, v36
	v_add_u32_e32 v36, s73, v36
	v_lshl_add_u32 v37, v36, 2, s67
	ds_write_b32 v37, v35
	v_lshl_add_u32 v35, v36, 1, s80
	s_waitcnt lgkmcnt(1)
	ds_write_b16 v35, v34
.LBB0_1045:
	s_or_b64 exec, exec, s[90:91]
	s_waitcnt lgkmcnt(0)
	v_mov_b32_e32 v34, 0
	s_and_saveexec_b64 s[90:91], s[40:41]
	v_mov_b32_e32 v34, v212
	s_or_b64 exec, exec, s[90:91]
	s_bcnt1_i32_b64 s40, vcc
	s_add_i32 s73, s73, s40
	v_cmp_le_u32_e32 vcc, s70, v52
	s_and_saveexec_b64 s[40:41], vcc
	s_cbranch_execz .LBB0_1049
	v_mbcnt_lo_u32_b32 v35, vcc_lo, 0
	v_mbcnt_hi_u32_b32 v35, vcc_hi, v35
	v_add_u32_e32 v35, s73, v35
	v_lshl_add_u32 v36, v35, 2, s67
	v_lshl_add_u32 v35, v35, 1, s80
	ds_write_b32 v36, v52
	s_waitcnt lgkmcnt(1)
	ds_write_b16 v35, v34
.LBB0_1049:
	s_or_b64 exec, exec, s[40:41]
	s_waitcnt lgkmcnt(0)
	v_mov_b32_e32 v34, 0
	s_and_saveexec_b64 s[40:41], s[38:39]
	v_mov_b32_e32 v34, v213
	s_or_b64 exec, exec, s[40:41]
	s_bcnt1_i32_b64 s38, vcc
	s_add_i32 s40, s73, s38
	v_cmp_le_u32_e32 vcc, s70, v51
	s_and_saveexec_b64 s[38:39], vcc
	s_cbranch_execz .LBB0_1053
	v_mbcnt_lo_u32_b32 v35, vcc_lo, 0
	v_mbcnt_hi_u32_b32 v35, vcc_hi, v35
	v_add_u32_e32 v35, s40, v35
	v_lshl_add_u32 v36, v35, 2, s67
	v_lshl_add_u32 v35, v35, 1, s80
	ds_write_b32 v36, v51
	s_waitcnt lgkmcnt(1)
	ds_write_b16 v35, v34
; #define LDS_WAIT() asm volatile("s_waitcnt lgkmcnt(0)" ::: "memory")
; template <bool FINAL>
; __device__ __forceinline__ void dsa_prune(LAS unsigned* cs, LAS unsigned short* ci, LAS unsigned* cnt, LAS float* thr, int q, int lane) {
;     ...
;     int base = 0;
; #pragma unroll
;     for (int i = 0; i < NE; ++i) { const int e = i * 64 + lane; const unsigned short id = e < n ? ix[e] : (unsigned short)0;
;         const bool keep = x[i] >= prefix; const unsigned long long mask = __ballot(keep);
;         const int pos = base + (int)__builtin_amdgcn_mbcnt_hi((unsigned)(mask >> 32), __builtin_amdgcn_mbcnt_lo((unsigned)mask, 0u));
;         LDS_WAIT();
;         if (keep) { c[pos] = x[i]; ix[pos] = id; }
;         base += __popcll(mask); }
.LBB0_1053:
	s_or_b64 exec, exec, s[38:39]
	s_waitcnt lgkmcnt(0)
	v_mov_b32_e32 v34, 0
	s_and_saveexec_b64 s[38:39], s[36:37]
	v_mov_b32_e32 v34, v214
	s_or_b64 exec, exec, s[38:39]
	s_bcnt1_i32_b64 s36, vcc
	s_add_i32 s38, s40, s36
	v_cmp_le_u32_e32 vcc, s70, v50
	s_and_saveexec_b64 s[36:37], vcc
	s_cbranch_execz .LBB0_1057
	v_mbcnt_lo_u32_b32 v35, vcc_lo, 0
	v_mbcnt_hi_u32_b32 v35, vcc_hi, v35
	v_add_u32_e32 v35, s38, v35
	v_lshl_add_u32 v36, v35, 2, s67
	v_lshl_add_u32 v35, v35, 1, s80
	ds_write_b32 v36, v50
	s_waitcnt lgkmcnt(1)
	ds_write_b16 v35, v34
.LBB0_1057:
	s_or_b64 exec, exec, s[36:37]
	s_waitcnt lgkmcnt(0)
	v_mov_b32_e32 v34, 0
	s_and_saveexec_b64 s[36:37], s[34:35]
	v_mov_b32_e32 v34, v215
	s_or_b64 exec, exec, s[36:37]
	s_bcnt1_i32_b64 s34, vcc
	s_add_i32 s36, s38, s34
	v_cmp_le_u32_e32 vcc, s70, v49
	s_and_saveexec_b64 s[34:35], vcc
	s_cbranch_execz .LBB0_1061
	v_mbcnt_lo_u32_b32 v35, vcc_lo, 0
	v_mbcnt_hi_u32_b32 v35, vcc_hi, v35
	v_add_u32_e32 v35, s36, v35
	v_lshl_add_u32 v36, v35, 2, s67
	v_lshl_add_u32 v35, v35, 1, s80
	ds_write_b32 v36, v49
	s_waitcnt lgkmcnt(1)
	ds_write_b16 v35, v34
.LBB0_1061:
	s_or_b64 exec, exec, s[34:35]
	s_waitcnt lgkmcnt(0)
	v_mov_b32_e32 v34, 0
	s_and_saveexec_b64 s[34:35], s[30:31]
	v_mov_b32_e32 v34, v216
	s_or_b64 exec, exec, s[34:35]
	s_bcnt1_i32_b64 s30, vcc
	s_add_i32 s34, s36, s30
	v_cmp_le_u32_e32 vcc, s70, v48
	s_and_saveexec_b64 s[30:31], vcc
	s_cbranch_execz .LBB0_1065
	v_mbcnt_lo_u32_b32 v35, vcc_lo, 0
	v_mbcnt_hi_u32_b32 v35, vcc_hi, v35
	v_add_u32_e32 v35, s34, v35
	v_lshl_add_u32 v36, v35, 2, s67
	v_lshl_add_u32 v35, v35, 1, s80
	ds_write_b32 v36, v48
	s_waitcnt lgkmcnt(1)
	ds_write_b16 v35, v34
.LBB0_1065:
	s_or_b64 exec, exec, s[30:31]
	s_waitcnt lgkmcnt(0)
	v_mov_b32_e32 v34, 0
	s_and_saveexec_b64 s[30:31], s[28:29]
	v_mov_b32_e32 v34, v217
	s_or_b64 exec, exec, s[30:31]
	s_bcnt1_i32_b64 s28, vcc
	s_add_i32 s30, s34, s28
	v_cmp_le_u32_e32 vcc, s70, v47
	s_and_saveexec_b64 s[28:29], vcc
	s_cbranch_execz .LBB0_1069
	v_mbcnt_lo_u32_b32 v35, vcc_lo, 0
	v_mbcnt_hi_u32_b32 v35, vcc_hi, v35
	v_add_u32_e32 v35, s30, v35
	v_lshl_add_u32 v36, v35, 2, s67
	v_lshl_add_u32 v35, v35, 1, s80
	ds_write_b32 v36, v47
	s_waitcnt lgkmcnt(1)
	ds_write_b16 v35, v34
.LBB0_1069:
	s_or_b64 exec, exec, s[28:29]
	s_waitcnt lgkmcnt(0)
	v_mov_b32_e32 v34, 0
	s_and_saveexec_b64 s[28:29], s[26:27]
	v_mov_b32_e32 v34, v218
	s_or_b64 exec, exec, s[28:29]
	s_bcnt1_i32_b64 s26, vcc
	s_add_i32 s28, s30, s26
	v_cmp_le_u32_e32 vcc, s70, v46
	s_and_saveexec_b64 s[26:27], vcc
	s_cbranch_execz .LBB0_1073
	v_mbcnt_lo_u32_b32 v35, vcc_lo, 0
	v_mbcnt_hi_u32_b32 v35, vcc_hi, v35
	v_add_u32_e32 v35, s28, v35
	v_lshl_add_u32 v36, v35, 2, s67
	v_lshl_add_u32 v35, v35, 1, s80
	ds_write_b32 v36, v46
	s_waitcnt lgkmcnt(1)
	ds_write_b16 v35, v34
.LBB0_1073:
	s_or_b64 exec, exec, s[26:27]
	s_waitcnt lgkmcnt(0)
	v_mov_b32_e32 v34, 0
	s_and_saveexec_b64 s[26:27], s[24:25]
	v_mov_b32_e32 v34, v219
	s_or_b64 exec, exec, s[26:27]
	s_bcnt1_i32_b64 s24, vcc
	s_add_i32 s26, s28, s24
	v_cmp_le_u32_e32 vcc, s70, v45
	s_and_saveexec_b64 s[24:25], vcc
	s_cbranch_execz .LBB0_1077
	v_mbcnt_lo_u32_b32 v35, vcc_lo, 0
	v_mbcnt_hi_u32_b32 v35, vcc_hi, v35
	v_add_u32_e32 v35, s26, v35
	v_lshl_add_u32 v36, v35, 2, s67
	v_lshl_add_u32 v35, v35, 1, s80
	ds_write_b32 v36, v45
	s_waitcnt lgkmcnt(1)
	ds_write_b16 v35, v34
; #define LDS_WAIT() asm volatile("s_waitcnt lgkmcnt(0)" ::: "memory")
; template <bool FINAL>
; __device__ __forceinline__ void dsa_prune(LAS unsigned* cs, LAS unsigned short* ci, LAS unsigned* cnt, LAS float* thr, int q, int lane) {
;     ...
;     int base = 0;
; #pragma unroll
;     for (int i = 0; i < NE; ++i) { const int e = i * 64 + lane; const unsigned short id = e < n ? ix[e] : (unsigned short)0;
;         const bool keep = x[i] >= prefix; const unsigned long long mask = __ballot(keep);
;         const int pos = base + (int)__builtin_amdgcn_mbcnt_hi((unsigned)(mask >> 32), __builtin_amdgcn_mbcnt_lo((unsigned)mask, 0u));
;         LDS_WAIT();
;         if (keep) { c[pos] = x[i]; ix[pos] = id; }
;         base += __popcll(mask); }
.LBB0_1077:
	s_or_b64 exec, exec, s[24:25]
	s_waitcnt lgkmcnt(0)
	v_mov_b32_e32 v34, 0
	s_and_saveexec_b64 s[24:25], s[22:23]
	v_mov_b32_e32 v34, v220
	s_or_b64 exec, exec, s[24:25]
	s_bcnt1_i32_b64 s22, vcc
	s_add_i32 s24, s26, s22
	v_cmp_le_u32_e32 vcc, s70, v44
	s_and_saveexec_b64 s[22:23], vcc
	s_cbranch_execz .LBB0_1081
	v_mbcnt_lo_u32_b32 v35, vcc_lo, 0
	v_mbcnt_hi_u32_b32 v35, vcc_hi, v35
	v_add_u32_e32 v35, s24, v35
	v_lshl_add_u32 v36, v35, 2, s67
	v_lshl_add_u32 v35, v35, 1, s80
	ds_write_b32 v36, v44
	s_waitcnt lgkmcnt(1)
	ds_write_b16 v35, v34
.LBB0_1081:
	s_or_b64 exec, exec, s[22:23]
	s_waitcnt lgkmcnt(0)
	v_mov_b32_e32 v34, 0
	s_and_saveexec_b64 s[22:23], s[20:21]
	v_mov_b32_e32 v34, v221
	s_or_b64 exec, exec, s[22:23]
	s_bcnt1_i32_b64 s20, vcc
	s_add_i32 s22, s24, s20
	v_cmp_le_u32_e32 vcc, s70, v43
	s_and_saveexec_b64 s[20:21], vcc
	s_cbranch_execz .LBB0_1085
	v_mbcnt_lo_u32_b32 v35, vcc_lo, 0
	v_mbcnt_hi_u32_b32 v35, vcc_hi, v35
	v_add_u32_e32 v35, s22, v35
	v_lshl_add_u32 v36, v35, 2, s67
	v_lshl_add_u32 v35, v35, 1, s80
	ds_write_b32 v36, v43
	s_waitcnt lgkmcnt(1)
	ds_write_b16 v35, v34
.LBB0_1085:
	s_or_b64 exec, exec, s[20:21]
	s_waitcnt lgkmcnt(0)
	v_mov_b32_e32 v34, 0
	s_and_saveexec_b64 s[20:21], s[18:19]
	v_mov_b32_e32 v34, v222
	s_or_b64 exec, exec, s[20:21]
	s_bcnt1_i32_b64 s18, vcc
	s_add_i32 s20, s22, s18
	v_cmp_le_u32_e32 vcc, s70, v42
	s_and_saveexec_b64 s[18:19], vcc
	s_cbranch_execz .LBB0_1089
	v_mbcnt_lo_u32_b32 v35, vcc_lo, 0
	v_mbcnt_hi_u32_b32 v35, vcc_hi, v35
	v_add_u32_e32 v35, s20, v35
	v_lshl_add_u32 v36, v35, 2, s67
	v_lshl_add_u32 v35, v35, 1, s80
	ds_write_b32 v36, v42
	s_waitcnt lgkmcnt(1)
	ds_write_b16 v35, v34
.LBB0_1089:
	s_or_b64 exec, exec, s[18:19]
	s_waitcnt lgkmcnt(0)
	v_mov_b32_e32 v34, 0
	s_and_saveexec_b64 s[18:19], s[16:17]
	v_mov_b32_e32 v34, v223
	s_or_b64 exec, exec, s[18:19]
	s_bcnt1_i32_b64 s16, vcc
	s_add_i32 s18, s20, s16
	v_cmp_le_u32_e32 vcc, s70, v41
	s_and_saveexec_b64 s[16:17], vcc
	s_cbranch_execz .LBB0_1093
	v_mbcnt_lo_u32_b32 v35, vcc_lo, 0
	v_mbcnt_hi_u32_b32 v35, vcc_hi, v35
	v_add_u32_e32 v35, s18, v35
	v_lshl_add_u32 v36, v35, 2, s67
	v_lshl_add_u32 v35, v35, 1, s80
	ds_write_b32 v36, v41
	s_waitcnt lgkmcnt(1)
	ds_write_b16 v35, v34
.LBB0_1093:
	s_or_b64 exec, exec, s[16:17]
	s_waitcnt lgkmcnt(0)
	v_mov_b32_e32 v34, 0
	s_and_saveexec_b64 s[16:17], s[14:15]
	v_mov_b32_e32 v34, v224
	s_or_b64 exec, exec, s[16:17]
	s_bcnt1_i32_b64 s14, vcc
	s_add_i32 s16, s18, s14
	v_cmp_le_u32_e32 vcc, s70, v40
	s_and_saveexec_b64 s[14:15], vcc
	s_cbranch_execz .LBB0_1097
	v_mbcnt_lo_u32_b32 v35, vcc_lo, 0
	v_mbcnt_hi_u32_b32 v35, vcc_hi, v35
	v_add_u32_e32 v35, s16, v35
	v_lshl_add_u32 v36, v35, 2, s67
	v_lshl_add_u32 v35, v35, 1, s80
	ds_write_b32 v36, v40
	s_waitcnt lgkmcnt(1)
	ds_write_b16 v35, v34
.LBB0_1097:
	s_or_b64 exec, exec, s[14:15]
	s_waitcnt lgkmcnt(0)
	v_mov_b32_e32 v34, 0
	s_and_saveexec_b64 s[14:15], s[12:13]
	v_mov_b32_e32 v34, v225
	s_or_b64 exec, exec, s[14:15]
	s_bcnt1_i32_b64 s12, vcc
	s_add_i32 s14, s16, s12
	v_cmp_le_u32_e32 vcc, s70, v39
	s_and_saveexec_b64 s[12:13], vcc
	s_cbranch_execz .LBB0_1101
	v_mbcnt_lo_u32_b32 v35, vcc_lo, 0
	v_mbcnt_hi_u32_b32 v35, vcc_hi, v35
	v_add_u32_e32 v35, s14, v35
	v_lshl_add_u32 v36, v35, 2, s67
	v_lshl_add_u32 v35, v35, 1, s80
	ds_write_b32 v36, v39
	s_waitcnt lgkmcnt(1)
	ds_write_b16 v35, v34
.LBB0_1101:
	s_or_b64 exec, exec, s[12:13]
	s_waitcnt lgkmcnt(0)
	v_mov_b32_e32 v34, 0
	s_and_saveexec_b64 s[12:13], s[10:11]
	v_mov_b32_e32 v34, v226
	s_or_b64 exec, exec, s[12:13]
	s_bcnt1_i32_b64 s10, vcc
	s_add_i32 s12, s14, s10
	v_cmp_le_u32_e32 vcc, s70, v38
	s_and_saveexec_b64 s[10:11], vcc
	s_cbranch_execz .LBB0_1105
	v_mbcnt_lo_u32_b32 v35, vcc_lo, 0
	v_mbcnt_hi_u32_b32 v35, vcc_hi, v35
	v_add_u32_e32 v35, s12, v35
	v_lshl_add_u32 v36, v35, 2, s67
	v_lshl_add_u32 v35, v35, 1, s80
	ds_write_b32 v36, v38
	s_waitcnt lgkmcnt(1)
	ds_write_b16 v35, v34

; #define LAS __attribute__((address_space(3)))
; template <bool FINAL>
; __device__ __forceinline__ void dsa_prune(LAS unsigned* cs, LAS unsigned short* ci, LAS unsigned* cnt, LAS float* thr, int q, int lane) {
;     const int n = __builtin_amdgcn_readfirstlane((int)cnt[q]);
;     if (n <= 256) return;
;     LAS unsigned* c = cs + q * CAP; LAS unsigned short* ix = ci + q * CAP;
;     constexpr int NE = CAP / 64;
;     unsigned x[NE];
; #pragma unroll
;     for (int i = 0; i < NE; ++i) { const int e = i * 64 + lane; x[i] = e < n ? c[e] : 0u; }
;     unsigned prefix = 0u; int kp = n;
.LBB0_1108:
	s_waitcnt lgkmcnt(0)
	v_mov_b32_e32 v34, s59
	ds_read_b32 v34, v34
	s_waitcnt lgkmcnt(0)
	v_readfirstlane_b32 s73, v34
	s_cmpk_lt_i32 s73, 0x101
	s_cbranch_scc1 .LBB0_1214
	ds_read2st64_b32 v[36:37], v90 offset1:1
	ds_read2st64_b32 v[34:35], v90 offset0:2 offset1:3
	v_cmp_gt_u32_e64 s[40:41], s73, v106
	v_mov_b32_e32 v51, 0
	v_mov_b32_e32 v52, 0
	s_and_saveexec_b64 s[10:11], s[40:41]
	ds_read_b32 v52, v90 offset:1024
	s_or_b64 exec, exec, s[10:11]
	v_cmp_gt_u32_e64 s[38:39], s73, v105
	s_and_saveexec_b64 s[10:11], s[38:39]
	ds_read_b32 v51, v90 offset:1280
	s_or_b64 exec, exec, s[10:11]
	v_cmp_gt_u32_e64 s[36:37], s73, v104
	v_mov_b32_e32 v49, 0
	v_mov_b32_e32 v50, 0
	s_and_saveexec_b64 s[10:11], s[36:37]
	ds_read_b32 v50, v90 offset:1536
	s_or_b64 exec, exec, s[10:11]
	v_cmp_gt_u32_e64 s[34:35], s73, v103
	s_and_saveexec_b64 s[10:11], s[34:35]
	ds_read_b32 v49, v90 offset:1792
	s_or_b64 exec, exec, s[10:11]
	v_cmp_gt_u32_e64 s[30:31], s73, v102
	v_mov_b32_e32 v47, 0
	v_mov_b32_e32 v48, 0
	s_and_saveexec_b64 s[10:11], s[30:31]
	ds_read_b32 v48, v90 offset:2048
	s_or_b64 exec, exec, s[10:11]
	v_cmp_gt_u32_e64 s[28:29], s73, v101
	s_and_saveexec_b64 s[10:11], s[28:29]
	ds_read_b32 v47, v90 offset:2304
	s_or_b64 exec, exec, s[10:11]
	v_cmp_gt_u32_e64 s[26:27], s73, v100
	v_mov_b32_e32 v45, 0
	v_mov_b32_e32 v46, 0
	s_and_saveexec_b64 s[10:11], s[26:27]
	ds_read_b32 v46, v90 offset:2560
	s_or_b64 exec, exec, s[10:11]
	v_cmp_gt_u32_e64 s[24:25], s73, v99
	s_and_saveexec_b64 s[10:11], s[24:25]
	ds_read_b32 v45, v90 offset:2816
	s_or_b64 exec, exec, s[10:11]
	v_cmp_gt_u32_e64 s[22:23], s73, v98
	v_mov_b32_e32 v43, 0
	v_mov_b32_e32 v44, 0
	s_and_saveexec_b64 s[10:11], s[22:23]
	ds_read_b32 v44, v90 offset:3072
	s_or_b64 exec, exec, s[10:11]
	v_cmp_gt_u32_e64 s[20:21], s73, v97
	s_and_saveexec_b64 s[10:11], s[20:21]
	ds_read_b32 v43, v90 offset:3328
	s_or_b64 exec, exec, s[10:11]
	v_cmp_gt_u32_e64 s[18:19], s73, v96
	v_mov_b32_e32 v41, 0
	v_mov_b32_e32 v42, 0
	s_and_saveexec_b64 s[10:11], s[18:19]
	ds_read_b32 v42, v90 offset:3584
	s_or_b64 exec, exec, s[10:11]
	v_cmp_gt_u32_e64 s[16:17], s73, v93
	s_and_saveexec_b64 s[10:11], s[16:17]
	ds_read_b32 v41, v90 offset:3840
	s_or_b64 exec, exec, s[10:11]
	v_cmp_gt_u32_e64 s[14:15], s73, v92
	v_mov_b32_e32 v39, 0
	v_mov_b32_e32 v40, 0
	s_and_saveexec_b64 s[10:11], s[14:15]
	ds_read_b32 v40, v90 offset:4096
	s_or_b64 exec, exec, s[10:11]
	v_cmp_gt_u32_e64 s[12:13], s73, v91
	s_and_saveexec_b64 s[10:11], s[12:13]
	ds_read_b32 v39, v90 offset:4352
	s_or_b64 exec, exec, s[10:11]
	v_cmp_gt_u32_e64 s[10:11], s73, v89
	v_mov_b32_e32 v38, 0
	s_and_saveexec_b64 s[90:91], s[10:11]
	ds_read_b32 v38, v90 offset:4608
	s_or_b64 exec, exec, s[90:91]
	s_mov_b32 s99, s73
	s_mov_b32 s92, 31
	s_mov_b32 s70, 0
	s_branch .LBB0_1141

; #define LDS_WAIT() asm volatile("s_waitcnt lgkmcnt(0)" ::: "memory")
; template <bool FINAL>
; __device__ __forceinline__ void dsa_prune(LAS unsigned* cs, LAS unsigned short* ci, LAS unsigned* cnt, LAS float* thr, int q, int lane) {
;     ...
;     int base = 0;
; #pragma unroll
;     for (int i = 0; i < NE; ++i) { const int e = i * 64 + lane; const unsigned short id = e < n ? ix[e] : (unsigned short)0;
;         const bool keep = x[i] >= prefix; const unsigned long long mask = __ballot(keep);
;         const int pos = base + (int)__builtin_amdgcn_mbcnt_hi((unsigned)(mask >> 32), __builtin_amdgcn_mbcnt_lo((unsigned)mask, 0u));
;         LDS_WAIT();
;         if (keep) { c[pos] = x[i]; ix[pos] = id; }
;         base += __popcll(mask); }
.LBB0_1143:
	ds_read_u16 v208, v85
	ds_read_u16 v209, v85 offset:128
	ds_read_u16 v210, v85 offset:256
	ds_read_u16 v211, v85 offset:384
	ds_read_u16 v212, v85 offset:512
	ds_read_u16 v213, v85 offset:640
	ds_read_u16 v214, v85 offset:768
	ds_read_u16 v215, v85 offset:896
	ds_read_u16 v216, v85 offset:1024
	ds_read_u16 v217, v85 offset:1152
	ds_read_u16 v218, v85 offset:1280
	ds_read_u16 v219, v85 offset:1408
	ds_read_u16 v220, v85 offset:1536
	ds_read_u16 v221, v85 offset:1664
	ds_read_u16 v222, v85 offset:1792
	ds_read_u16 v223, v85 offset:1920
	ds_read_u16 v224, v85 offset:2048
	ds_read_u16 v225, v85 offset:2176
	ds_read_u16 v226, v85 offset:2304
	s_waitcnt lgkmcnt(0)
	v_mov_b32_e32 v53, v208
	v_cmp_le_u32_e32 vcc, s70, v36
	s_and_saveexec_b64 s[90:91], vcc
	s_cbranch_execz .LBB0_1145
	v_mbcnt_lo_u32_b32 v54, vcc_lo, 0
	v_mbcnt_hi_u32_b32 v54, vcc_hi, v54
	v_lshl_add_u32 v55, v54, 2, s89
	ds_write_b32 v55, v36
	v_lshl_add_u32 v36, v54, 1, s95
	s_waitcnt lgkmcnt(1)
	ds_write_b16 v36, v53
.LBB0_1145:
	s_or_b64 exec, exec, s[90:91]
	v_mov_b32_e32 v36, v209
	s_bcnt1_i32_b64 s73, vcc
	v_cmp_le_u32_e32 vcc, s70, v37
	s_and_saveexec_b64 s[90:91], vcc
	s_cbranch_execz .LBB0_1147
	s_waitcnt lgkmcnt(1)
	v_mbcnt_lo_u32_b32 v53, vcc_lo, 0
	v_mbcnt_hi_u32_b32 v53, vcc_hi, v53
	v_add_u32_e32 v53, s73, v53
	v_lshl_add_u32 v54, v53, 2, s89
	ds_write_b32 v54, v37
	v_lshl_add_u32 v37, v53, 1, s95
	s_waitcnt lgkmcnt(1)
	ds_write_b16 v37, v36
.LBB0_1147:
	s_or_b64 exec, exec, s[90:91]
	s_waitcnt lgkmcnt(0)
	v_mov_b32_e32 v36, v210
	s_bcnt1_i32_b64 s78, vcc
	s_add_i32 s73, s78, s73
	v_cmp_le_u32_e32 vcc, s70, v34
	s_and_saveexec_b64 s[90:91], vcc
	s_cbranch_execz .LBB0_1149
	v_mbcnt_lo_u32_b32 v37, vcc_lo, 0
	v_mbcnt_hi_u32_b32 v37, vcc_hi, v37
	v_add_u32_e32 v37, s73, v37
	v_lshl_add_u32 v53, v37, 2, s89
	ds_write_b32 v53, v34
	v_lshl_add_u32 v34, v37, 1, s95
	s_waitcnt lgkmcnt(1)
	ds_write_b16 v34, v36
.LBB0_1149:
	s_or_b64 exec, exec, s[90:91]
	v_mov_b32_e32 v34, v211
	s_bcnt1_i32_b64 s78, vcc
	s_add_i32 s73, s73, s78
	v_cmp_le_u32_e32 vcc, s70, v35
	s_and_saveexec_b64 s[90:91], vcc
	s_cbranch_execz .LBB0_1151
	s_waitcnt lgkmcnt(1)
	v_mbcnt_lo_u32_b32 v36, vcc_lo, 0
	v_mbcnt_hi_u32_b32 v36, vcc_hi, v36
	v_add_u32_e32 v36, s73, v36
	v_lshl_add_u32 v37, v36, 2, s89
	ds_write_b32 v37, v35
	v_lshl_add_u32 v35, v36, 1, s95
	s_waitcnt lgkmcnt(1)
	ds_write_b16 v35, v34
.LBB0_1151:
	s_or_b64 exec, exec, s[90:91]
	s_waitcnt lgkmcnt(0)
	v_mov_b32_e32 v34, 0
	s_and_saveexec_b64 s[90:91], s[40:41]
	v_mov_b32_e32 v34, v212
	s_or_b64 exec, exec, s[90:91]
	s_bcnt1_i32_b64 s40, vcc
	s_add_i32 s73, s73, s40
	v_cmp_le_u32_e32 vcc, s70, v52
	s_and_saveexec_b64 s[40:41], vcc
	s_cbranch_execz .LBB0_1155
	v_mbcnt_lo_u32_b32 v35, vcc_lo, 0
	v_mbcnt_hi_u32_b32 v35, vcc_hi, v35
	v_add_u32_e32 v35, s73, v35
	v_lshl_add_u32 v36, v35, 2, s89
	v_lshl_add_u32 v35, v35, 1, s95
	ds_write_b32 v36, v52
	s_waitcnt lgkmcnt(1)
	ds_write_b16 v35, v34
.LBB0_1155:
	s_or_b64 exec, exec, s[40:41]
	s_waitcnt lgkmcnt(0)
	v_mov_b32_e32 v34, 0
	s_and_saveexec_b64 s[40:41], s[38:39]
	v_mov_b32_e32 v34, v213
	s_or_b64 exec, exec, s[40:41]
	s_bcnt1_i32_b64 s38, vcc
	s_add_i32 s40, s73, s38
	v_cmp_le_u32_e32 vcc, s70, v51
	s_and_saveexec_b64 s[38:39], vcc
	s_cbranch_execz .LBB0_1159
	v_mbcnt_lo_u32_b32 v35, vcc_lo, 0
	v_mbcnt_hi_u32_b32 v35, vcc_hi, v35
	v_add_u32_e32 v35, s40, v35
	v_lshl_add_u32 v36, v35, 2, s89
	v_lshl_add_u32 v35, v35, 1, s95
	ds_write_b32 v36, v51
	s_waitcnt lgkmcnt(1)
	ds_write_b16 v35, v34
.LBB0_1159:
	s_or_b64 exec, exec, s[38:39]
	s_waitcnt lgkmcnt(0)
	v_mov_b32_e32 v34, 0
	s_and_saveexec_b64 s[38:39], s[36:37]
	v_mov_b32_e32 v34, v214
	s_or_b64 exec, exec, s[38:39]
	s_bcnt1_i32_b64 s36, vcc
	s_add_i32 s38, s40, s36
	v_cmp_le_u32_e32 vcc, s70, v50
	s_and_saveexec_b64 s[36:37], vcc
	s_cbranch_execz .LBB0_1163
	v_mbcnt_lo_u32_b32 v35, vcc_lo, 0
	v_mbcnt_hi_u32_b32 v35, vcc_hi, v35
	v_add_u32_e32 v35, s38, v35
	v_lshl_add_u32 v36, v35, 2, s89
	v_lshl_add_u32 v35, v35, 1, s95
	ds_write_b32 v36, v50
	s_waitcnt lgkmcnt(1)
	ds_write_b16 v35, v34
.LBB0_1163:
	s_or_b64 exec, exec, s[36:37]
	s_waitcnt lgkmcnt(0)
	v_mov_b32_e32 v34, 0
	s_and_saveexec_b64 s[36:37], s[34:35]
	v_mov_b32_e32 v34, v215
	s_or_b64 exec, exec, s[36:37]
	s_bcnt1_i32_b64 s34, vcc
	s_add_i32 s36, s38, s34
	v_cmp_le_u32_e32 vcc, s70, v49
	s_and_saveexec_b64 s[34:35], vcc
	s_cbranch_execz .LBB0_1167
	v_mbcnt_lo_u32_b32 v35, vcc_lo, 0
	v_mbcnt_hi_u32_b32 v35, vcc_hi, v35
	v_add_u32_e32 v35, s36, v35
	v_lshl_add_u32 v36, v35, 2, s89
	v_lshl_add_u32 v35, v35, 1, s95
	ds_write_b32 v36, v49
	s_waitcnt lgkmcnt(1)
	ds_write_b16 v35, v34
.LBB0_1167:
	s_or_b64 exec, exec, s[34:35]
	s_waitcnt lgkmcnt(0)
	v_mov_b32_e32 v34, 0
	s_and_saveexec_b64 s[34:35], s[30:31]
	v_mov_b32_e32 v34, v216
	s_or_b64 exec, exec, s[34:35]
	s_bcnt1_i32_b64 s30, vcc
	s_add_i32 s34, s36, s30
	v_cmp_le_u32_e32 vcc, s70, v48
	s_and_saveexec_b64 s[30:31], vcc
	s_cbranch_execz .LBB0_1171
	v_mbcnt_lo_u32_b32 v35, vcc_lo, 0
	v_mbcnt_hi_u32_b32 v35, vcc_hi, v35
	v_add_u32_e32 v35, s34, v35
	v_lshl_add_u32 v36, v35, 2, s89
	v_lshl_add_u32 v35, v35, 1, s95
	ds_write_b32 v36, v48
	s_waitcnt lgkmcnt(1)
	ds_write_b16 v35, v34
; #define LDS_WAIT() asm volatile("s_waitcnt lgkmcnt(0)" ::: "memory")
; template <bool FINAL>
; __device__ __forceinline__ void dsa_prune(LAS unsigned* cs, LAS unsigned short* ci, LAS unsigned* cnt, LAS float* thr, int q, int lane) {
;     ...
;     int base = 0;
; #pragma unroll
;     for (int i = 0; i < NE; ++i) { const int e = i * 64 + lane; const unsigned short id = e < n ? ix[e] : (unsigned short)0;
;         const bool keep = x[i] >= prefix; const unsigned long long mask = __ballot(keep);
;         const int pos = base + (int)__builtin_amdgcn_mbcnt_hi((unsigned)(mask >> 32), __builtin_amdgcn_mbcnt_lo((unsigned)mask, 0u));
;         LDS_WAIT();
;         if (keep) { c[pos] = x[i]; ix[pos] = id; }
;         base += __popcll(mask); }
.LBB0_1171:
	s_or_b64 exec, exec, s[30:31]
	s_waitcnt lgkmcnt(0)
	v_mov_b32_e32 v34, 0
	s_and_saveexec_b64 s[30:31], s[28:29]
	v_mov_b32_e32 v34, v217
	s_or_b64 exec, exec, s[30:31]
	s_bcnt1_i32_b64 s28, vcc
	s_add_i32 s30, s34, s28
	v_cmp_le_u32_e32 vcc, s70, v47
	s_and_saveexec_b64 s[28:29], vcc
	s_cbranch_execz .LBB0_1175
	v_mbcnt_lo_u32_b32 v35, vcc_lo, 0
	v_mbcnt_hi_u32_b32 v35, vcc_hi, v35
	v_add_u32_e32 v35, s30, v35
	v_lshl_add_u32 v36, v35, 2, s89
	v_lshl_add_u32 v35, v35, 1, s95
	ds_write_b32 v36, v47
	s_waitcnt lgkmcnt(1)
	ds_write_b16 v35, v34
.LBB0_1175:
	s_or_b64 exec, exec, s[28:29]
	s_waitcnt lgkmcnt(0)
	v_mov_b32_e32 v34, 0
	s_and_saveexec_b64 s[28:29], s[26:27]
	v_mov_b32_e32 v34, v218
	s_or_b64 exec, exec, s[28:29]
	s_bcnt1_i32_b64 s26, vcc
	s_add_i32 s28, s30, s26
	v_cmp_le_u32_e32 vcc, s70, v46
	s_and_saveexec_b64 s[26:27], vcc
	s_cbranch_execz .LBB0_1179
	v_mbcnt_lo_u32_b32 v35, vcc_lo, 0
	v_mbcnt_hi_u32_b32 v35, vcc_hi, v35
	v_add_u32_e32 v35, s28, v35
	v_lshl_add_u32 v36, v35, 2, s89
	v_lshl_add_u32 v35, v35, 1, s95
	ds_write_b32 v36, v46
	s_waitcnt lgkmcnt(1)
	ds_write_b16 v35, v34
.LBB0_1179:
	s_or_b64 exec, exec, s[26:27]
	s_waitcnt lgkmcnt(0)
	v_mov_b32_e32 v34, 0
	s_and_saveexec_b64 s[26:27], s[24:25]
	v_mov_b32_e32 v34, v219
	s_or_b64 exec, exec, s[26:27]
	s_bcnt1_i32_b64 s24, vcc
	s_add_i32 s26, s28, s24
	v_cmp_le_u32_e32 vcc, s70, v45
	s_and_saveexec_b64 s[24:25], vcc
	s_cbranch_execz .LBB0_1183
	v_mbcnt_lo_u32_b32 v35, vcc_lo, 0
	v_mbcnt_hi_u32_b32 v35, vcc_hi, v35
	v_add_u32_e32 v35, s26, v35
	v_lshl_add_u32 v36, v35, 2, s89
	v_lshl_add_u32 v35, v35, 1, s95
	ds_write_b32 v36, v45
	s_waitcnt lgkmcnt(1)
	ds_write_b16 v35, v34
.LBB0_1183:
	s_or_b64 exec, exec, s[24:25]
	s_waitcnt lgkmcnt(0)
	v_mov_b32_e32 v34, 0
	s_and_saveexec_b64 s[24:25], s[22:23]
	v_mov_b32_e32 v34, v220
	s_or_b64 exec, exec, s[24:25]
	s_bcnt1_i32_b64 s22, vcc
	s_add_i32 s24, s26, s22
	v_cmp_le_u32_e32 vcc, s70, v44
	s_and_saveexec_b64 s[22:23], vcc
	s_cbranch_execz .LBB0_1187
	v_mbcnt_lo_u32_b32 v35, vcc_lo, 0
	v_mbcnt_hi_u32_b32 v35, vcc_hi, v35
	v_add_u32_e32 v35, s24, v35
	v_lshl_add_u32 v36, v35, 2, s89
	v_lshl_add_u32 v35, v35, 1, s95
	ds_write_b32 v36, v44
	s_waitcnt lgkmcnt(1)
	ds_write_b16 v35, v34
.LBB0_1187:
	s_or_b64 exec, exec, s[22:23]
	s_waitcnt lgkmcnt(0)
	v_mov_b32_e32 v34, 0
	s_and_saveexec_b64 s[22:23], s[20:21]
	v_mov_b32_e32 v34, v221
	s_or_b64 exec, exec, s[22:23]
	s_bcnt1_i32_b64 s20, vcc
	s_add_i32 s22, s24, s20
	v_cmp_le_u32_e32 vcc, s70, v43
	s_and_saveexec_b64 s[20:21], vcc
	s_cbranch_execz .LBB0_1191
	v_mbcnt_lo_u32_b32 v35, vcc_lo, 0
	v_mbcnt_hi_u32_b32 v35, vcc_hi, v35
	v_add_u32_e32 v35, s22, v35
	v_lshl_add_u32 v36, v35, 2, s89
	v_lshl_add_u32 v35, v35, 1, s95
	ds_write_b32 v36, v43
	s_waitcnt lgkmcnt(1)
	ds_write_b16 v35, v34
.LBB0_1191:
	s_or_b64 exec, exec, s[20:21]
	s_waitcnt lgkmcnt(0)
	v_mov_b32_e32 v34, 0
	s_and_saveexec_b64 s[20:21], s[18:19]
	v_mov_b32_e32 v34, v222
	s_or_b64 exec, exec, s[20:21]
	s_bcnt1_i32_b64 s18, vcc
	s_add_i32 s20, s22, s18
	v_cmp_le_u32_e32 vcc, s70, v42
	s_and_saveexec_b64 s[18:19], vcc
	s_cbranch_execz .LBB0_1195
	v_mbcnt_lo_u32_b32 v35, vcc_lo, 0
	v_mbcnt_hi_u32_b32 v35, vcc_hi, v35
	v_add_u32_e32 v35, s20, v35
	v_lshl_add_u32 v36, v35, 2, s89
	v_lshl_add_u32 v35, v35, 1, s95
	ds_write_b32 v36, v42
	s_waitcnt lgkmcnt(1)
	ds_write_b16 v35, v34
.LBB0_1195:
	s_or_b64 exec, exec, s[18:19]
	s_waitcnt lgkmcnt(0)
	v_mov_b32_e32 v34, 0
	s_and_saveexec_b64 s[18:19], s[16:17]
	v_mov_b32_e32 v34, v223
	s_or_b64 exec, exec, s[18:19]
	s_bcnt1_i32_b64 s16, vcc
	s_add_i32 s18, s20, s16
	v_cmp_le_u32_e32 vcc, s70, v41
	s_and_saveexec_b64 s[16:17], vcc
	s_cbranch_execz .LBB0_1199
	v_mbcnt_lo_u32_b32 v35, vcc_lo, 0
	v_mbcnt_hi_u32_b32 v35, vcc_hi, v35
	v_add_u32_e32 v35, s18, v35
	v_lshl_add_u32 v36, v35, 2, s89
	v_lshl_add_u32 v35, v35, 1, s95
	ds_write_b32 v36, v41
	s_waitcnt lgkmcnt(1)
	ds_write_b16 v35, v34
.LBB0_1199:
	s_or_b64 exec, exec, s[16:17]
	s_waitcnt lgkmcnt(0)
	v_mov_b32_e32 v34, 0
	s_and_saveexec_b64 s[16:17], s[14:15]
	v_mov_b32_e32 v34, v224
	s_or_b64 exec, exec, s[16:17]
	s_bcnt1_i32_b64 s14, vcc
	s_add_i32 s16, s18, s14
	v_cmp_le_u32_e32 vcc, s70, v40
	s_and_saveexec_b64 s[14:15], vcc
	s_cbranch_execz .LBB0_1203
	v_mbcnt_lo_u32_b32 v35, vcc_lo, 0
	v_mbcnt_hi_u32_b32 v35, vcc_hi, v35
	v_add_u32_e32 v35, s16, v35
	v_lshl_add_u32 v36, v35, 2, s89
	v_lshl_add_u32 v35, v35, 1, s95
	ds_write_b32 v36, v40
	s_waitcnt lgkmcnt(1)
	ds_write_b16 v35, v34
.LBB0_1203:
	s_or_b64 exec, exec, s[14:15]
	s_waitcnt lgkmcnt(0)
	v_mov_b32_e32 v34, 0
	s_and_saveexec_b64 s[14:15], s[12:13]
	v_mov_b32_e32 v34, v225
	s_or_b64 exec, exec, s[14:15]
	s_bcnt1_i32_b64 s12, vcc
	s_add_i32 s14, s16, s12
	v_cmp_le_u32_e32 vcc, s70, v39
	s_and_saveexec_b64 s[12:13], vcc
	s_cbranch_execz .LBB0_1207
	v_mbcnt_lo_u32_b32 v35, vcc_lo, 0
	v_mbcnt_hi_u32_b32 v35, vcc_hi, v35
	v_add_u32_e32 v35, s14, v35
	v_lshl_add_u32 v36, v35, 2, s89
	v_lshl_add_u32 v35, v35, 1, s95
	ds_write_b32 v36, v39
	s_waitcnt lgkmcnt(1)
	ds_write_b16 v35, v34
.LBB0_1207:
	s_or_b64 exec, exec, s[12:13]
	s_waitcnt lgkmcnt(0)
	v_mov_b32_e32 v34, 0
	s_and_saveexec_b64 s[12:13], s[10:11]
	v_mov_b32_e32 v34, v226
	s_or_b64 exec, exec, s[12:13]
	s_bcnt1_i32_b64 s10, vcc
	s_add_i32 s12, s14, s10
	v_cmp_le_u32_e32 vcc, s70, v38
	s_and_saveexec_b64 s[10:11], vcc
	s_cbranch_execz .LBB0_1211
	v_mbcnt_lo_u32_b32 v35, vcc_lo, 0
	v_mbcnt_hi_u32_b32 v35, vcc_hi, v35
	v_add_u32_e32 v35, s12, v35
	v_lshl_add_u32 v36, v35, 2, s89
	v_lshl_add_u32 v35, v35, 1, s95
	ds_write_b32 v36, v38
	s_waitcnt lgkmcnt(1)
	ds_write_b16 v35, v34

; #define LAS __attribute__((address_space(3)))
; #define LDS_WAIT() asm volatile("s_waitcnt lgkmcnt(0)" ::: "memory")
; template <bool FINAL>
; __device__ __forceinline__ void dsa_prune(LAS unsigned* cs, LAS unsigned short* ci, LAS unsigned* cnt, LAS float* thr, int q, int lane) {
;     const int n = __builtin_amdgcn_readfirstlane((int)cnt[q]);
;     if (n <= 256) return;
;     LAS unsigned* c = cs + q * CAP; LAS unsigned short* ix = ci + q * CAP;
;     constexpr int NE = CAP / 64;
;     unsigned x[NE];
; #pragma unroll
;     for (int i = 0; i < NE; ++i) { const int e = i * 64 + lane; x[i] = e < n ? c[e] : 0u; }
;     unsigned prefix = 0u; int kp = n;
;     ...
; #pragma unroll
;         for (int i = 0; i < NE; ++i) k += __popcll(__ballot(x[i] >= trial));
;         if (k >= 256) { prefix = trial; kp = k; }
;         if (kp == 256 || (!FINAL && bit <= 16 && kp <= 320)) break; }
;     int base = 0;
; #pragma unroll
;     for (int i = 0; i < NE; ++i) { const int e = i * 64 + lane; const unsigned short id = e < n ? ix[e] : (unsigned short)0;
;         const bool keep = x[i] >= prefix; const unsigned long long mask = __ballot(keep);
;         const int pos = base + (int)__builtin_amdgcn_mbcnt_hi((unsigned)(mask >> 32), __builtin_amdgcn_mbcnt_lo((unsigned)mask, 0u));
;         LDS_WAIT();
;         if (keep) { c[pos] = x[i]; ix[pos] = id; }
;         base += __popcll(mask); }
;     if (lane == 0) { cnt[q] = (unsigned)base; thr[q] = ord2f(prefix); }
.LBB0_1219:
	s_or_b64 exec, exec, s[10:11]
	v_mov_b32_e32 v2, s66
	ds_read_b32 v2, v2
	v_readlane_b32 s79, v236, 39
	s_movk_i32 s96, 0x100
	s_waitcnt lgkmcnt(0)
	v_readfirstlane_b32 s1, v2
	s_cmpk_lt_i32 s1, 0x101
	s_cbranch_scc1 .LBB0_1323
	ds_read2st64_b32 v[4:5], v108 offset1:1
	ds_read2st64_b32 v[2:3], v108 offset0:2 offset1:3
	v_cmp_gt_u32_e64 s[40:41], s1, v106
	v_mov_b32_e32 v19, 0
	v_mov_b32_e32 v20, 0
	s_and_saveexec_b64 s[10:11], s[40:41]
	ds_read_b32 v20, v108 offset:1024
	s_or_b64 exec, exec, s[10:11]
	v_cmp_gt_u32_e64 s[38:39], s1, v105
	s_and_saveexec_b64 s[10:11], s[38:39]
	ds_read_b32 v19, v108 offset:1280
	s_or_b64 exec, exec, s[10:11]
	v_cmp_gt_u32_e64 s[36:37], s1, v104
	v_mov_b32_e32 v17, 0
	v_mov_b32_e32 v18, 0
	s_and_saveexec_b64 s[10:11], s[36:37]
	ds_read_b32 v18, v108 offset:1536
	s_or_b64 exec, exec, s[10:11]
	v_cmp_gt_u32_e64 s[34:35], s1, v103
	s_and_saveexec_b64 s[10:11], s[34:35]
	ds_read_b32 v17, v108 offset:1792
	s_or_b64 exec, exec, s[10:11]
	v_cmp_gt_u32_e64 s[30:31], s1, v102
	v_mov_b32_e32 v15, 0
	v_mov_b32_e32 v16, 0
	s_and_saveexec_b64 s[10:11], s[30:31]
	ds_read_b32 v16, v108 offset:2048
	s_or_b64 exec, exec, s[10:11]
	v_cmp_gt_u32_e64 s[28:29], s1, v101
	s_and_saveexec_b64 s[10:11], s[28:29]
	ds_read_b32 v15, v108 offset:2304
	s_or_b64 exec, exec, s[10:11]
	v_cmp_gt_u32_e64 s[26:27], s1, v100
	v_mov_b32_e32 v13, 0
	v_mov_b32_e32 v14, 0
	s_and_saveexec_b64 s[10:11], s[26:27]
	ds_read_b32 v14, v108 offset:2560
	s_or_b64 exec, exec, s[10:11]
	v_cmp_gt_u32_e64 s[24:25], s1, v99
	s_and_saveexec_b64 s[10:11], s[24:25]
	ds_read_b32 v13, v108 offset:2816
	s_or_b64 exec, exec, s[10:11]
	v_cmp_gt_u32_e64 s[22:23], s1, v98
	v_mov_b32_e32 v11, 0
	v_mov_b32_e32 v12, 0
	s_and_saveexec_b64 s[10:11], s[22:23]
	ds_read_b32 v12, v108 offset:3072
	s_or_b64 exec, exec, s[10:11]
	v_cmp_gt_u32_e64 s[20:21], s1, v97
	s_and_saveexec_b64 s[10:11], s[20:21]
	ds_read_b32 v11, v108 offset:3328
	s_or_b64 exec, exec, s[10:11]
	v_cmp_gt_u32_e64 s[18:19], s1, v96
	v_mov_b32_e32 v9, 0
	v_mov_b32_e32 v10, 0
	s_and_saveexec_b64 s[10:11], s[18:19]
	ds_read_b32 v10, v108 offset:3584
	s_or_b64 exec, exec, s[10:11]
	v_cmp_gt_u32_e64 s[16:17], s1, v93
	s_and_saveexec_b64 s[10:11], s[16:17]
	ds_read_b32 v9, v108 offset:3840
	s_or_b64 exec, exec, s[10:11]
	v_cmp_gt_u32_e64 s[14:15], s1, v92
	v_mov_b32_e32 v7, 0
	v_mov_b32_e32 v8, 0
	s_and_saveexec_b64 s[10:11], s[14:15]
	ds_read_b32 v8, v108 offset:4096
	s_or_b64 exec, exec, s[10:11]
	v_cmp_gt_u32_e64 s[12:13], s1, v91
	s_and_saveexec_b64 s[10:11], s[12:13]
	ds_read_b32 v7, v108 offset:4352
	s_or_b64 exec, exec, s[10:11]
	v_cmp_gt_u32_e64 s[10:11], s1, v89
	v_mov_b32_e32 v6, 0
	s_and_saveexec_b64 s[42:43], s[10:11]
	ds_read_b32 v6, v108 offset:4608
	s_or_b64 exec, exec, s[42:43]
	s_mov_b32 s99, s1
	s_mov_b32 s70, 31
	s_mov_b32 s0, 0
.LBB0_1251:
	s_lshl_b32 s42, 1, s70
	s_or_b32 s42, s42, s0
	s_waitcnt lgkmcnt(0)
	v_cmp_le_u32_e32 vcc, s42, v4
	s_bcnt1_i32_b64 s43, vcc
	v_cmp_le_u32_e32 vcc, s42, v5
	s_bcnt1_i32_b64 s32, vcc
	s_add_i32 s43, s43, s32
	v_cmp_le_u32_e32 vcc, s42, v2
	s_bcnt1_i32_b64 s32, vcc
	s_add_i32 s43, s43, s32
	v_cmp_le_u32_e32 vcc, s42, v3
	s_bcnt1_i32_b64 s32, vcc
	s_add_i32 s43, s43, s32
	v_cmp_le_u32_e32 vcc, s42, v20
	s_bcnt1_i32_b64 s32, vcc
	s_add_i32 s43, s43, s32
	s_cmpk_le_u32 s99, 320
	s_cbranch_scc1 .Lps_done_c
	v_cmp_le_u32_e32 vcc, s42, v19
	s_bcnt1_i32_b64 s32, vcc
	s_add_i32 s43, s43, s32
	v_cmp_le_u32_e32 vcc, s42, v18
	s_bcnt1_i32_b64 s32, vcc
	s_add_i32 s43, s43, s32
	v_cmp_le_u32_e32 vcc, s42, v17
	s_bcnt1_i32_b64 s32, vcc
	s_add_i32 s43, s43, s32
	s_cmpk_le_u32 s99, 512
	s_cbranch_scc1 .Lps_done_c
	v_cmp_le_u32_e32 vcc, s42, v16
	s_bcnt1_i32_b64 s32, vcc
	s_add_i32 s43, s43, s32
	v_cmp_le_u32_e32 vcc, s42, v15
	s_bcnt1_i32_b64 s32, vcc
	s_add_i32 s43, s43, s32
	v_cmp_le_u32_e32 vcc, s42, v14
	s_bcnt1_i32_b64 s32, vcc
	s_add_i32 s43, s43, s32
	v_cmp_le_u32_e32 vcc, s42, v13
	s_bcnt1_i32_b64 s32, vcc
	s_add_i32 s43, s43, s32
	s_cmpk_le_u32 s99, 768
	s_cbranch_scc1 .Lps_done_c
	v_cmp_le_u32_e32 vcc, s42, v12
	s_bcnt1_i32_b64 s32, vcc
	s_add_i32 s43, s43, s32
	v_cmp_le_u32_e32 vcc, s42, v11
	s_bcnt1_i32_b64 s32, vcc
	s_add_i32 s43, s43, s32
	v_cmp_le_u32_e32 vcc, s42, v10
	s_bcnt1_i32_b64 s32, vcc
	s_add_i32 s43, s43, s32
	s_cmpk_le_u32 s99, 960
	s_cbranch_scc1 .Lps_done_c
	v_cmp_le_u32_e32 vcc, s42, v9
	s_bcnt1_i32_b64 s32, vcc
	s_add_i32 s43, s43, s32
	v_cmp_le_u32_e32 vcc, s42, v8
	s_bcnt1_i32_b64 s32, vcc
	s_add_i32 s43, s43, s32
	v_cmp_le_u32_e32 vcc, s42, v7
	s_bcnt1_i32_b64 s32, vcc
	s_add_i32 s43, s43, s32
	v_cmp_le_u32_e32 vcc, s42, v6
	s_bcnt1_i32_b64 s32, vcc
	s_add_i32 s43, s43, s32
.Lps_done_c:
	s_cmpk_gt_u32 s43, 0xff
	s_cselect_b32 s1, s43, s1
	s_cselect_b32 s0, s42, s0
	s_cmpk_eq_i32 s1, 0x100
	s_cselect_b64 s[42:43], -1, 0
	v_sub_co_u32_e64 v21, s[90:91], s70, 1
	s_or_b64 s[42:43], s[42:43], s[90:91]
	v_readfirstlane_b32 s70, v21
	s_andn2_b64 vcc, exec, s[42:43]
	s_cbranch_vccnz .LBB0_1251
	ds_read_u16 v208, v107
	ds_read_u16 v209, v107 offset:128
	ds_read_u16 v210, v107 offset:256
	ds_read_u16 v211, v107 offset:384
	ds_read_u16 v212, v107 offset:512
	ds_read_u16 v213, v107 offset:640
	ds_read_u16 v214, v107 offset:768
	ds_read_u16 v215, v107 offset:896
	ds_read_u16 v216, v107 offset:1024
	ds_read_u16 v217, v107 offset:1152
	ds_read_u16 v218, v107 offset:1280
	ds_read_u16 v219, v107 offset:1408
	ds_read_u16 v220, v107 offset:1536
	ds_read_u16 v221, v107 offset:1664
	ds_read_u16 v222, v107 offset:1792
	ds_read_u16 v223, v107 offset:1920
	ds_read_u16 v224, v107 offset:2048
	ds_read_u16 v225, v107 offset:2176
	ds_read_u16 v226, v107 offset:2304
	s_waitcnt lgkmcnt(0)
	v_mov_b32_e32 v21, v208
	v_cmp_le_u32_e32 vcc, s0, v4
	s_and_saveexec_b64 s[42:43], vcc
	s_cbranch_execz .LBB0_1254
	v_mbcnt_lo_u32_b32 v22, vcc_lo, 0
	v_mbcnt_hi_u32_b32 v22, vcc_hi, v22
	v_lshl_add_u32 v23, v22, 2, s67
	ds_write_b32 v23, v4
	v_lshl_add_u32 v4, v22, 1, s80
	s_waitcnt lgkmcnt(1)
	ds_write_b16 v4, v21
; #define LDS_WAIT() asm volatile("s_waitcnt lgkmcnt(0)" ::: "memory")
; template <bool FINAL>
; __device__ __forceinline__ void dsa_prune(LAS unsigned* cs, LAS unsigned short* ci, LAS unsigned* cnt, LAS float* thr, int q, int lane) {
;     ...
;     int base = 0;
; #pragma unroll
;     for (int i = 0; i < NE; ++i) { const int e = i * 64 + lane; const unsigned short id = e < n ? ix[e] : (unsigned short)0;
;         const bool keep = x[i] >= prefix; const unsigned long long mask = __ballot(keep);
;         const int pos = base + (int)__builtin_amdgcn_mbcnt_hi((unsigned)(mask >> 32), __builtin_amdgcn_mbcnt_lo((unsigned)mask, 0u));
;         LDS_WAIT();
;         if (keep) { c[pos] = x[i]; ix[pos] = id; }
;         base += __popcll(mask); }
.LBB0_1254:
	s_or_b64 exec, exec, s[42:43]
	v_mov_b32_e32 v4, v209
	s_bcnt1_i32_b64 s1, vcc
	v_cmp_le_u32_e32 vcc, s0, v5
	s_and_saveexec_b64 s[42:43], vcc
	s_cbranch_execz .LBB0_1256
	s_waitcnt lgkmcnt(1)
	v_mbcnt_lo_u32_b32 v21, vcc_lo, 0
	v_mbcnt_hi_u32_b32 v21, vcc_hi, v21
	v_add_u32_e32 v21, s1, v21
	v_lshl_add_u32 v22, v21, 2, s67
	ds_write_b32 v22, v5
	v_lshl_add_u32 v5, v21, 1, s80
	s_waitcnt lgkmcnt(1)
	ds_write_b16 v5, v4
.LBB0_1256:
	s_or_b64 exec, exec, s[42:43]
	s_waitcnt lgkmcnt(0)
	v_mov_b32_e32 v4, v210
	s_bcnt1_i32_b64 s42, vcc
	s_add_i32 s1, s42, s1
	v_cmp_le_u32_e32 vcc, s0, v2
	s_and_saveexec_b64 s[42:43], vcc
	s_cbranch_execz .LBB0_1258
	v_mbcnt_lo_u32_b32 v5, vcc_lo, 0
	v_mbcnt_hi_u32_b32 v5, vcc_hi, v5
	v_add_u32_e32 v5, s1, v5
	v_lshl_add_u32 v21, v5, 2, s67
	ds_write_b32 v21, v2
	v_lshl_add_u32 v2, v5, 1, s80
	s_waitcnt lgkmcnt(1)
	ds_write_b16 v2, v4
.LBB0_1258:
	s_or_b64 exec, exec, s[42:43]
	v_mov_b32_e32 v2, v211
	s_bcnt1_i32_b64 s42, vcc
	s_add_i32 s1, s1, s42
	v_cmp_le_u32_e32 vcc, s0, v3
	s_and_saveexec_b64 s[42:43], vcc
	s_cbranch_execz .LBB0_1260
	s_waitcnt lgkmcnt(1)
	v_mbcnt_lo_u32_b32 v4, vcc_lo, 0
	v_mbcnt_hi_u32_b32 v4, vcc_hi, v4
	v_add_u32_e32 v4, s1, v4
	v_lshl_add_u32 v5, v4, 2, s67
	ds_write_b32 v5, v3
	v_lshl_add_u32 v3, v4, 1, s80
	s_waitcnt lgkmcnt(1)
	ds_write_b16 v3, v2
.LBB0_1260:
	s_or_b64 exec, exec, s[42:43]
	s_waitcnt lgkmcnt(0)
	v_mov_b32_e32 v2, 0
	s_and_saveexec_b64 s[42:43], s[40:41]
	v_mov_b32_e32 v2, v212
	s_or_b64 exec, exec, s[42:43]
	s_bcnt1_i32_b64 s40, vcc
	s_add_i32 s1, s1, s40
	v_cmp_le_u32_e32 vcc, s0, v20
	s_and_saveexec_b64 s[40:41], vcc
	s_cbranch_execz .LBB0_1264
	v_mbcnt_lo_u32_b32 v3, vcc_lo, 0
	v_mbcnt_hi_u32_b32 v3, vcc_hi, v3
	v_add_u32_e32 v3, s1, v3
	v_lshl_add_u32 v4, v3, 2, s67
	v_lshl_add_u32 v3, v3, 1, s80
	ds_write_b32 v4, v20
	s_waitcnt lgkmcnt(1)
	ds_write_b16 v3, v2
.LBB0_1264:
	s_or_b64 exec, exec, s[40:41]
	s_waitcnt lgkmcnt(0)
	v_mov_b32_e32 v2, 0
	s_and_saveexec_b64 s[40:41], s[38:39]
	v_mov_b32_e32 v2, v213
	s_or_b64 exec, exec, s[40:41]
	s_bcnt1_i32_b64 s38, vcc
	s_add_i32 s1, s1, s38
	v_cmp_le_u32_e32 vcc, s0, v19
	s_and_saveexec_b64 s[38:39], vcc
	s_cbranch_execz .LBB0_1268
	v_mbcnt_lo_u32_b32 v3, vcc_lo, 0
	v_mbcnt_hi_u32_b32 v3, vcc_hi, v3
	v_add_u32_e32 v3, s1, v3
	v_lshl_add_u32 v4, v3, 2, s67
	v_lshl_add_u32 v3, v3, 1, s80
	ds_write_b32 v4, v19
	s_waitcnt lgkmcnt(1)
	ds_write_b16 v3, v2
.LBB0_1268:
	s_or_b64 exec, exec, s[38:39]
	s_waitcnt lgkmcnt(0)
	v_mov_b32_e32 v2, 0
	s_and_saveexec_b64 s[38:39], s[36:37]
	v_mov_b32_e32 v2, v214
	s_or_b64 exec, exec, s[38:39]
	s_bcnt1_i32_b64 s36, vcc
	s_add_i32 s1, s1, s36
	v_cmp_le_u32_e32 vcc, s0, v18
	s_and_saveexec_b64 s[36:37], vcc
	s_cbranch_execz .LBB0_1272
	v_mbcnt_lo_u32_b32 v3, vcc_lo, 0
	v_mbcnt_hi_u32_b32 v3, vcc_hi, v3
	v_add_u32_e32 v3, s1, v3
	v_lshl_add_u32 v4, v3, 2, s67
	v_lshl_add_u32 v3, v3, 1, s80
	ds_write_b32 v4, v18
	s_waitcnt lgkmcnt(1)
	ds_write_b16 v3, v2
.LBB0_1272:
	s_or_b64 exec, exec, s[36:37]
	s_waitcnt lgkmcnt(0)
	v_mov_b32_e32 v2, 0
	s_and_saveexec_b64 s[36:37], s[34:35]
	v_mov_b32_e32 v2, v215
	s_or_b64 exec, exec, s[36:37]
	s_bcnt1_i32_b64 s34, vcc
	s_add_i32 s1, s1, s34
	v_cmp_le_u32_e32 vcc, s0, v17
	s_and_saveexec_b64 s[34:35], vcc
	s_cbranch_execz .LBB0_1276
	v_mbcnt_lo_u32_b32 v3, vcc_lo, 0
	v_mbcnt_hi_u32_b32 v3, vcc_hi, v3
	v_add_u32_e32 v3, s1, v3
	v_lshl_add_u32 v4, v3, 2, s67
	v_lshl_add_u32 v3, v3, 1, s80
	ds_write_b32 v4, v17
	s_waitcnt lgkmcnt(1)
	ds_write_b16 v3, v2
.LBB0_1276:
	s_or_b64 exec, exec, s[34:35]
	s_waitcnt lgkmcnt(0)
	v_mov_b32_e32 v2, 0
	s_and_saveexec_b64 s[34:35], s[30:31]
	v_mov_b32_e32 v2, v216
	s_or_b64 exec, exec, s[34:35]
	s_bcnt1_i32_b64 s30, vcc
	s_add_i32 s1, s1, s30
	v_cmp_le_u32_e32 vcc, s0, v16
	s_and_saveexec_b64 s[30:31], vcc
	s_cbranch_execz .LBB0_1280
	v_mbcnt_lo_u32_b32 v3, vcc_lo, 0
	v_mbcnt_hi_u32_b32 v3, vcc_hi, v3
	v_add_u32_e32 v3, s1, v3
	v_lshl_add_u32 v4, v3, 2, s67
	v_lshl_add_u32 v3, v3, 1, s80
	ds_write_b32 v4, v16
	s_waitcnt lgkmcnt(1)
	ds_write_b16 v3, v2
.LBB0_1280:
	s_or_b64 exec, exec, s[30:31]
	s_waitcnt lgkmcnt(0)
	v_mov_b32_e32 v2, 0
	s_and_saveexec_b64 s[30:31], s[28:29]
	v_mov_b32_e32 v2, v217
	s_or_b64 exec, exec, s[30:31]
	s_bcnt1_i32_b64 s28, vcc
	s_add_i32 s1, s1, s28
	v_cmp_le_u32_e32 vcc, s0, v15
	s_and_saveexec_b64 s[28:29], vcc
	s_cbranch_execz .LBB0_1284
	v_mbcnt_lo_u32_b32 v3, vcc_lo, 0
	v_mbcnt_hi_u32_b32 v3, vcc_hi, v3
	v_add_u32_e32 v3, s1, v3
	v_lshl_add_u32 v4, v3, 2, s67
	v_lshl_add_u32 v3, v3, 1, s80
	ds_write_b32 v4, v15
	s_waitcnt lgkmcnt(1)
	ds_write_b16 v3, v2
; #define LDS_WAIT() asm volatile("s_waitcnt lgkmcnt(0)" ::: "memory")
; template <bool FINAL>
; __device__ __forceinline__ void dsa_prune(LAS unsigned* cs, LAS unsigned short* ci, LAS unsigned* cnt, LAS float* thr, int q, int lane) {
;     ...
;     int base = 0;
; #pragma unroll
;     for (int i = 0; i < NE; ++i) { const int e = i * 64 + lane; const unsigned short id = e < n ? ix[e] : (unsigned short)0;
;         const bool keep = x[i] >= prefix; const unsigned long long mask = __ballot(keep);
;         const int pos = base + (int)__builtin_amdgcn_mbcnt_hi((unsigned)(mask >> 32), __builtin_amdgcn_mbcnt_lo((unsigned)mask, 0u));
;         LDS_WAIT();
;         if (keep) { c[pos] = x[i]; ix[pos] = id; }
;         base += __popcll(mask); }
.LBB0_1284:
	s_or_b64 exec, exec, s[28:29]
	s_waitcnt lgkmcnt(0)
	v_mov_b32_e32 v2, 0
	s_and_saveexec_b64 s[28:29], s[26:27]
	v_mov_b32_e32 v2, v218
	s_or_b64 exec, exec, s[28:29]
	s_bcnt1_i32_b64 s26, vcc
	s_add_i32 s1, s1, s26
	v_cmp_le_u32_e32 vcc, s0, v14
	s_and_saveexec_b64 s[26:27], vcc
	s_cbranch_execz .LBB0_1288
	v_mbcnt_lo_u32_b32 v3, vcc_lo, 0
	v_mbcnt_hi_u32_b32 v3, vcc_hi, v3
	v_add_u32_e32 v3, s1, v3
	v_lshl_add_u32 v4, v3, 2, s67
	v_lshl_add_u32 v3, v3, 1, s80
	ds_write_b32 v4, v14
	s_waitcnt lgkmcnt(1)
	ds_write_b16 v3, v2
.LBB0_1288:
	s_or_b64 exec, exec, s[26:27]
	s_waitcnt lgkmcnt(0)
	v_mov_b32_e32 v2, 0
	s_and_saveexec_b64 s[26:27], s[24:25]
	v_mov_b32_e32 v2, v219
	s_or_b64 exec, exec, s[26:27]
	s_bcnt1_i32_b64 s24, vcc
	s_add_i32 s1, s1, s24
	v_cmp_le_u32_e32 vcc, s0, v13
	s_and_saveexec_b64 s[24:25], vcc
	s_cbranch_execz .LBB0_1292
	v_mbcnt_lo_u32_b32 v3, vcc_lo, 0
	v_mbcnt_hi_u32_b32 v3, vcc_hi, v3
	v_add_u32_e32 v3, s1, v3
	v_lshl_add_u32 v4, v3, 2, s67
	v_lshl_add_u32 v3, v3, 1, s80
	ds_write_b32 v4, v13
	s_waitcnt lgkmcnt(1)
	ds_write_b16 v3, v2
.LBB0_1292:
	s_or_b64 exec, exec, s[24:25]
	s_waitcnt lgkmcnt(0)
	v_mov_b32_e32 v2, 0
	s_and_saveexec_b64 s[24:25], s[22:23]
	v_mov_b32_e32 v2, v220
	s_or_b64 exec, exec, s[24:25]
	s_bcnt1_i32_b64 s22, vcc
	s_add_i32 s1, s1, s22
	v_cmp_le_u32_e32 vcc, s0, v12
	s_and_saveexec_b64 s[22:23], vcc
	s_cbranch_execz .LBB0_1296
	v_mbcnt_lo_u32_b32 v3, vcc_lo, 0
	v_mbcnt_hi_u32_b32 v3, vcc_hi, v3
	v_add_u32_e32 v3, s1, v3
	v_lshl_add_u32 v4, v3, 2, s67
	v_lshl_add_u32 v3, v3, 1, s80
	ds_write_b32 v4, v12
	s_waitcnt lgkmcnt(1)
	ds_write_b16 v3, v2
.LBB0_1296:
	s_or_b64 exec, exec, s[22:23]
	s_waitcnt lgkmcnt(0)
	v_mov_b32_e32 v2, 0
	s_and_saveexec_b64 s[22:23], s[20:21]
	v_mov_b32_e32 v2, v221
	s_or_b64 exec, exec, s[22:23]
	s_bcnt1_i32_b64 s20, vcc
	s_add_i32 s1, s1, s20
	v_cmp_le_u32_e32 vcc, s0, v11
	s_and_saveexec_b64 s[20:21], vcc
	s_cbranch_execz .LBB0_1300
	v_mbcnt_lo_u32_b32 v3, vcc_lo, 0
	v_mbcnt_hi_u32_b32 v3, vcc_hi, v3
	v_add_u32_e32 v3, s1, v3
	v_lshl_add_u32 v4, v3, 2, s67
	v_lshl_add_u32 v3, v3, 1, s80
	ds_write_b32 v4, v11
	s_waitcnt lgkmcnt(1)
	ds_write_b16 v3, v2
.LBB0_1300:
	s_or_b64 exec, exec, s[20:21]
	s_waitcnt lgkmcnt(0)
	v_mov_b32_e32 v2, 0
	s_and_saveexec_b64 s[20:21], s[18:19]
	v_mov_b32_e32 v2, v222
	s_or_b64 exec, exec, s[20:21]
	s_bcnt1_i32_b64 s18, vcc
	s_add_i32 s1, s1, s18
	v_cmp_le_u32_e32 vcc, s0, v10
	s_and_saveexec_b64 s[18:19], vcc
	s_cbranch_execz .LBB0_1304
	v_mbcnt_lo_u32_b32 v3, vcc_lo, 0
	v_mbcnt_hi_u32_b32 v3, vcc_hi, v3
	v_add_u32_e32 v3, s1, v3
	v_lshl_add_u32 v4, v3, 2, s67
	v_lshl_add_u32 v3, v3, 1, s80
	ds_write_b32 v4, v10
	s_waitcnt lgkmcnt(1)
	ds_write_b16 v3, v2
.LBB0_1304:
	s_or_b64 exec, exec, s[18:19]
	s_waitcnt lgkmcnt(0)
	v_mov_b32_e32 v2, 0
	s_and_saveexec_b64 s[18:19], s[16:17]
	v_mov_b32_e32 v2, v223
	s_or_b64 exec, exec, s[18:19]
	s_bcnt1_i32_b64 s16, vcc
	s_add_i32 s1, s1, s16
	v_cmp_le_u32_e32 vcc, s0, v9
	s_and_saveexec_b64 s[16:17], vcc
	s_cbranch_execz .LBB0_1308
	v_mbcnt_lo_u32_b32 v3, vcc_lo, 0
	v_mbcnt_hi_u32_b32 v3, vcc_hi, v3
	v_add_u32_e32 v3, s1, v3
	v_lshl_add_u32 v4, v3, 2, s67
	v_lshl_add_u32 v3, v3, 1, s80
	ds_write_b32 v4, v9
	s_waitcnt lgkmcnt(1)
	ds_write_b16 v3, v2
.LBB0_1308:
	s_or_b64 exec, exec, s[16:17]
	s_waitcnt lgkmcnt(0)
	v_mov_b32_e32 v2, 0
	s_and_saveexec_b64 s[16:17], s[14:15]
	v_mov_b32_e32 v2, v224
	s_or_b64 exec, exec, s[16:17]
	s_bcnt1_i32_b64 s14, vcc
	s_add_i32 s1, s1, s14
	v_cmp_le_u32_e32 vcc, s0, v8
	s_and_saveexec_b64 s[14:15], vcc
	s_cbranch_execz .LBB0_1312
	v_mbcnt_lo_u32_b32 v3, vcc_lo, 0
	v_mbcnt_hi_u32_b32 v3, vcc_hi, v3
	v_add_u32_e32 v3, s1, v3
	v_lshl_add_u32 v4, v3, 2, s67
	v_lshl_add_u32 v3, v3, 1, s80
	ds_write_b32 v4, v8
	s_waitcnt lgkmcnt(1)
	ds_write_b16 v3, v2
.LBB0_1312:
	s_or_b64 exec, exec, s[14:15]
	s_waitcnt lgkmcnt(0)
	v_mov_b32_e32 v2, 0
	s_and_saveexec_b64 s[14:15], s[12:13]
	v_mov_b32_e32 v2, v225
	s_or_b64 exec, exec, s[14:15]
	s_bcnt1_i32_b64 s12, vcc
	s_add_i32 s1, s1, s12
	v_cmp_le_u32_e32 vcc, s0, v7
	s_and_saveexec_b64 s[12:13], vcc
	s_cbranch_execz .LBB0_1316
	v_mbcnt_lo_u32_b32 v3, vcc_lo, 0
	v_mbcnt_hi_u32_b32 v3, vcc_hi, v3
	v_add_u32_e32 v3, s1, v3
	v_lshl_add_u32 v4, v3, 2, s67
	v_lshl_add_u32 v3, v3, 1, s80
	ds_write_b32 v4, v7
	s_waitcnt lgkmcnt(1)
	ds_write_b16 v3, v2
.LBB0_1316:
	s_or_b64 exec, exec, s[12:13]
	s_waitcnt lgkmcnt(0)
	v_mov_b32_e32 v2, 0
	s_and_saveexec_b64 s[12:13], s[10:11]
	v_mov_b32_e32 v2, v226
	s_or_b64 exec, exec, s[12:13]
	s_bcnt1_i32_b64 s10, vcc
	s_add_i32 s1, s1, s10
	v_cmp_le_u32_e32 vcc, s0, v6
	s_and_saveexec_b64 s[10:11], vcc
	s_cbranch_execz .LBB0_1320
	v_mbcnt_lo_u32_b32 v3, vcc_lo, 0
	v_mbcnt_hi_u32_b32 v3, vcc_hi, v3
	v_add_u32_e32 v3, s1, v3
	v_lshl_add_u32 v4, v3, 2, s67
	v_lshl_add_u32 v3, v3, 1, s80
	ds_write_b32 v4, v6
	s_waitcnt lgkmcnt(1)
	ds_write_b16 v3, v2

; #define LAS __attribute__((address_space(3)))
; #define LDS_WAIT() asm volatile("s_waitcnt lgkmcnt(0)" ::: "memory")
; template <bool FINAL>
; __device__ __forceinline__ void dsa_prune(LAS unsigned* cs, LAS unsigned short* ci, LAS unsigned* cnt, LAS float* thr, int q, int lane) {
;     const int n = __builtin_amdgcn_readfirstlane((int)cnt[q]);
;     if (n <= 256) return;
;     LAS unsigned* c = cs + q * CAP; LAS unsigned short* ix = ci + q * CAP;
;     constexpr int NE = CAP / 64;
;     unsigned x[NE];
; #pragma unroll
;     for (int i = 0; i < NE; ++i) { const int e = i * 64 + lane; x[i] = e < n ? c[e] : 0u; }
;     unsigned prefix = 0u; int kp = n;
;     ...
; #pragma unroll
;         for (int i = 0; i < NE; ++i) k += __popcll(__ballot(x[i] >= trial));
;         if (k >= 256) { prefix = trial; kp = k; }
;         if (kp == 256 || (!FINAL && bit <= 16 && kp <= 320)) break; }
;     int base = 0;
; #pragma unroll
;     for (int i = 0; i < NE; ++i) { const int e = i * 64 + lane; const unsigned short id = e < n ? ix[e] : (unsigned short)0;
;         const bool keep = x[i] >= prefix; const unsigned long long mask = __ballot(keep);
;         const int pos = base + (int)__builtin_amdgcn_mbcnt_hi((unsigned)(mask >> 32), __builtin_amdgcn_mbcnt_lo((unsigned)mask, 0u));
;         LDS_WAIT();
;         if (keep) { c[pos] = x[i]; ix[pos] = id; }
;         base += __popcll(mask); }
;     if (lane == 0) { cnt[q] = (unsigned)base; thr[q] = ord2f(prefix); }
.LBB0_1323:
	s_waitcnt lgkmcnt(0)
	v_mov_b32_e32 v2, s59
	ds_read_b32 v2, v2
	s_waitcnt lgkmcnt(0)
	v_readfirstlane_b32 s1, v2
	s_cmpk_lt_i32 s1, 0x101
	s_cbranch_scc1 .LBB0_1427
	ds_read2st64_b32 v[4:5], v90 offset1:1
	ds_read2st64_b32 v[2:3], v90 offset0:2 offset1:3
	v_cmp_gt_u32_e64 s[40:41], s1, v106
	v_mov_b32_e32 v19, 0
	v_mov_b32_e32 v20, 0
	s_and_saveexec_b64 s[10:11], s[40:41]
	ds_read_b32 v20, v90 offset:1024
	s_or_b64 exec, exec, s[10:11]
	v_cmp_gt_u32_e64 s[38:39], s1, v105
	s_and_saveexec_b64 s[10:11], s[38:39]
	ds_read_b32 v19, v90 offset:1280
	s_or_b64 exec, exec, s[10:11]
	v_cmp_gt_u32_e64 s[36:37], s1, v104
	v_mov_b32_e32 v17, 0
	v_mov_b32_e32 v18, 0
	s_and_saveexec_b64 s[10:11], s[36:37]
	ds_read_b32 v18, v90 offset:1536
	s_or_b64 exec, exec, s[10:11]
	v_cmp_gt_u32_e64 s[34:35], s1, v103
	s_and_saveexec_b64 s[10:11], s[34:35]
	ds_read_b32 v17, v90 offset:1792
	s_or_b64 exec, exec, s[10:11]
	v_cmp_gt_u32_e64 s[30:31], s1, v102
	v_mov_b32_e32 v15, 0
	v_mov_b32_e32 v16, 0
	s_and_saveexec_b64 s[10:11], s[30:31]
	ds_read_b32 v16, v90 offset:2048
	s_or_b64 exec, exec, s[10:11]
	v_cmp_gt_u32_e64 s[28:29], s1, v101
	s_and_saveexec_b64 s[10:11], s[28:29]
	ds_read_b32 v15, v90 offset:2304
	s_or_b64 exec, exec, s[10:11]
	v_cmp_gt_u32_e64 s[26:27], s1, v100
	v_mov_b32_e32 v13, 0
	v_mov_b32_e32 v14, 0
	s_and_saveexec_b64 s[10:11], s[26:27]
	ds_read_b32 v14, v90 offset:2560
	s_or_b64 exec, exec, s[10:11]
	v_cmp_gt_u32_e64 s[24:25], s1, v99
	s_and_saveexec_b64 s[10:11], s[24:25]
	ds_read_b32 v13, v90 offset:2816
	s_or_b64 exec, exec, s[10:11]
	v_cmp_gt_u32_e64 s[22:23], s1, v98
	v_mov_b32_e32 v11, 0
	v_mov_b32_e32 v12, 0
	s_and_saveexec_b64 s[10:11], s[22:23]
	ds_read_b32 v12, v90 offset:3072
	s_or_b64 exec, exec, s[10:11]
	v_cmp_gt_u32_e64 s[20:21], s1, v97
	s_and_saveexec_b64 s[10:11], s[20:21]
	ds_read_b32 v11, v90 offset:3328
	s_or_b64 exec, exec, s[10:11]
	v_cmp_gt_u32_e64 s[18:19], s1, v96
	v_mov_b32_e32 v9, 0
	v_mov_b32_e32 v10, 0
	s_and_saveexec_b64 s[10:11], s[18:19]
	ds_read_b32 v10, v90 offset:3584
	s_or_b64 exec, exec, s[10:11]
	v_cmp_gt_u32_e64 s[16:17], s1, v93
	s_and_saveexec_b64 s[10:11], s[16:17]
	ds_read_b32 v9, v90 offset:3840
	s_or_b64 exec, exec, s[10:11]
	v_cmp_gt_u32_e64 s[14:15], s1, v92
	v_mov_b32_e32 v7, 0
	v_mov_b32_e32 v8, 0
	s_and_saveexec_b64 s[10:11], s[14:15]
	ds_read_b32 v8, v90 offset:4096
	s_or_b64 exec, exec, s[10:11]
	v_cmp_gt_u32_e64 s[12:13], s1, v91
	s_and_saveexec_b64 s[10:11], s[12:13]
	ds_read_b32 v7, v90 offset:4352
	s_or_b64 exec, exec, s[10:11]
	v_cmp_gt_u32_e64 s[10:11], s1, v89
	v_mov_b32_e32 v6, 0
	s_and_saveexec_b64 s[42:43], s[10:11]
	ds_read_b32 v6, v90 offset:4608
	s_or_b64 exec, exec, s[42:43]
	s_mov_b32 s99, s1
	s_mov_b32 s66, 31
	s_mov_b32 s0, 0
.LBB0_1355:
	s_lshl_b32 s42, 1, s66
	s_or_b32 s42, s42, s0
	s_waitcnt lgkmcnt(0)
	v_cmp_le_u32_e32 vcc, s42, v4
	s_bcnt1_i32_b64 s43, vcc
	v_cmp_le_u32_e32 vcc, s42, v5
	s_bcnt1_i32_b64 s32, vcc
	s_add_i32 s43, s43, s32
	v_cmp_le_u32_e32 vcc, s42, v2
	s_bcnt1_i32_b64 s32, vcc
	s_add_i32 s43, s43, s32
	v_cmp_le_u32_e32 vcc, s42, v3
	s_bcnt1_i32_b64 s32, vcc
	s_add_i32 s43, s43, s32
	v_cmp_le_u32_e32 vcc, s42, v20
	s_bcnt1_i32_b64 s32, vcc
	s_add_i32 s43, s43, s32
	s_cmpk_le_u32 s99, 320
	s_cbranch_scc1 .Lps_done_d
	v_cmp_le_u32_e32 vcc, s42, v19
	s_bcnt1_i32_b64 s32, vcc
	s_add_i32 s43, s43, s32
	v_cmp_le_u32_e32 vcc, s42, v18
	s_bcnt1_i32_b64 s32, vcc
	s_add_i32 s43, s43, s32
	v_cmp_le_u32_e32 vcc, s42, v17
	s_bcnt1_i32_b64 s32, vcc
	s_add_i32 s43, s43, s32
	s_cmpk_le_u32 s99, 512
	s_cbranch_scc1 .Lps_done_d
	v_cmp_le_u32_e32 vcc, s42, v16
	s_bcnt1_i32_b64 s32, vcc
	s_add_i32 s43, s43, s32
	v_cmp_le_u32_e32 vcc, s42, v15
	s_bcnt1_i32_b64 s32, vcc
	s_add_i32 s43, s43, s32
	v_cmp_le_u32_e32 vcc, s42, v14
	s_bcnt1_i32_b64 s32, vcc
	s_add_i32 s43, s43, s32
	v_cmp_le_u32_e32 vcc, s42, v13
	s_bcnt1_i32_b64 s32, vcc
	s_add_i32 s43, s43, s32
	s_cmpk_le_u32 s99, 768
	s_cbranch_scc1 .Lps_done_d
	v_cmp_le_u32_e32 vcc, s42, v12
	s_bcnt1_i32_b64 s32, vcc
	s_add_i32 s43, s43, s32
	v_cmp_le_u32_e32 vcc, s42, v11
	s_bcnt1_i32_b64 s32, vcc
	s_add_i32 s43, s43, s32
	v_cmp_le_u32_e32 vcc, s42, v10
	s_bcnt1_i32_b64 s32, vcc
	s_add_i32 s43, s43, s32
	s_cmpk_le_u32 s99, 960
	s_cbranch_scc1 .Lps_done_d
	v_cmp_le_u32_e32 vcc, s42, v9
	s_bcnt1_i32_b64 s32, vcc
	s_add_i32 s43, s43, s32
	v_cmp_le_u32_e32 vcc, s42, v8
	s_bcnt1_i32_b64 s32, vcc
	s_add_i32 s43, s43, s32
	v_cmp_le_u32_e32 vcc, s42, v7
	s_bcnt1_i32_b64 s32, vcc
	s_add_i32 s43, s43, s32
	v_cmp_le_u32_e32 vcc, s42, v6
	s_bcnt1_i32_b64 s32, vcc
	s_add_i32 s43, s43, s32
.Lps_done_d:
	s_cmpk_gt_u32 s43, 0xff
	s_cselect_b32 s1, s43, s1
	s_cselect_b32 s0, s42, s0
	s_cmpk_eq_i32 s1, 0x100
	s_cselect_b64 s[42:43], -1, 0
	v_sub_co_u32_e64 v21, s[90:91], s66, 1
	s_or_b64 s[42:43], s[42:43], s[90:91]
	v_readfirstlane_b32 s66, v21
	s_andn2_b64 vcc, exec, s[42:43]
	s_cbranch_vccnz .LBB0_1355
	ds_read_u16 v208, v85
	ds_read_u16 v209, v85 offset:128
	ds_read_u16 v210, v85 offset:256
	ds_read_u16 v211, v85 offset:384
	ds_read_u16 v212, v85 offset:512
	ds_read_u16 v213, v85 offset:640
	ds_read_u16 v214, v85 offset:768
	ds_read_u16 v215, v85 offset:896
	ds_read_u16 v216, v85 offset:1024
	ds_read_u16 v217, v85 offset:1152
	ds_read_u16 v218, v85 offset:1280
	ds_read_u16 v219, v85 offset:1408
	ds_read_u16 v220, v85 offset:1536
	ds_read_u16 v221, v85 offset:1664
	ds_read_u16 v222, v85 offset:1792
	ds_read_u16 v223, v85 offset:1920
	ds_read_u16 v224, v85 offset:2048
	ds_read_u16 v225, v85 offset:2176
	ds_read_u16 v226, v85 offset:2304
	s_waitcnt lgkmcnt(0)
	v_mov_b32_e32 v21, v208
	v_cmp_le_u32_e32 vcc, s0, v4
	s_and_saveexec_b64 s[42:43], vcc
	s_cbranch_execz .LBB0_1358
	v_mbcnt_lo_u32_b32 v22, vcc_lo, 0
	v_mbcnt_hi_u32_b32 v22, vcc_hi, v22
	v_lshl_add_u32 v23, v22, 2, s89
	ds_write_b32 v23, v4
	v_lshl_add_u32 v4, v22, 1, s95
	s_waitcnt lgkmcnt(1)
	ds_write_b16 v4, v21
; #define LDS_WAIT() asm volatile("s_waitcnt lgkmcnt(0)" ::: "memory")
; template <bool FINAL>
; __device__ __forceinline__ void dsa_prune(LAS unsigned* cs, LAS unsigned short* ci, LAS unsigned* cnt, LAS float* thr, int q, int lane) {
;     ...
;     int base = 0;
; #pragma unroll
;     for (int i = 0; i < NE; ++i) { const int e = i * 64 + lane; const unsigned short id = e < n ? ix[e] : (unsigned short)0;
;         const bool keep = x[i] >= prefix; const unsigned long long mask = __ballot(keep);
;         const int pos = base + (int)__builtin_amdgcn_mbcnt_hi((unsigned)(mask >> 32), __builtin_amdgcn_mbcnt_lo((unsigned)mask, 0u));
;         LDS_WAIT();
;         if (keep) { c[pos] = x[i]; ix[pos] = id; }
;         base += __popcll(mask); }
.LBB0_1358:
	s_or_b64 exec, exec, s[42:43]
	v_mov_b32_e32 v4, v209
	s_bcnt1_i32_b64 s1, vcc
	v_cmp_le_u32_e32 vcc, s0, v5
	s_and_saveexec_b64 s[42:43], vcc
	s_cbranch_execz .LBB0_1360
	s_waitcnt lgkmcnt(1)
	v_mbcnt_lo_u32_b32 v21, vcc_lo, 0
	v_mbcnt_hi_u32_b32 v21, vcc_hi, v21
	v_add_u32_e32 v21, s1, v21
	v_lshl_add_u32 v22, v21, 2, s89
	ds_write_b32 v22, v5
	v_lshl_add_u32 v5, v21, 1, s95
	s_waitcnt lgkmcnt(1)
	ds_write_b16 v5, v4
.LBB0_1360:
	s_or_b64 exec, exec, s[42:43]
	s_waitcnt lgkmcnt(0)
	v_mov_b32_e32 v4, v210
	s_bcnt1_i32_b64 s42, vcc
	s_add_i32 s1, s42, s1
	v_cmp_le_u32_e32 vcc, s0, v2
	s_and_saveexec_b64 s[42:43], vcc
	s_cbranch_execz .LBB0_1362
	v_mbcnt_lo_u32_b32 v5, vcc_lo, 0
	v_mbcnt_hi_u32_b32 v5, vcc_hi, v5
	v_add_u32_e32 v5, s1, v5
	v_lshl_add_u32 v21, v5, 2, s89
	ds_write_b32 v21, v2
	v_lshl_add_u32 v2, v5, 1, s95
	s_waitcnt lgkmcnt(1)
	ds_write_b16 v2, v4
.LBB0_1362:
	s_or_b64 exec, exec, s[42:43]
	v_mov_b32_e32 v2, v211
	s_bcnt1_i32_b64 s42, vcc
	s_add_i32 s1, s1, s42
	v_cmp_le_u32_e32 vcc, s0, v3
	s_and_saveexec_b64 s[42:43], vcc
	s_cbranch_execz .LBB0_1364
	s_waitcnt lgkmcnt(1)
	v_mbcnt_lo_u32_b32 v4, vcc_lo, 0
	v_mbcnt_hi_u32_b32 v4, vcc_hi, v4
	v_add_u32_e32 v4, s1, v4
	v_lshl_add_u32 v5, v4, 2, s89
	ds_write_b32 v5, v3
	v_lshl_add_u32 v3, v4, 1, s95
	s_waitcnt lgkmcnt(1)
	ds_write_b16 v3, v2
.LBB0_1364:
	s_or_b64 exec, exec, s[42:43]
	s_waitcnt lgkmcnt(0)
	v_mov_b32_e32 v2, 0
	s_and_saveexec_b64 s[42:43], s[40:41]
	v_mov_b32_e32 v2, v212
	s_or_b64 exec, exec, s[42:43]
	s_bcnt1_i32_b64 s40, vcc
	s_add_i32 s1, s1, s40
	v_cmp_le_u32_e32 vcc, s0, v20
	s_and_saveexec_b64 s[40:41], vcc
	s_cbranch_execz .LBB0_1368
	v_mbcnt_lo_u32_b32 v3, vcc_lo, 0
	v_mbcnt_hi_u32_b32 v3, vcc_hi, v3
	v_add_u32_e32 v3, s1, v3
	v_lshl_add_u32 v4, v3, 2, s89
	v_lshl_add_u32 v3, v3, 1, s95
	ds_write_b32 v4, v20
	s_waitcnt lgkmcnt(1)
	ds_write_b16 v3, v2
.LBB0_1368:
	s_or_b64 exec, exec, s[40:41]
	s_waitcnt lgkmcnt(0)
	v_mov_b32_e32 v2, 0
	s_and_saveexec_b64 s[40:41], s[38:39]
	v_mov_b32_e32 v2, v213
	s_or_b64 exec, exec, s[40:41]
	s_bcnt1_i32_b64 s38, vcc
	s_add_i32 s1, s1, s38
	v_cmp_le_u32_e32 vcc, s0, v19
	s_and_saveexec_b64 s[38:39], vcc
	s_cbranch_execz .LBB0_1372
	v_mbcnt_lo_u32_b32 v3, vcc_lo, 0
	v_mbcnt_hi_u32_b32 v3, vcc_hi, v3
	v_add_u32_e32 v3, s1, v3
	v_lshl_add_u32 v4, v3, 2, s89
	v_lshl_add_u32 v3, v3, 1, s95
	ds_write_b32 v4, v19
	s_waitcnt lgkmcnt(1)
	ds_write_b16 v3, v2
.LBB0_1372:
	s_or_b64 exec, exec, s[38:39]
	s_waitcnt lgkmcnt(0)
	v_mov_b32_e32 v2, 0
	s_and_saveexec_b64 s[38:39], s[36:37]
	v_mov_b32_e32 v2, v214
	s_or_b64 exec, exec, s[38:39]
	s_bcnt1_i32_b64 s36, vcc
	s_add_i32 s1, s1, s36
	v_cmp_le_u32_e32 vcc, s0, v18
	s_and_saveexec_b64 s[36:37], vcc
	s_cbranch_execz .LBB0_1376
	v_mbcnt_lo_u32_b32 v3, vcc_lo, 0
	v_mbcnt_hi_u32_b32 v3, vcc_hi, v3
	v_add_u32_e32 v3, s1, v3
	v_lshl_add_u32 v4, v3, 2, s89
	v_lshl_add_u32 v3, v3, 1, s95
	ds_write_b32 v4, v18
	s_waitcnt lgkmcnt(1)
	ds_write_b16 v3, v2
.LBB0_1376:
	s_or_b64 exec, exec, s[36:37]
	s_waitcnt lgkmcnt(0)
	v_mov_b32_e32 v2, 0
	s_and_saveexec_b64 s[36:37], s[34:35]
	v_mov_b32_e32 v2, v215
	s_or_b64 exec, exec, s[36:37]
	s_bcnt1_i32_b64 s34, vcc
	s_add_i32 s1, s1, s34
	v_cmp_le_u32_e32 vcc, s0, v17
	s_and_saveexec_b64 s[34:35], vcc
	s_cbranch_execz .LBB0_1380
	v_mbcnt_lo_u32_b32 v3, vcc_lo, 0
	v_mbcnt_hi_u32_b32 v3, vcc_hi, v3
	v_add_u32_e32 v3, s1, v3
	v_lshl_add_u32 v4, v3, 2, s89
	v_lshl_add_u32 v3, v3, 1, s95
	ds_write_b32 v4, v17
	s_waitcnt lgkmcnt(1)
	ds_write_b16 v3, v2
.LBB0_1380:
	s_or_b64 exec, exec, s[34:35]
	s_waitcnt lgkmcnt(0)
	v_mov_b32_e32 v2, 0
	s_and_saveexec_b64 s[34:35], s[30:31]
	v_mov_b32_e32 v2, v216
	s_or_b64 exec, exec, s[34:35]
	s_bcnt1_i32_b64 s30, vcc
	s_add_i32 s1, s1, s30
	v_cmp_le_u32_e32 vcc, s0, v16
	s_and_saveexec_b64 s[30:31], vcc
	s_cbranch_execz .LBB0_1384
	v_mbcnt_lo_u32_b32 v3, vcc_lo, 0
	v_mbcnt_hi_u32_b32 v3, vcc_hi, v3
	v_add_u32_e32 v3, s1, v3
	v_lshl_add_u32 v4, v3, 2, s89
	v_lshl_add_u32 v3, v3, 1, s95
	ds_write_b32 v4, v16
	s_waitcnt lgkmcnt(1)
	ds_write_b16 v3, v2
.LBB0_1384:
	s_or_b64 exec, exec, s[30:31]
	s_waitcnt lgkmcnt(0)
	v_mov_b32_e32 v2, 0
	s_and_saveexec_b64 s[30:31], s[28:29]
	v_mov_b32_e32 v2, v217
	s_or_b64 exec, exec, s[30:31]
	s_bcnt1_i32_b64 s28, vcc
	s_add_i32 s1, s1, s28
	v_cmp_le_u32_e32 vcc, s0, v15
	s_and_saveexec_b64 s[28:29], vcc
	s_cbranch_execz .LBB0_1388
	v_mbcnt_lo_u32_b32 v3, vcc_lo, 0
	v_mbcnt_hi_u32_b32 v3, vcc_hi, v3
	v_add_u32_e32 v3, s1, v3
	v_lshl_add_u32 v4, v3, 2, s89
	v_lshl_add_u32 v3, v3, 1, s95
	ds_write_b32 v4, v15
	s_waitcnt lgkmcnt(1)
	ds_write_b16 v3, v2
; #define LDS_WAIT() asm volatile("s_waitcnt lgkmcnt(0)" ::: "memory")
; template <bool FINAL>
; __device__ __forceinline__ void dsa_prune(LAS unsigned* cs, LAS unsigned short* ci, LAS unsigned* cnt, LAS float* thr, int q, int lane) {
;     ...
;     int base = 0;
; #pragma unroll
;     for (int i = 0; i < NE; ++i) { const int e = i * 64 + lane; const unsigned short id = e < n ? ix[e] : (unsigned short)0;
;         const bool keep = x[i] >= prefix; const unsigned long long mask = __ballot(keep);
;         const int pos = base + (int)__builtin_amdgcn_mbcnt_hi((unsigned)(mask >> 32), __builtin_amdgcn_mbcnt_lo((unsigned)mask, 0u));
;         LDS_WAIT();
;         if (keep) { c[pos] = x[i]; ix[pos] = id; }
;         base += __popcll(mask); }
.LBB0_1388:
	s_or_b64 exec, exec, s[28:29]
	s_waitcnt lgkmcnt(0)
	v_mov_b32_e32 v2, 0
	s_and_saveexec_b64 s[28:29], s[26:27]
	v_mov_b32_e32 v2, v218
	s_or_b64 exec, exec, s[28:29]
	s_bcnt1_i32_b64 s26, vcc
	s_add_i32 s1, s1, s26
	v_cmp_le_u32_e32 vcc, s0, v14
	s_and_saveexec_b64 s[26:27], vcc
	s_cbranch_execz .LBB0_1392
	v_mbcnt_lo_u32_b32 v3, vcc_lo, 0
	v_mbcnt_hi_u32_b32 v3, vcc_hi, v3
	v_add_u32_e32 v3, s1, v3
	v_lshl_add_u32 v4, v3, 2, s89
	v_lshl_add_u32 v3, v3, 1, s95
	ds_write_b32 v4, v14
	s_waitcnt lgkmcnt(1)
	ds_write_b16 v3, v2
.LBB0_1392:
	s_or_b64 exec, exec, s[26:27]
	s_waitcnt lgkmcnt(0)
	v_mov_b32_e32 v2, 0
	s_and_saveexec_b64 s[26:27], s[24:25]
	v_mov_b32_e32 v2, v219
	s_or_b64 exec, exec, s[26:27]
	s_bcnt1_i32_b64 s24, vcc
	s_add_i32 s1, s1, s24
	v_cmp_le_u32_e32 vcc, s0, v13
	s_and_saveexec_b64 s[24:25], vcc
	s_cbranch_execz .LBB0_1396
	v_mbcnt_lo_u32_b32 v3, vcc_lo, 0
	v_mbcnt_hi_u32_b32 v3, vcc_hi, v3
	v_add_u32_e32 v3, s1, v3
	v_lshl_add_u32 v4, v3, 2, s89
	v_lshl_add_u32 v3, v3, 1, s95
	ds_write_b32 v4, v13
	s_waitcnt lgkmcnt(1)
	ds_write_b16 v3, v2
.LBB0_1396:
	s_or_b64 exec, exec, s[24:25]
	s_waitcnt lgkmcnt(0)
	v_mov_b32_e32 v2, 0
	s_and_saveexec_b64 s[24:25], s[22:23]
	v_mov_b32_e32 v2, v220
	s_or_b64 exec, exec, s[24:25]
	s_bcnt1_i32_b64 s22, vcc
	s_add_i32 s1, s1, s22
	v_cmp_le_u32_e32 vcc, s0, v12
	s_and_saveexec_b64 s[22:23], vcc
	s_cbranch_execz .LBB0_1400
	v_mbcnt_lo_u32_b32 v3, vcc_lo, 0
	v_mbcnt_hi_u32_b32 v3, vcc_hi, v3
	v_add_u32_e32 v3, s1, v3
	v_lshl_add_u32 v4, v3, 2, s89
	v_lshl_add_u32 v3, v3, 1, s95
	ds_write_b32 v4, v12
	s_waitcnt lgkmcnt(1)
	ds_write_b16 v3, v2
.LBB0_1400:
	s_or_b64 exec, exec, s[22:23]
	s_waitcnt lgkmcnt(0)
	v_mov_b32_e32 v2, 0
	s_and_saveexec_b64 s[22:23], s[20:21]
	v_mov_b32_e32 v2, v221
	s_or_b64 exec, exec, s[22:23]
	s_bcnt1_i32_b64 s20, vcc
	s_add_i32 s1, s1, s20
	v_cmp_le_u32_e32 vcc, s0, v11
	s_and_saveexec_b64 s[20:21], vcc
	s_cbranch_execz .LBB0_1404
	v_mbcnt_lo_u32_b32 v3, vcc_lo, 0
	v_mbcnt_hi_u32_b32 v3, vcc_hi, v3
	v_add_u32_e32 v3, s1, v3
	v_lshl_add_u32 v4, v3, 2, s89
	v_lshl_add_u32 v3, v3, 1, s95
	ds_write_b32 v4, v11
	s_waitcnt lgkmcnt(1)
	ds_write_b16 v3, v2
.LBB0_1404:
	s_or_b64 exec, exec, s[20:21]
	s_waitcnt lgkmcnt(0)
	v_mov_b32_e32 v2, 0
	s_and_saveexec_b64 s[20:21], s[18:19]
	v_mov_b32_e32 v2, v222
	s_or_b64 exec, exec, s[20:21]
	s_bcnt1_i32_b64 s18, vcc
	s_add_i32 s1, s1, s18
	v_cmp_le_u32_e32 vcc, s0, v10
	s_and_saveexec_b64 s[18:19], vcc
	s_cbranch_execz .LBB0_1408
	v_mbcnt_lo_u32_b32 v3, vcc_lo, 0
	v_mbcnt_hi_u32_b32 v3, vcc_hi, v3
	v_add_u32_e32 v3, s1, v3
	v_lshl_add_u32 v4, v3, 2, s89
	v_lshl_add_u32 v3, v3, 1, s95
	ds_write_b32 v4, v10
	s_waitcnt lgkmcnt(1)
	ds_write_b16 v3, v2
.LBB0_1408:
	s_or_b64 exec, exec, s[18:19]
	s_waitcnt lgkmcnt(0)
	v_mov_b32_e32 v2, 0
	s_and_saveexec_b64 s[18:19], s[16:17]
	v_mov_b32_e32 v2, v223
	s_or_b64 exec, exec, s[18:19]
	s_bcnt1_i32_b64 s16, vcc
	s_add_i32 s1, s1, s16
	v_cmp_le_u32_e32 vcc, s0, v9
	s_and_saveexec_b64 s[16:17], vcc
	s_cbranch_execz .LBB0_1412
	v_mbcnt_lo_u32_b32 v3, vcc_lo, 0
	v_mbcnt_hi_u32_b32 v3, vcc_hi, v3
	v_add_u32_e32 v3, s1, v3
	v_lshl_add_u32 v4, v3, 2, s89
	v_lshl_add_u32 v3, v3, 1, s95
	ds_write_b32 v4, v9
	s_waitcnt lgkmcnt(1)
	ds_write_b16 v3, v2
.LBB0_1412:
	s_or_b64 exec, exec, s[16:17]
	s_waitcnt lgkmcnt(0)
	v_mov_b32_e32 v2, 0
	s_and_saveexec_b64 s[16:17], s[14:15]
	v_mov_b32_e32 v2, v224
	s_or_b64 exec, exec, s[16:17]
	s_bcnt1_i32_b64 s14, vcc
	s_add_i32 s1, s1, s14
	v_cmp_le_u32_e32 vcc, s0, v8
	s_and_saveexec_b64 s[14:15], vcc
	s_cbranch_execz .LBB0_1416
	v_mbcnt_lo_u32_b32 v3, vcc_lo, 0
	v_mbcnt_hi_u32_b32 v3, vcc_hi, v3
	v_add_u32_e32 v3, s1, v3
	v_lshl_add_u32 v4, v3, 2, s89
	v_lshl_add_u32 v3, v3, 1, s95
	ds_write_b32 v4, v8
	s_waitcnt lgkmcnt(1)
	ds_write_b16 v3, v2
.LBB0_1416:
	s_or_b64 exec, exec, s[14:15]
	s_waitcnt lgkmcnt(0)
	v_mov_b32_e32 v2, 0
	s_and_saveexec_b64 s[14:15], s[12:13]
	v_mov_b32_e32 v2, v225
	s_or_b64 exec, exec, s[14:15]
	s_bcnt1_i32_b64 s12, vcc
	s_add_i32 s1, s1, s12
	v_cmp_le_u32_e32 vcc, s0, v7
	s_and_saveexec_b64 s[12:13], vcc
	s_cbranch_execz .LBB0_1420
	v_mbcnt_lo_u32_b32 v3, vcc_lo, 0
	v_mbcnt_hi_u32_b32 v3, vcc_hi, v3
	v_add_u32_e32 v3, s1, v3
	v_lshl_add_u32 v4, v3, 2, s89
	v_lshl_add_u32 v3, v3, 1, s95
	ds_write_b32 v4, v7
	s_waitcnt lgkmcnt(1)
	ds_write_b16 v3, v2
.LBB0_1420:
	s_or_b64 exec, exec, s[12:13]
	s_waitcnt lgkmcnt(0)
	v_mov_b32_e32 v2, 0
	s_and_saveexec_b64 s[12:13], s[10:11]
	v_mov_b32_e32 v2, v226
	s_or_b64 exec, exec, s[12:13]
	s_bcnt1_i32_b64 s10, vcc
	s_add_i32 s1, s1, s10
	v_cmp_le_u32_e32 vcc, s0, v6
	s_and_saveexec_b64 s[10:11], vcc
	s_cbranch_execz .LBB0_1424
	v_mbcnt_lo_u32_b32 v3, vcc_lo, 0
	v_mbcnt_hi_u32_b32 v3, vcc_hi, v3
	v_add_u32_e32 v3, s1, v3
	v_lshl_add_u32 v4, v3, 2, s89
	v_lshl_add_u32 v3, v3, 1, s95
	ds_write_b32 v4, v6
	s_waitcnt lgkmcnt(1)
	ds_write_b16 v3, v2

; #define LAS __attribute__((address_space(3)))
; __device__ __forceinline__ void dsa_unit(int wv, const Args& A, LAS unsigned char* lds, int s, int qt) {
;     ...
;     for (int qi2 = 0; qi2 < 2; ++qi2) {
;         const int qq = 2 * w + qi2; int n = __builtin_amdgcn_readfirstlane((int)cnt[qq]); n = n > 256 ? 256 : n;
;         const size_t qrow = qrow0 + qq; const int qpos = qpos0 + qq;
;         LAS const unsigned short* lst = ci + qq * CAP;
;         long qf[8];
; #pragma unroll
;         for (int kk = 0; kk < 8; ++kk) { qf[kk] = 0;
;             if (fr < 8 && (fr >> 2) == (kk >> 2)) { const h16x8 q = __builtin_bit_cast(h16x8, *(const u32x4*)(PROJ + qrow * PW + C_Q + fr * 128 + ((kk >> 1) & 1) * 64 + fq * 16 + (kk & 1) * 8));
;                 f32x4 a, bq;
; #pragma unroll
;                 for (int e = 0; e < 4; ++e) { a[e] = 16.f * (float)q[e]; bq[e] = 16.f * (float)q[4 + e]; }
;                 qf[kk] = __builtin_bit_cast(long, pack_fp8x8(a, bq)); } }
;         const int nt = n >> 4;
;         long kf[8];
;     ...
;         DSA_LOADT(kf, 0);
;         for (int kt = 0; kt < nt; ++kt) {
;             long k1[8];
;             DSA_LOADT(k1, kt + 1);
.LBB0_1429:
	s_or_b32 s1, s0, s94
	s_lshl_b32 s12, s1, 2
	s_add_i32 s12, s12, 0
	s_add_i32 s12, s12, 0x1c800
	v_mov_b32_e32 v0, s12
	ds_read_b32 v0, v0
	s_ashr_i32 s12, s1, 31
	s_add_u32 s22, s1, s5
	s_addc_u32 s23, s12, 0
	s_mul_i32 s14, s23, 0x2e00
	v_mad_u64_u32 v[2:3], s[12:13], s22, v157, v[22:23]
	s_waitcnt lgkmcnt(0)
	v_readfirstlane_b32 s30, v0
	v_add_u32_e32 v3, s14, v3
	v_mov_b64_e32 v[32:33], 0
	v_mov_b64_e32 v[34:35], 0
	v_mov_b64_e32 v[36:37], 0
	v_mov_b64_e32 v[38:39], 0
	v_mov_b64_e32 v[40:41], 0
	v_mov_b64_e32 v[42:43], 0
	v_mov_b64_e32 v[44:45], 0
	v_mov_b64_e32 v[46:47], 0
	s_or_b64 s[14:15], s[10:11], s[20:21]
	s_and_saveexec_b64 s[12:13], s[14:15]
	global_load_dwordx4 v[56:59], v[2:3], off
	global_load_dwordx4 v[60:63], v[2:3], off offset:16
	global_load_dwordx4 v[64:67], v[2:3], off offset:128
	global_load_dwordx4 v[68:71], v[2:3], off offset:144
	s_waitcnt vmcnt(3)
	v_cvt_f32_f16_e32 v145, v56
	v_cvt_f32_f16_e32 v146, v58
	v_cvt_f32_f16_sdwa v147, v56 dst_sel:DWORD dst_unused:UNUSED_PAD src0_sel:WORD_1
	v_cvt_f32_f16_sdwa v148, v58 dst_sel:DWORD dst_unused:UNUSED_PAD src0_sel:WORD_1
	v_mul_f32_e32 v145, 0x41800000, v145
	v_mul_f32_e32 v146, 0x41800000, v146
	v_mul_f32_e32 v147, 0x41800000, v147
	v_mul_f32_e32 v148, 0x41800000, v148
	v_cvt_f32_f16_e32 v149, v57
	v_cvt_f32_f16_e32 v158, v59
	v_cvt_f32_f16_sdwa v159, v57 dst_sel:DWORD dst_unused:UNUSED_PAD src0_sel:WORD_1
	v_cvt_f32_f16_sdwa v160, v59 dst_sel:DWORD dst_unused:UNUSED_PAD src0_sel:WORD_1
	v_cvt_pk_fp8_f32 v72, v145, v147
	v_cvt_pk_fp8_f32 v73, v146, v148
	v_mul_f32_e32 v149, 0x41800000, v149
	v_mul_f32_e32 v158, 0x41800000, v158
	v_mul_f32_e32 v159, 0x41800000, v159
	v_mul_f32_e32 v160, 0x41800000, v160
	v_cvt_pk_fp8_f32 v72, v149, v159 op_sel:[0,0,1]
	v_cvt_pk_fp8_f32 v73, v158, v160 op_sel:[0,0,1]
	s_waitcnt vmcnt(2)
	v_cvt_f32_f16_e32 v145, v60
	v_cvt_f32_f16_e32 v146, v62
	v_cvt_f32_f16_sdwa v147, v60 dst_sel:DWORD dst_unused:UNUSED_PAD src0_sel:WORD_1
	v_cvt_f32_f16_sdwa v148, v62 dst_sel:DWORD dst_unused:UNUSED_PAD src0_sel:WORD_1
	v_mul_f32_e32 v145, 0x41800000, v145
	v_mul_f32_e32 v146, 0x41800000, v146
	v_mul_f32_e32 v147, 0x41800000, v147
	v_mul_f32_e32 v148, 0x41800000, v148
	v_cvt_f32_f16_e32 v149, v61
	v_cvt_f32_f16_e32 v158, v63
	v_cvt_f32_f16_sdwa v159, v61 dst_sel:DWORD dst_unused:UNUSED_PAD src0_sel:WORD_1
	v_cvt_f32_f16_sdwa v160, v63 dst_sel:DWORD dst_unused:UNUSED_PAD src0_sel:WORD_1
	v_cvt_pk_fp8_f32 v74, v145, v147
	v_cvt_pk_fp8_f32 v75, v146, v148
	v_mul_f32_e32 v149, 0x41800000, v149
	v_mul_f32_e32 v158, 0x41800000, v158
	v_mul_f32_e32 v159, 0x41800000, v159
	v_mul_f32_e32 v160, 0x41800000, v160
	v_cvt_pk_fp8_f32 v74, v149, v159 op_sel:[0,0,1]
	v_cvt_pk_fp8_f32 v75, v158, v160 op_sel:[0,0,1]
	s_waitcnt vmcnt(1)
	v_cvt_f32_f16_e32 v145, v64
	v_cvt_f32_f16_e32 v146, v66
	v_cvt_f32_f16_sdwa v147, v64 dst_sel:DWORD dst_unused:UNUSED_PAD src0_sel:WORD_1
	v_cvt_f32_f16_sdwa v148, v66 dst_sel:DWORD dst_unused:UNUSED_PAD src0_sel:WORD_1
	v_mul_f32_e32 v145, 0x41800000, v145
	v_mul_f32_e32 v146, 0x41800000, v146
	v_mul_f32_e32 v147, 0x41800000, v147
	v_mul_f32_e32 v148, 0x41800000, v148
	v_cvt_f32_f16_e32 v149, v65
	v_cvt_f32_f16_e32 v158, v67
	v_cvt_f32_f16_sdwa v159, v65 dst_sel:DWORD dst_unused:UNUSED_PAD src0_sel:WORD_1
	v_cvt_f32_f16_sdwa v160, v67 dst_sel:DWORD dst_unused:UNUSED_PAD src0_sel:WORD_1
	v_cvt_pk_fp8_f32 v76, v145, v147
	v_cvt_pk_fp8_f32 v77, v146, v148
	v_mul_f32_e32 v149, 0x41800000, v149
	v_mul_f32_e32 v158, 0x41800000, v158
	v_mul_f32_e32 v159, 0x41800000, v159
	v_mul_f32_e32 v160, 0x41800000, v160
	v_cvt_pk_fp8_f32 v76, v149, v159 op_sel:[0,0,1]
	v_cvt_pk_fp8_f32 v77, v158, v160 op_sel:[0,0,1]
	s_waitcnt vmcnt(0)
	v_cvt_f32_f16_e32 v145, v68
	v_cvt_f32_f16_e32 v146, v70
	v_cvt_f32_f16_sdwa v147, v68 dst_sel:DWORD dst_unused:UNUSED_PAD src0_sel:WORD_1
	v_cvt_f32_f16_sdwa v148, v70 dst_sel:DWORD dst_unused:UNUSED_PAD src0_sel:WORD_1
	v_mul_f32_e32 v145, 0x41800000, v145
	v_mul_f32_e32 v146, 0x41800000, v146
	v_mul_f32_e32 v147, 0x41800000, v147
	v_mul_f32_e32 v148, 0x41800000, v148
	v_cvt_f32_f16_e32 v149, v69
	v_cvt_f32_f16_e32 v158, v71
	v_cvt_f32_f16_sdwa v159, v69 dst_sel:DWORD dst_unused:UNUSED_PAD src0_sel:WORD_1
	v_cvt_f32_f16_sdwa v160, v71 dst_sel:DWORD dst_unused:UNUSED_PAD src0_sel:WORD_1
	v_cvt_pk_fp8_f32 v78, v145, v147
	v_cvt_pk_fp8_f32 v79, v146, v148
	v_mul_f32_e32 v149, 0x41800000, v149
	v_mul_f32_e32 v158, 0x41800000, v158
	v_mul_f32_e32 v159, 0x41800000, v159
	v_mul_f32_e32 v160, 0x41800000, v160
	v_cvt_pk_fp8_f32 v78, v149, v159 op_sel:[0,0,1]
	v_cvt_pk_fp8_f32 v79, v158, v160 op_sel:[0,0,1]
	s_nop 0
	v_cndmask_b32_e64 v34, 0, v72, s[10:11]
	v_cndmask_b32_e64 v35, 0, v73, s[10:11]
	v_cndmask_b32_e64 v42, 0, v72, s[20:21]
	v_cndmask_b32_e64 v43, 0, v73, s[20:21]
	v_cndmask_b32_e64 v32, 0, v74, s[10:11]
	v_cndmask_b32_e64 v33, 0, v75, s[10:11]
	v_cndmask_b32_e64 v40, 0, v74, s[20:21]
	v_cndmask_b32_e64 v41, 0, v75, s[20:21]
	v_cndmask_b32_e64 v38, 0, v76, s[10:11]
	v_cndmask_b32_e64 v39, 0, v77, s[10:11]
	v_cndmask_b32_e64 v46, 0, v76, s[20:21]
	v_cndmask_b32_e64 v47, 0, v77, s[20:21]
	v_cndmask_b32_e64 v36, 0, v78, s[10:11]
	v_cndmask_b32_e64 v37, 0, v79, s[10:11]
	v_cndmask_b32_e64 v44, 0, v78, s[20:21]
	v_cndmask_b32_e64 v45, 0, v79, s[20:21]
	s_or_b64 exec, exec, s[12:13]
	s_min_i32 s29, s30, 0x100
	s_ashr_i32 s16, s29, 4
	s_cmp_lt_i32 s16, 1
	s_mulk_i32 s0, 0x980
	s_cbranch_scc1 .LBB0_1458
	s_mul_i32 s12, s1, 0x980
	s_add_i32 s1, s1, s4
	v_lshl_add_u32 v141, v94, 1, s12
	v_add_u32_e32 v141, 0x13000, v141
	ds_read_u16 v107, v141
	ds_read_u16 v108, v141 offset:32
	ds_read_u16 v109, v141 offset:64
	ds_read_u16 v110, v141 offset:96
	ds_read_u16 v111, v141 offset:128
	ds_read_u16 v112, v141 offset:160
	ds_read_u16 v113, v141 offset:192
	ds_read_u16 v114, v141 offset:224
	ds_read_u16 v115, v141 offset:256
	ds_read_u16 v116, v141 offset:288
	ds_read_u16 v117, v141 offset:320
	ds_read_u16 v118, v141 offset:352
	ds_read_u16 v119, v141 offset:384
	ds_read_u16 v120, v141 offset:416
	ds_read_u16 v121, v141 offset:448
	ds_read_u16 v122, v141 offset:480
	v_add_u32_e32 v142, s0, v104
	v_add_u32_e32 v142, 0x13000, v142
	v_add_u32_e32 v143, 0x1cc80, v103
	v_mbcnt_lo_u32_b32 v144, -1, 0
	v_mbcnt_hi_u32_b32 v144, -1, v144
	v_lshrrev_b32_e32 v144, 4, v144
	v_lshlrev_b32_e32 v144, 4, v144
	s_waitcnt lgkmcnt(0)
	v_add_lshl_u32 v107, s48, v107, 8
	v_add_u32_e32 v107, v144, v107
	global_load_dwordx4 v[56:59], v107, s[84:85]
	global_load_dwordx4 v[60:63], v107, s[84:85] offset:64
	global_load_dwordx4 v[64:67], v107, s[84:85] offset:128
	global_load_dwordx4 v[68:71], v107, s[84:85] offset:192
	s_cmp_gt_i32 s16, 1
	s_cbranch_scc0 .Lqk_ni_pre
	v_add_lshl_u32 v108, s48, v108, 8
	v_add_u32_e32 v108, v144, v108
	global_load_dwordx4 v[72:75], v108, s[84:85]
	global_load_dwordx4 v[76:79], v108, s[84:85] offset:64
	global_load_dwordx4 v[80:83], v108, s[84:85] offset:128
	global_load_dwordx4 v[84:87], v108, s[84:85] offset:192
; __device__ __forceinline__ void dsa_unit(int wv, const Args& A, LAS unsigned char* lds, int s, int qt) {
;     ...
;         DSA_LOADT(kf, 0);
;         for (int kt = 0; kt < nt; ++kt) {
;             long k1[8];
;             DSA_LOADT(k1, kt + 1);
.Lqk_ni_pre:
	ds_read_b64 v[92:93], v142
	s_cmp_gt_i32 s16, 2
	s_cbranch_scc0 .Lqk_ni_0
	v_add_lshl_u32 v109, s48, v109, 8
	v_add_u32_e32 v109, v144, v109
	global_load_dwordx4 v[124:127], v109, s[84:85]
	global_load_dwordx4 v[128:131], v109, s[84:85] offset:64
	global_load_dwordx4 v[132:135], v109, s[84:85] offset:128
	global_load_dwordx4 v[136:139], v109, s[84:85] offset:192
	s_waitcnt vmcnt(8)
	s_branch .Lqk_go_0
.Lqk_ni_0:
	s_cmp_gt_i32 s16, 1
	s_cbranch_scc0 .Lqk_nj_0
	s_waitcnt vmcnt(4)
	s_branch .Lqk_go_0

; __device__ __forceinline__ void dsa_unit(int wv, const Args& A, LAS unsigned char* lds, int s, int qt) {
;     ...
;         for (int kt = 0; kt < nt; ++kt) {
;             long k1[8];
;             DSA_LOADT(k1, kt + 1);
;             f32x4 a = {0.f, 0.f, 0.f, 0.f};
; #pragma unroll
;             for (int kk = 0; kk < 8; ++kk) a = __builtin_amdgcn_mfma_f32_16x16x32_fp8_fp8(kf[kk], qf[kk], a, 0, 0, 0);
;             if (fr < 8) {
; #pragma unroll
;                 for (int r = 0; r < 4; ++r) { const int e2 = kt * 16 + fq * 4 + r; const int key2 = lst[e2];
;                     Pw[e2 * 8 + fr] = (h16)(a[r] * 0.0625f + relb[rel_bucket(key2 - qpos) * 8 + fr]); } }
; #pragma unroll
;             for (int kk = 0; kk < 8; ++kk) kf[kk] = k1[kk];
;         }
.Lqk_go_0:
	v_mfma_f32_16x16x32_fp8_fp8 v[88:91], v[56:57], v[34:35], 0
	v_mfma_f32_16x16x32_fp8_fp8 v[88:91], v[58:59], v[32:33], v[88:91]
	v_mfma_f32_16x16x32_fp8_fp8 v[88:91], v[60:61], v[38:39], v[88:91]
	v_mfma_f32_16x16x32_fp8_fp8 v[88:91], v[62:63], v[36:37], v[88:91]
	v_mfma_f32_16x16x32_fp8_fp8 v[88:91], v[64:65], v[42:43], v[88:91]
	v_mfma_f32_16x16x32_fp8_fp8 v[88:91], v[66:67], v[40:41], v[88:91]
	v_mfma_f32_16x16x32_fp8_fp8 v[88:91], v[68:69], v[46:47], v[88:91]
	v_mfma_f32_16x16x32_fp8_fp8 v[88:91], v[70:71], v[44:45], v[88:91]
	s_and_saveexec_b64 s[12:13], s[8:9]
	s_waitcnt lgkmcnt(0)
	v_and_b32_e32 v145, 0xffff, v92
	v_lshrrev_b32_e32 v146, 16, v92
	v_and_b32_e32 v147, 0xffff, v93
	v_lshrrev_b32_e32 v148, 16, v93
	v_subrev_u32_e32 v145, s1, v145
	v_subrev_u32_e32 v146, s1, v146
	v_subrev_u32_e32 v147, s1, v147
	v_subrev_u32_e32 v148, s1, v148
	v_sub_u32_e32 v149, 0, v145
	v_sub_u32_e32 v158, 0, v146
	v_sub_u32_e32 v159, 0, v147
	v_sub_u32_e32 v160, 0, v148
	v_max_i32_e32 v149, v145, v149
	v_max_i32_e32 v158, v146, v158
	v_max_i32_e32 v159, v147, v159
	v_max_i32_e32 v160, v148, v160
	v_mul_u32_u24_e32 v161, v149, v149
	v_mul_u32_u24_e32 v162, v158, v158
	v_mul_u32_u24_e32 v163, v159, v159
	v_mul_u32_u24_e32 v164, v160, v160
	v_cvt_f32_u32_e32 v161, v161
	v_cvt_f32_u32_e32 v162, v162
	v_cvt_f32_u32_e32 v163, v163
	v_cvt_f32_u32_e32 v164, v164
	v_lshrrev_b32_e32 v161, 23, v161
	v_lshrrev_b32_e32 v162, 23, v162
	v_lshrrev_b32_e32 v163, 23, v163
	v_lshrrev_b32_e32 v164, 23, v164
	v_add_u32_e32 v161, 0xffffff83, v161
	v_add_u32_e32 v162, 0xffffff83, v162
	v_add_u32_e32 v163, 0xffffff83, v163
	v_add_u32_e32 v164, 0xffffff83, v164
	v_min_u32_e32 v161, 15, v161
	v_min_u32_e32 v162, 15, v162
	v_min_u32_e32 v163, 15, v163
	v_min_u32_e32 v164, 15, v164
	v_cmp_gt_u32_e32 vcc, 8, v149
	v_cmp_gt_u32_e64 s[26:27], 8, v158
	v_cmp_gt_u32_e64 s[36:37], 8, v159
	v_cmp_gt_u32_e64 s[38:39], 8, v160
	v_med3_i32 v165, v145, 0, 1
	v_med3_i32 v166, v146, 0, 1
	v_med3_i32 v167, v147, 0, 1
	v_med3_i32 v168, v148, 0, 1
	v_cndmask_b32_e64 v161, v161, v149, vcc
	v_cndmask_b32_e64 v162, v162, v158, s[26:27]
	v_cndmask_b32_e64 v163, v163, v159, s[36:37]
	v_cndmask_b32_e64 v164, v164, v160, s[38:39]
	v_lshl_add_u32 v161, v165, 4, v161
	v_lshl_add_u32 v162, v166, 4, v162
	v_lshl_add_u32 v163, v167, 4, v163
	v_lshl_add_u32 v164, v168, 4, v164
	v_lshl_add_u32 v165, v161, 5, v25
	v_lshl_add_u32 v166, v162, 5, v25
	v_lshl_add_u32 v167, v163, 5, v25
	v_lshl_add_u32 v168, v164, 5, v25
	ds_read_b32 v165, v165
	ds_read_b32 v166, v166
	ds_read_b32 v167, v167
	ds_read_b32 v168, v168
	s_waitcnt lgkmcnt(3)
	v_fma_mixlo_f16 v165, v88, s3, v165
	s_waitcnt lgkmcnt(2)
	v_fma_mixlo_f16 v166, v89, s3, v166
	s_waitcnt lgkmcnt(1)
	v_fma_mixlo_f16 v167, v90, s3, v167
	s_waitcnt lgkmcnt(0)
	v_fma_mixlo_f16 v168, v91, s3, v168
	ds_write_b16 v143, v165
	ds_write_b16 v143, v166 offset:16
	ds_write_b16 v143, v167 offset:32
	ds_write_b16 v143, v168 offset:48
	s_mov_b64 exec, s[12:13]
	s_cmp_le_i32 s16, 1
	s_cbranch_scc1 .Lqk_done
	ds_read_b64 v[92:93], v142 offset:32
	s_cmp_gt_i32 s16, 3
	s_cbranch_scc0 .Lqk_ni_1
	v_add_lshl_u32 v110, s48, v110, 8
	v_add_u32_e32 v110, v144, v110
	global_load_dwordx4 v[56:59], v110, s[84:85]
	global_load_dwordx4 v[60:63], v110, s[84:85] offset:64
	global_load_dwordx4 v[64:67], v110, s[84:85] offset:128
	global_load_dwordx4 v[68:71], v110, s[84:85] offset:192
	s_waitcnt vmcnt(8)
	s_branch .Lqk_go_1
.Lqk_ni_1:
	s_cmp_gt_i32 s16, 2
	s_cbranch_scc0 .Lqk_nj_1
	s_waitcnt vmcnt(4)
	s_branch .Lqk_go_1

; __device__ __forceinline__ void dsa_unit(int wv, const Args& A, LAS unsigned char* lds, int s, int qt) {
;     ...
;         for (int kt = 0; kt < nt; ++kt) {
;             long k1[8];
;             DSA_LOADT(k1, kt + 1);
;             f32x4 a = {0.f, 0.f, 0.f, 0.f};
; #pragma unroll
;             for (int kk = 0; kk < 8; ++kk) a = __builtin_amdgcn_mfma_f32_16x16x32_fp8_fp8(kf[kk], qf[kk], a, 0, 0, 0);
;             if (fr < 8) {
; #pragma unroll
;                 for (int r = 0; r < 4; ++r) { const int e2 = kt * 16 + fq * 4 + r; const int key2 = lst[e2];
;                     Pw[e2 * 8 + fr] = (h16)(a[r] * 0.0625f + relb[rel_bucket(key2 - qpos) * 8 + fr]); } }
; #pragma unroll
;             for (int kk = 0; kk < 8; ++kk) kf[kk] = k1[kk];
;         }
.Lqk_go_1:
	v_mfma_f32_16x16x32_fp8_fp8 v[88:91], v[72:73], v[34:35], 0
	v_mfma_f32_16x16x32_fp8_fp8 v[88:91], v[74:75], v[32:33], v[88:91]
	v_mfma_f32_16x16x32_fp8_fp8 v[88:91], v[76:77], v[38:39], v[88:91]
	v_mfma_f32_16x16x32_fp8_fp8 v[88:91], v[78:79], v[36:37], v[88:91]
	v_mfma_f32_16x16x32_fp8_fp8 v[88:91], v[80:81], v[42:43], v[88:91]
	v_mfma_f32_16x16x32_fp8_fp8 v[88:91], v[82:83], v[40:41], v[88:91]
	v_mfma_f32_16x16x32_fp8_fp8 v[88:91], v[84:85], v[46:47], v[88:91]
	v_mfma_f32_16x16x32_fp8_fp8 v[88:91], v[86:87], v[44:45], v[88:91]
	s_and_saveexec_b64 s[12:13], s[8:9]
	s_waitcnt lgkmcnt(0)
	v_and_b32_e32 v145, 0xffff, v92
	v_lshrrev_b32_e32 v146, 16, v92
	v_and_b32_e32 v147, 0xffff, v93
	v_lshrrev_b32_e32 v148, 16, v93
	v_subrev_u32_e32 v145, s1, v145
	v_subrev_u32_e32 v146, s1, v146
	v_subrev_u32_e32 v147, s1, v147
	v_subrev_u32_e32 v148, s1, v148
	v_sub_u32_e32 v149, 0, v145
	v_sub_u32_e32 v158, 0, v146
	v_sub_u32_e32 v159, 0, v147
	v_sub_u32_e32 v160, 0, v148
	v_max_i32_e32 v149, v145, v149
	v_max_i32_e32 v158, v146, v158
	v_max_i32_e32 v159, v147, v159
	v_max_i32_e32 v160, v148, v160
	v_mul_u32_u24_e32 v161, v149, v149
	v_mul_u32_u24_e32 v162, v158, v158
	v_mul_u32_u24_e32 v163, v159, v159
	v_mul_u32_u24_e32 v164, v160, v160
	v_cvt_f32_u32_e32 v161, v161
	v_cvt_f32_u32_e32 v162, v162
	v_cvt_f32_u32_e32 v163, v163
	v_cvt_f32_u32_e32 v164, v164
	v_lshrrev_b32_e32 v161, 23, v161
	v_lshrrev_b32_e32 v162, 23, v162
	v_lshrrev_b32_e32 v163, 23, v163
	v_lshrrev_b32_e32 v164, 23, v164
	v_add_u32_e32 v161, 0xffffff83, v161
	v_add_u32_e32 v162, 0xffffff83, v162
	v_add_u32_e32 v163, 0xffffff83, v163
	v_add_u32_e32 v164, 0xffffff83, v164
	v_min_u32_e32 v161, 15, v161
	v_min_u32_e32 v162, 15, v162
	v_min_u32_e32 v163, 15, v163
	v_min_u32_e32 v164, 15, v164
	v_cmp_gt_u32_e32 vcc, 8, v149
	v_cmp_gt_u32_e64 s[26:27], 8, v158
	v_cmp_gt_u32_e64 s[36:37], 8, v159
	v_cmp_gt_u32_e64 s[38:39], 8, v160
	v_med3_i32 v165, v145, 0, 1
	v_med3_i32 v166, v146, 0, 1
	v_med3_i32 v167, v147, 0, 1
	v_med3_i32 v168, v148, 0, 1
	v_cndmask_b32_e64 v161, v161, v149, vcc
	v_cndmask_b32_e64 v162, v162, v158, s[26:27]
	v_cndmask_b32_e64 v163, v163, v159, s[36:37]
	v_cndmask_b32_e64 v164, v164, v160, s[38:39]
	v_lshl_add_u32 v161, v165, 4, v161
	v_lshl_add_u32 v162, v166, 4, v162
	v_lshl_add_u32 v163, v167, 4, v163
	v_lshl_add_u32 v164, v168, 4, v164
	v_lshl_add_u32 v165, v161, 5, v25
	v_lshl_add_u32 v166, v162, 5, v25
	v_lshl_add_u32 v167, v163, 5, v25
	v_lshl_add_u32 v168, v164, 5, v25
	ds_read_b32 v165, v165
	ds_read_b32 v166, v166
	ds_read_b32 v167, v167
	ds_read_b32 v168, v168
	s_waitcnt lgkmcnt(3)
	v_fma_mixlo_f16 v165, v88, s3, v165
	s_waitcnt lgkmcnt(2)
	v_fma_mixlo_f16 v166, v89, s3, v166
	s_waitcnt lgkmcnt(1)
	v_fma_mixlo_f16 v167, v90, s3, v167
	s_waitcnt lgkmcnt(0)
	v_fma_mixlo_f16 v168, v91, s3, v168
	ds_write_b16 v143, v165 offset:256
	ds_write_b16 v143, v166 offset:272
	ds_write_b16 v143, v167 offset:288
	ds_write_b16 v143, v168 offset:304
	s_mov_b64 exec, s[12:13]
	s_cmp_le_i32 s16, 2
	s_cbranch_scc1 .Lqk_done
	ds_read_b64 v[92:93], v142 offset:64
	s_cmp_gt_i32 s16, 4
	s_cbranch_scc0 .Lqk_ni_2
	v_add_lshl_u32 v111, s48, v111, 8
	v_add_u32_e32 v111, v144, v111
	global_load_dwordx4 v[72:75], v111, s[84:85]
	global_load_dwordx4 v[76:79], v111, s[84:85] offset:64
	global_load_dwordx4 v[80:83], v111, s[84:85] offset:128
	global_load_dwordx4 v[84:87], v111, s[84:85] offset:192
	s_waitcnt vmcnt(8)
	s_branch .Lqk_go_2
.Lqk_ni_2:
	s_cmp_gt_i32 s16, 3
	s_cbranch_scc0 .Lqk_nj_2
	s_waitcnt vmcnt(4)
	s_branch .Lqk_go_2

; __device__ __forceinline__ void dsa_unit(int wv, const Args& A, LAS unsigned char* lds, int s, int qt) {
;     ...
;         for (int kt = 0; kt < nt; ++kt) {
;             long k1[8];
;             DSA_LOADT(k1, kt + 1);
;             f32x4 a = {0.f, 0.f, 0.f, 0.f};
; #pragma unroll
;             for (int kk = 0; kk < 8; ++kk) a = __builtin_amdgcn_mfma_f32_16x16x32_fp8_fp8(kf[kk], qf[kk], a, 0, 0, 0);
;             if (fr < 8) {
; #pragma unroll
;                 for (int r = 0; r < 4; ++r) { const int e2 = kt * 16 + fq * 4 + r; const int key2 = lst[e2];
;                     Pw[e2 * 8 + fr] = (h16)(a[r] * 0.0625f + relb[rel_bucket(key2 - qpos) * 8 + fr]); } }
; #pragma unroll
;             for (int kk = 0; kk < 8; ++kk) kf[kk] = k1[kk];
;         }
.Lqk_go_2:
	v_mfma_f32_16x16x32_fp8_fp8 v[88:91], v[124:125], v[34:35], 0
	v_mfma_f32_16x16x32_fp8_fp8 v[88:91], v[126:127], v[32:33], v[88:91]
	v_mfma_f32_16x16x32_fp8_fp8 v[88:91], v[128:129], v[38:39], v[88:91]
	v_mfma_f32_16x16x32_fp8_fp8 v[88:91], v[130:131], v[36:37], v[88:91]
	v_mfma_f32_16x16x32_fp8_fp8 v[88:91], v[132:133], v[42:43], v[88:91]
	v_mfma_f32_16x16x32_fp8_fp8 v[88:91], v[134:135], v[40:41], v[88:91]
	v_mfma_f32_16x16x32_fp8_fp8 v[88:91], v[136:137], v[46:47], v[88:91]
	v_mfma_f32_16x16x32_fp8_fp8 v[88:91], v[138:139], v[44:45], v[88:91]
	s_and_saveexec_b64 s[12:13], s[8:9]
	s_waitcnt lgkmcnt(0)
	v_and_b32_e32 v145, 0xffff, v92
	v_lshrrev_b32_e32 v146, 16, v92
	v_and_b32_e32 v147, 0xffff, v93
	v_lshrrev_b32_e32 v148, 16, v93
	v_subrev_u32_e32 v145, s1, v145
	v_subrev_u32_e32 v146, s1, v146
	v_subrev_u32_e32 v147, s1, v147
	v_subrev_u32_e32 v148, s1, v148
	v_sub_u32_e32 v149, 0, v145
	v_sub_u32_e32 v158, 0, v146
	v_sub_u32_e32 v159, 0, v147
	v_sub_u32_e32 v160, 0, v148
	v_max_i32_e32 v149, v145, v149
	v_max_i32_e32 v158, v146, v158
	v_max_i32_e32 v159, v147, v159
	v_max_i32_e32 v160, v148, v160
	v_mul_u32_u24_e32 v161, v149, v149
	v_mul_u32_u24_e32 v162, v158, v158
	v_mul_u32_u24_e32 v163, v159, v159
	v_mul_u32_u24_e32 v164, v160, v160
	v_cvt_f32_u32_e32 v161, v161
	v_cvt_f32_u32_e32 v162, v162
	v_cvt_f32_u32_e32 v163, v163
	v_cvt_f32_u32_e32 v164, v164
	v_lshrrev_b32_e32 v161, 23, v161
	v_lshrrev_b32_e32 v162, 23, v162
	v_lshrrev_b32_e32 v163, 23, v163
	v_lshrrev_b32_e32 v164, 23, v164
	v_add_u32_e32 v161, 0xffffff83, v161
	v_add_u32_e32 v162, 0xffffff83, v162
	v_add_u32_e32 v163, 0xffffff83, v163
	v_add_u32_e32 v164, 0xffffff83, v164
	v_min_u32_e32 v161, 15, v161
	v_min_u32_e32 v162, 15, v162
	v_min_u32_e32 v163, 15, v163
	v_min_u32_e32 v164, 15, v164
	v_cmp_gt_u32_e32 vcc, 8, v149
	v_cmp_gt_u32_e64 s[26:27], 8, v158
	v_cmp_gt_u32_e64 s[36:37], 8, v159
	v_cmp_gt_u32_e64 s[38:39], 8, v160
	v_med3_i32 v165, v145, 0, 1
	v_med3_i32 v166, v146, 0, 1
	v_med3_i32 v167, v147, 0, 1
	v_med3_i32 v168, v148, 0, 1
	v_cndmask_b32_e64 v161, v161, v149, vcc
	v_cndmask_b32_e64 v162, v162, v158, s[26:27]
	v_cndmask_b32_e64 v163, v163, v159, s[36:37]
	v_cndmask_b32_e64 v164, v164, v160, s[38:39]
	v_lshl_add_u32 v161, v165, 4, v161
	v_lshl_add_u32 v162, v166, 4, v162
	v_lshl_add_u32 v163, v167, 4, v163
	v_lshl_add_u32 v164, v168, 4, v164
	v_lshl_add_u32 v165, v161, 5, v25
	v_lshl_add_u32 v166, v162, 5, v25
	v_lshl_add_u32 v167, v163, 5, v25
	v_lshl_add_u32 v168, v164, 5, v25
	ds_read_b32 v165, v165
	ds_read_b32 v166, v166
	ds_read_b32 v167, v167
	ds_read_b32 v168, v168
	s_waitcnt lgkmcnt(3)
	v_fma_mixlo_f16 v165, v88, s3, v165
	s_waitcnt lgkmcnt(2)
	v_fma_mixlo_f16 v166, v89, s3, v166
	s_waitcnt lgkmcnt(1)
	v_fma_mixlo_f16 v167, v90, s3, v167
	s_waitcnt lgkmcnt(0)
	v_fma_mixlo_f16 v168, v91, s3, v168
	ds_write_b16 v143, v165 offset:512
	ds_write_b16 v143, v166 offset:528
	ds_write_b16 v143, v167 offset:544
	ds_write_b16 v143, v168 offset:560
	s_mov_b64 exec, s[12:13]
	s_cmp_le_i32 s16, 3
	s_cbranch_scc1 .Lqk_done
	ds_read_b64 v[92:93], v142 offset:96
	s_cmp_gt_i32 s16, 5
	s_cbranch_scc0 .Lqk_ni_3
	v_add_lshl_u32 v112, s48, v112, 8
	v_add_u32_e32 v112, v144, v112
	global_load_dwordx4 v[124:127], v112, s[84:85]
	global_load_dwordx4 v[128:131], v112, s[84:85] offset:64
	global_load_dwordx4 v[132:135], v112, s[84:85] offset:128
	global_load_dwordx4 v[136:139], v112, s[84:85] offset:192
	s_waitcnt vmcnt(8)
	s_branch .Lqk_go_3
.Lqk_ni_3:
	s_cmp_gt_i32 s16, 4
	s_cbranch_scc0 .Lqk_nj_3
	s_waitcnt vmcnt(4)
	s_branch .Lqk_go_3

; __device__ __forceinline__ void dsa_unit(int wv, const Args& A, LAS unsigned char* lds, int s, int qt) {
;     ...
;         for (int kt = 0; kt < nt; ++kt) {
;             long k1[8];
;             DSA_LOADT(k1, kt + 1);
;             f32x4 a = {0.f, 0.f, 0.f, 0.f};
; #pragma unroll
;             for (int kk = 0; kk < 8; ++kk) a = __builtin_amdgcn_mfma_f32_16x16x32_fp8_fp8(kf[kk], qf[kk], a, 0, 0, 0);
;             if (fr < 8) {
; #pragma unroll
;                 for (int r = 0; r < 4; ++r) { const int e2 = kt * 16 + fq * 4 + r; const int key2 = lst[e2];
;                     Pw[e2 * 8 + fr] = (h16)(a[r] * 0.0625f + relb[rel_bucket(key2 - qpos) * 8 + fr]); } }
; #pragma unroll
;             for (int kk = 0; kk < 8; ++kk) kf[kk] = k1[kk];
;         }
.Lqk_go_3:
	v_mfma_f32_16x16x32_fp8_fp8 v[88:91], v[56:57], v[34:35], 0
	v_mfma_f32_16x16x32_fp8_fp8 v[88:91], v[58:59], v[32:33], v[88:91]
	v_mfma_f32_16x16x32_fp8_fp8 v[88:91], v[60:61], v[38:39], v[88:91]
	v_mfma_f32_16x16x32_fp8_fp8 v[88:91], v[62:63], v[36:37], v[88:91]
	v_mfma_f32_16x16x32_fp8_fp8 v[88:91], v[64:65], v[42:43], v[88:91]
	v_mfma_f32_16x16x32_fp8_fp8 v[88:91], v[66:67], v[40:41], v[88:91]
	v_mfma_f32_16x16x32_fp8_fp8 v[88:91], v[68:69], v[46:47], v[88:91]
	v_mfma_f32_16x16x32_fp8_fp8 v[88:91], v[70:71], v[44:45], v[88:91]
	s_and_saveexec_b64 s[12:13], s[8:9]
	s_waitcnt lgkmcnt(0)
	v_and_b32_e32 v145, 0xffff, v92
	v_lshrrev_b32_e32 v146, 16, v92
	v_and_b32_e32 v147, 0xffff, v93
	v_lshrrev_b32_e32 v148, 16, v93
	v_subrev_u32_e32 v145, s1, v145
	v_subrev_u32_e32 v146, s1, v146
	v_subrev_u32_e32 v147, s1, v147
	v_subrev_u32_e32 v148, s1, v148
	v_sub_u32_e32 v149, 0, v145
	v_sub_u32_e32 v158, 0, v146
	v_sub_u32_e32 v159, 0, v147
	v_sub_u32_e32 v160, 0, v148
	v_max_i32_e32 v149, v145, v149
	v_max_i32_e32 v158, v146, v158
	v_max_i32_e32 v159, v147, v159
	v_max_i32_e32 v160, v148, v160
	v_mul_u32_u24_e32 v161, v149, v149
	v_mul_u32_u24_e32 v162, v158, v158
	v_mul_u32_u24_e32 v163, v159, v159
	v_mul_u32_u24_e32 v164, v160, v160
	v_cvt_f32_u32_e32 v161, v161
	v_cvt_f32_u32_e32 v162, v162
	v_cvt_f32_u32_e32 v163, v163
	v_cvt_f32_u32_e32 v164, v164
	v_lshrrev_b32_e32 v161, 23, v161
	v_lshrrev_b32_e32 v162, 23, v162
	v_lshrrev_b32_e32 v163, 23, v163
	v_lshrrev_b32_e32 v164, 23, v164
	v_add_u32_e32 v161, 0xffffff83, v161
	v_add_u32_e32 v162, 0xffffff83, v162
	v_add_u32_e32 v163, 0xffffff83, v163
	v_add_u32_e32 v164, 0xffffff83, v164
	v_min_u32_e32 v161, 15, v161
	v_min_u32_e32 v162, 15, v162
	v_min_u32_e32 v163, 15, v163
	v_min_u32_e32 v164, 15, v164
	v_cmp_gt_u32_e32 vcc, 8, v149
	v_cmp_gt_u32_e64 s[26:27], 8, v158
	v_cmp_gt_u32_e64 s[36:37], 8, v159
	v_cmp_gt_u32_e64 s[38:39], 8, v160
	v_med3_i32 v165, v145, 0, 1
	v_med3_i32 v166, v146, 0, 1
	v_med3_i32 v167, v147, 0, 1
	v_med3_i32 v168, v148, 0, 1
	v_cndmask_b32_e64 v161, v161, v149, vcc
	v_cndmask_b32_e64 v162, v162, v158, s[26:27]
	v_cndmask_b32_e64 v163, v163, v159, s[36:37]
	v_cndmask_b32_e64 v164, v164, v160, s[38:39]
	v_lshl_add_u32 v161, v165, 4, v161
	v_lshl_add_u32 v162, v166, 4, v162
	v_lshl_add_u32 v163, v167, 4, v163
	v_lshl_add_u32 v164, v168, 4, v164
	v_lshl_add_u32 v165, v161, 5, v25
	v_lshl_add_u32 v166, v162, 5, v25
	v_lshl_add_u32 v167, v163, 5, v25
	v_lshl_add_u32 v168, v164, 5, v25
	ds_read_b32 v165, v165
	ds_read_b32 v166, v166
	ds_read_b32 v167, v167
	ds_read_b32 v168, v168
	s_waitcnt lgkmcnt(3)
	v_fma_mixlo_f16 v165, v88, s3, v165
	s_waitcnt lgkmcnt(2)
	v_fma_mixlo_f16 v166, v89, s3, v166
	s_waitcnt lgkmcnt(1)
	v_fma_mixlo_f16 v167, v90, s3, v167
	s_waitcnt lgkmcnt(0)
	v_fma_mixlo_f16 v168, v91, s3, v168
	ds_write_b16 v143, v165 offset:768
	ds_write_b16 v143, v166 offset:784
	ds_write_b16 v143, v167 offset:800
	ds_write_b16 v143, v168 offset:816
	s_mov_b64 exec, s[12:13]
	s_cmp_le_i32 s16, 4
	s_cbranch_scc1 .Lqk_done
	ds_read_b64 v[92:93], v142 offset:128
	s_cmp_gt_i32 s16, 6
	s_cbranch_scc0 .Lqk_ni_4
	v_add_lshl_u32 v113, s48, v113, 8
	v_add_u32_e32 v113, v144, v113
	global_load_dwordx4 v[56:59], v113, s[84:85]
	global_load_dwordx4 v[60:63], v113, s[84:85] offset:64
	global_load_dwordx4 v[64:67], v113, s[84:85] offset:128
	global_load_dwordx4 v[68:71], v113, s[84:85] offset:192
	s_waitcnt vmcnt(8)
	s_branch .Lqk_go_4
.Lqk_ni_4:
	s_cmp_gt_i32 s16, 5
	s_cbranch_scc0 .Lqk_nj_4
	s_waitcnt vmcnt(4)
	s_branch .Lqk_go_4

; __device__ __forceinline__ void dsa_unit(int wv, const Args& A, LAS unsigned char* lds, int s, int qt) {
;     ...
;         for (int kt = 0; kt < nt; ++kt) {
;             long k1[8];
;             DSA_LOADT(k1, kt + 1);
;             f32x4 a = {0.f, 0.f, 0.f, 0.f};
; #pragma unroll
;             for (int kk = 0; kk < 8; ++kk) a = __builtin_amdgcn_mfma_f32_16x16x32_fp8_fp8(kf[kk], qf[kk], a, 0, 0, 0);
;             if (fr < 8) {
; #pragma unroll
;                 for (int r = 0; r < 4; ++r) { const int e2 = kt * 16 + fq * 4 + r; const int key2 = lst[e2];
;                     Pw[e2 * 8 + fr] = (h16)(a[r] * 0.0625f + relb[rel_bucket(key2 - qpos) * 8 + fr]); } }
; #pragma unroll
;             for (int kk = 0; kk < 8; ++kk) kf[kk] = k1[kk];
;         }
.Lqk_go_4:
	v_mfma_f32_16x16x32_fp8_fp8 v[88:91], v[72:73], v[34:35], 0
	v_mfma_f32_16x16x32_fp8_fp8 v[88:91], v[74:75], v[32:33], v[88:91]
	v_mfma_f32_16x16x32_fp8_fp8 v[88:91], v[76:77], v[38:39], v[88:91]
	v_mfma_f32_16x16x32_fp8_fp8 v[88:91], v[78:79], v[36:37], v[88:91]
	v_mfma_f32_16x16x32_fp8_fp8 v[88:91], v[80:81], v[42:43], v[88:91]
	v_mfma_f32_16x16x32_fp8_fp8 v[88:91], v[82:83], v[40:41], v[88:91]
	v_mfma_f32_16x16x32_fp8_fp8 v[88:91], v[84:85], v[46:47], v[88:91]
	v_mfma_f32_16x16x32_fp8_fp8 v[88:91], v[86:87], v[44:45], v[88:91]
	s_and_saveexec_b64 s[12:13], s[8:9]
	s_waitcnt lgkmcnt(0)
	v_and_b32_e32 v145, 0xffff, v92
	v_lshrrev_b32_e32 v146, 16, v92
	v_and_b32_e32 v147, 0xffff, v93
	v_lshrrev_b32_e32 v148, 16, v93
	v_subrev_u32_e32 v145, s1, v145
	v_subrev_u32_e32 v146, s1, v146
	v_subrev_u32_e32 v147, s1, v147
	v_subrev_u32_e32 v148, s1, v148
	v_sub_u32_e32 v149, 0, v145
	v_sub_u32_e32 v158, 0, v146
	v_sub_u32_e32 v159, 0, v147
	v_sub_u32_e32 v160, 0, v148
	v_max_i32_e32 v149, v145, v149
	v_max_i32_e32 v158, v146, v158
	v_max_i32_e32 v159, v147, v159
	v_max_i32_e32 v160, v148, v160
	v_mul_u32_u24_e32 v161, v149, v149
	v_mul_u32_u24_e32 v162, v158, v158
	v_mul_u32_u24_e32 v163, v159, v159
	v_mul_u32_u24_e32 v164, v160, v160
	v_cvt_f32_u32_e32 v161, v161
	v_cvt_f32_u32_e32 v162, v162
	v_cvt_f32_u32_e32 v163, v163
	v_cvt_f32_u32_e32 v164, v164
	v_lshrrev_b32_e32 v161, 23, v161
	v_lshrrev_b32_e32 v162, 23, v162
	v_lshrrev_b32_e32 v163, 23, v163
	v_lshrrev_b32_e32 v164, 23, v164
	v_add_u32_e32 v161, 0xffffff83, v161
	v_add_u32_e32 v162, 0xffffff83, v162
	v_add_u32_e32 v163, 0xffffff83, v163
	v_add_u32_e32 v164, 0xffffff83, v164
	v_min_u32_e32 v161, 15, v161
	v_min_u32_e32 v162, 15, v162
	v_min_u32_e32 v163, 15, v163
	v_min_u32_e32 v164, 15, v164
	v_cmp_gt_u32_e32 vcc, 8, v149
	v_cmp_gt_u32_e64 s[26:27], 8, v158
	v_cmp_gt_u32_e64 s[36:37], 8, v159
	v_cmp_gt_u32_e64 s[38:39], 8, v160
	v_med3_i32 v165, v145, 0, 1
	v_med3_i32 v166, v146, 0, 1
	v_med3_i32 v167, v147, 0, 1
	v_med3_i32 v168, v148, 0, 1
	v_cndmask_b32_e64 v161, v161, v149, vcc
	v_cndmask_b32_e64 v162, v162, v158, s[26:27]
	v_cndmask_b32_e64 v163, v163, v159, s[36:37]
	v_cndmask_b32_e64 v164, v164, v160, s[38:39]
	v_lshl_add_u32 v161, v165, 4, v161
	v_lshl_add_u32 v162, v166, 4, v162
	v_lshl_add_u32 v163, v167, 4, v163
	v_lshl_add_u32 v164, v168, 4, v164
	v_lshl_add_u32 v165, v161, 5, v25
	v_lshl_add_u32 v166, v162, 5, v25
	v_lshl_add_u32 v167, v163, 5, v25
	v_lshl_add_u32 v168, v164, 5, v25
	ds_read_b32 v165, v165
	ds_read_b32 v166, v166
	ds_read_b32 v167, v167
	ds_read_b32 v168, v168
	s_waitcnt lgkmcnt(3)
	v_fma_mixlo_f16 v165, v88, s3, v165
	s_waitcnt lgkmcnt(2)
	v_fma_mixlo_f16 v166, v89, s3, v166
	s_waitcnt lgkmcnt(1)
	v_fma_mixlo_f16 v167, v90, s3, v167
	s_waitcnt lgkmcnt(0)
	v_fma_mixlo_f16 v168, v91, s3, v168
	ds_write_b16 v143, v165 offset:1024
	ds_write_b16 v143, v166 offset:1040
	ds_write_b16 v143, v167 offset:1056
	ds_write_b16 v143, v168 offset:1072
	s_mov_b64 exec, s[12:13]
	s_cmp_le_i32 s16, 5
	s_cbranch_scc1 .Lqk_done
	ds_read_b64 v[92:93], v142 offset:160
	s_cmp_gt_i32 s16, 7
	s_cbranch_scc0 .Lqk_ni_5
	v_add_lshl_u32 v114, s48, v114, 8
	v_add_u32_e32 v114, v144, v114
	global_load_dwordx4 v[72:75], v114, s[84:85]
	global_load_dwordx4 v[76:79], v114, s[84:85] offset:64
	global_load_dwordx4 v[80:83], v114, s[84:85] offset:128
	global_load_dwordx4 v[84:87], v114, s[84:85] offset:192
	s_waitcnt vmcnt(8)
	s_branch .Lqk_go_5
.Lqk_ni_5:
	s_cmp_gt_i32 s16, 6
	s_cbranch_scc0 .Lqk_nj_5
	s_waitcnt vmcnt(4)
	s_branch .Lqk_go_5

; __device__ __forceinline__ void dsa_unit(int wv, const Args& A, LAS unsigned char* lds, int s, int qt) {
;     ...
;         for (int kt = 0; kt < nt; ++kt) {
;             long k1[8];
;             DSA_LOADT(k1, kt + 1);
;             f32x4 a = {0.f, 0.f, 0.f, 0.f};
; #pragma unroll
;             for (int kk = 0; kk < 8; ++kk) a = __builtin_amdgcn_mfma_f32_16x16x32_fp8_fp8(kf[kk], qf[kk], a, 0, 0, 0);
;             if (fr < 8) {
; #pragma unroll
;                 for (int r = 0; r < 4; ++r) { const int e2 = kt * 16 + fq * 4 + r; const int key2 = lst[e2];
;                     Pw[e2 * 8 + fr] = (h16)(a[r] * 0.0625f + relb[rel_bucket(key2 - qpos) * 8 + fr]); } }
; #pragma unroll
;             for (int kk = 0; kk < 8; ++kk) kf[kk] = k1[kk];
;         }
.Lqk_go_5:
	v_mfma_f32_16x16x32_fp8_fp8 v[88:91], v[124:125], v[34:35], 0
	v_mfma_f32_16x16x32_fp8_fp8 v[88:91], v[126:127], v[32:33], v[88:91]
	v_mfma_f32_16x16x32_fp8_fp8 v[88:91], v[128:129], v[38:39], v[88:91]
	v_mfma_f32_16x16x32_fp8_fp8 v[88:91], v[130:131], v[36:37], v[88:91]
	v_mfma_f32_16x16x32_fp8_fp8 v[88:91], v[132:133], v[42:43], v[88:91]
	v_mfma_f32_16x16x32_fp8_fp8 v[88:91], v[134:135], v[40:41], v[88:91]
	v_mfma_f32_16x16x32_fp8_fp8 v[88:91], v[136:137], v[46:47], v[88:91]
	v_mfma_f32_16x16x32_fp8_fp8 v[88:91], v[138:139], v[44:45], v[88:91]
	s_and_saveexec_b64 s[12:13], s[8:9]
	s_waitcnt lgkmcnt(0)
	v_and_b32_e32 v145, 0xffff, v92
	v_lshrrev_b32_e32 v146, 16, v92
	v_and_b32_e32 v147, 0xffff, v93
	v_lshrrev_b32_e32 v148, 16, v93
	v_subrev_u32_e32 v145, s1, v145
	v_subrev_u32_e32 v146, s1, v146
	v_subrev_u32_e32 v147, s1, v147
	v_subrev_u32_e32 v148, s1, v148
	v_sub_u32_e32 v149, 0, v145
	v_sub_u32_e32 v158, 0, v146
	v_sub_u32_e32 v159, 0, v147
	v_sub_u32_e32 v160, 0, v148
	v_max_i32_e32 v149, v145, v149
	v_max_i32_e32 v158, v146, v158
	v_max_i32_e32 v159, v147, v159
	v_max_i32_e32 v160, v148, v160
	v_mul_u32_u24_e32 v161, v149, v149
	v_mul_u32_u24_e32 v162, v158, v158
	v_mul_u32_u24_e32 v163, v159, v159
	v_mul_u32_u24_e32 v164, v160, v160
	v_cvt_f32_u32_e32 v161, v161
	v_cvt_f32_u32_e32 v162, v162
	v_cvt_f32_u32_e32 v163, v163
	v_cvt_f32_u32_e32 v164, v164
	v_lshrrev_b32_e32 v161, 23, v161
	v_lshrrev_b32_e32 v162, 23, v162
	v_lshrrev_b32_e32 v163, 23, v163
	v_lshrrev_b32_e32 v164, 23, v164
	v_add_u32_e32 v161, 0xffffff83, v161
	v_add_u32_e32 v162, 0xffffff83, v162
	v_add_u32_e32 v163, 0xffffff83, v163
	v_add_u32_e32 v164, 0xffffff83, v164
	v_min_u32_e32 v161, 15, v161
	v_min_u32_e32 v162, 15, v162
	v_min_u32_e32 v163, 15, v163
	v_min_u32_e32 v164, 15, v164
	v_cmp_gt_u32_e32 vcc, 8, v149
	v_cmp_gt_u32_e64 s[26:27], 8, v158
	v_cmp_gt_u32_e64 s[36:37], 8, v159
	v_cmp_gt_u32_e64 s[38:39], 8, v160
	v_med3_i32 v165, v145, 0, 1
	v_med3_i32 v166, v146, 0, 1
	v_med3_i32 v167, v147, 0, 1
	v_med3_i32 v168, v148, 0, 1
	v_cndmask_b32_e64 v161, v161, v149, vcc
	v_cndmask_b32_e64 v162, v162, v158, s[26:27]
	v_cndmask_b32_e64 v163, v163, v159, s[36:37]
	v_cndmask_b32_e64 v164, v164, v160, s[38:39]
	v_lshl_add_u32 v161, v165, 4, v161
	v_lshl_add_u32 v162, v166, 4, v162
	v_lshl_add_u32 v163, v167, 4, v163
	v_lshl_add_u32 v164, v168, 4, v164
	v_lshl_add_u32 v165, v161, 5, v25
	v_lshl_add_u32 v166, v162, 5, v25
	v_lshl_add_u32 v167, v163, 5, v25
	v_lshl_add_u32 v168, v164, 5, v25
	ds_read_b32 v165, v165
	ds_read_b32 v166, v166
	ds_read_b32 v167, v167
	ds_read_b32 v168, v168
	s_waitcnt lgkmcnt(3)
	v_fma_mixlo_f16 v165, v88, s3, v165
	s_waitcnt lgkmcnt(2)
	v_fma_mixlo_f16 v166, v89, s3, v166
	s_waitcnt lgkmcnt(1)
	v_fma_mixlo_f16 v167, v90, s3, v167
	s_waitcnt lgkmcnt(0)
	v_fma_mixlo_f16 v168, v91, s3, v168
	ds_write_b16 v143, v165 offset:1280
	ds_write_b16 v143, v166 offset:1296
	ds_write_b16 v143, v167 offset:1312
	ds_write_b16 v143, v168 offset:1328
	s_mov_b64 exec, s[12:13]
	s_cmp_le_i32 s16, 6
	s_cbranch_scc1 .Lqk_done
	ds_read_b64 v[92:93], v142 offset:192
	s_cmp_gt_i32 s16, 8
	s_cbranch_scc0 .Lqk_ni_6
	v_add_lshl_u32 v115, s48, v115, 8
	v_add_u32_e32 v115, v144, v115
	global_load_dwordx4 v[124:127], v115, s[84:85]
	global_load_dwordx4 v[128:131], v115, s[84:85] offset:64
	global_load_dwordx4 v[132:135], v115, s[84:85] offset:128
	global_load_dwordx4 v[136:139], v115, s[84:85] offset:192
	s_waitcnt vmcnt(8)
	s_branch .Lqk_go_6
.Lqk_ni_6:
	s_cmp_gt_i32 s16, 7
	s_cbranch_scc0 .Lqk_nj_6
	s_waitcnt vmcnt(4)
	s_branch .Lqk_go_6

; __device__ __forceinline__ void dsa_unit(int wv, const Args& A, LAS unsigned char* lds, int s, int qt) {
;     ...
;         for (int kt = 0; kt < nt; ++kt) {
;             long k1[8];
;             DSA_LOADT(k1, kt + 1);
;             f32x4 a = {0.f, 0.f, 0.f, 0.f};
; #pragma unroll
;             for (int kk = 0; kk < 8; ++kk) a = __builtin_amdgcn_mfma_f32_16x16x32_fp8_fp8(kf[kk], qf[kk], a, 0, 0, 0);
;             if (fr < 8) {
; #pragma unroll
;                 for (int r = 0; r < 4; ++r) { const int e2 = kt * 16 + fq * 4 + r; const int key2 = lst[e2];
;                     Pw[e2 * 8 + fr] = (h16)(a[r] * 0.0625f + relb[rel_bucket(key2 - qpos) * 8 + fr]); } }
; #pragma unroll
;             for (int kk = 0; kk < 8; ++kk) kf[kk] = k1[kk];
;         }
.Lqk_go_6:
	v_mfma_f32_16x16x32_fp8_fp8 v[88:91], v[56:57], v[34:35], 0
	v_mfma_f32_16x16x32_fp8_fp8 v[88:91], v[58:59], v[32:33], v[88:91]
	v_mfma_f32_16x16x32_fp8_fp8 v[88:91], v[60:61], v[38:39], v[88:91]
	v_mfma_f32_16x16x32_fp8_fp8 v[88:91], v[62:63], v[36:37], v[88:91]
	v_mfma_f32_16x16x32_fp8_fp8 v[88:91], v[64:65], v[42:43], v[88:91]
	v_mfma_f32_16x16x32_fp8_fp8 v[88:91], v[66:67], v[40:41], v[88:91]
	v_mfma_f32_16x16x32_fp8_fp8 v[88:91], v[68:69], v[46:47], v[88:91]
	v_mfma_f32_16x16x32_fp8_fp8 v[88:91], v[70:71], v[44:45], v[88:91]
	s_and_saveexec_b64 s[12:13], s[8:9]
	s_waitcnt lgkmcnt(0)
	v_and_b32_e32 v145, 0xffff, v92
	v_lshrrev_b32_e32 v146, 16, v92
	v_and_b32_e32 v147, 0xffff, v93
	v_lshrrev_b32_e32 v148, 16, v93
	v_subrev_u32_e32 v145, s1, v145
	v_subrev_u32_e32 v146, s1, v146
	v_subrev_u32_e32 v147, s1, v147
	v_subrev_u32_e32 v148, s1, v148
	v_sub_u32_e32 v149, 0, v145
	v_sub_u32_e32 v158, 0, v146
	v_sub_u32_e32 v159, 0, v147
	v_sub_u32_e32 v160, 0, v148
	v_max_i32_e32 v149, v145, v149
	v_max_i32_e32 v158, v146, v158
	v_max_i32_e32 v159, v147, v159
	v_max_i32_e32 v160, v148, v160
	v_mul_u32_u24_e32 v161, v149, v149
	v_mul_u32_u24_e32 v162, v158, v158
	v_mul_u32_u24_e32 v163, v159, v159
	v_mul_u32_u24_e32 v164, v160, v160
	v_cvt_f32_u32_e32 v161, v161
	v_cvt_f32_u32_e32 v162, v162
	v_cvt_f32_u32_e32 v163, v163
	v_cvt_f32_u32_e32 v164, v164
	v_lshrrev_b32_e32 v161, 23, v161
	v_lshrrev_b32_e32 v162, 23, v162
	v_lshrrev_b32_e32 v163, 23, v163
	v_lshrrev_b32_e32 v164, 23, v164
	v_add_u32_e32 v161, 0xffffff83, v161
	v_add_u32_e32 v162, 0xffffff83, v162
	v_add_u32_e32 v163, 0xffffff83, v163
	v_add_u32_e32 v164, 0xffffff83, v164
	v_min_u32_e32 v161, 15, v161
	v_min_u32_e32 v162, 15, v162
	v_min_u32_e32 v163, 15, v163
	v_min_u32_e32 v164, 15, v164
	v_cmp_gt_u32_e32 vcc, 8, v149
	v_cmp_gt_u32_e64 s[26:27], 8, v158
	v_cmp_gt_u32_e64 s[36:37], 8, v159
	v_cmp_gt_u32_e64 s[38:39], 8, v160
	v_med3_i32 v165, v145, 0, 1
	v_med3_i32 v166, v146, 0, 1
	v_med3_i32 v167, v147, 0, 1
	v_med3_i32 v168, v148, 0, 1
	v_cndmask_b32_e64 v161, v161, v149, vcc
	v_cndmask_b32_e64 v162, v162, v158, s[26:27]
	v_cndmask_b32_e64 v163, v163, v159, s[36:37]
	v_cndmask_b32_e64 v164, v164, v160, s[38:39]
	v_lshl_add_u32 v161, v165, 4, v161
	v_lshl_add_u32 v162, v166, 4, v162
	v_lshl_add_u32 v163, v167, 4, v163
	v_lshl_add_u32 v164, v168, 4, v164
	v_lshl_add_u32 v165, v161, 5, v25
	v_lshl_add_u32 v166, v162, 5, v25
	v_lshl_add_u32 v167, v163, 5, v25
	v_lshl_add_u32 v168, v164, 5, v25
	ds_read_b32 v165, v165
	ds_read_b32 v166, v166
	ds_read_b32 v167, v167
	ds_read_b32 v168, v168
	s_waitcnt lgkmcnt(3)
	v_fma_mixlo_f16 v165, v88, s3, v165
	s_waitcnt lgkmcnt(2)
	v_fma_mixlo_f16 v166, v89, s3, v166
	s_waitcnt lgkmcnt(1)
	v_fma_mixlo_f16 v167, v90, s3, v167
	s_waitcnt lgkmcnt(0)
	v_fma_mixlo_f16 v168, v91, s3, v168
	ds_write_b16 v143, v165 offset:1536
	ds_write_b16 v143, v166 offset:1552
	ds_write_b16 v143, v167 offset:1568
	ds_write_b16 v143, v168 offset:1584
	s_mov_b64 exec, s[12:13]
	s_cmp_le_i32 s16, 7
	s_cbranch_scc1 .Lqk_done
	ds_read_b64 v[92:93], v142 offset:224
	s_cmp_gt_i32 s16, 9
	s_cbranch_scc0 .Lqk_ni_7
	v_add_lshl_u32 v116, s48, v116, 8
	v_add_u32_e32 v116, v144, v116
	global_load_dwordx4 v[56:59], v116, s[84:85]
	global_load_dwordx4 v[60:63], v116, s[84:85] offset:64
	global_load_dwordx4 v[64:67], v116, s[84:85] offset:128
	global_load_dwordx4 v[68:71], v116, s[84:85] offset:192
	s_waitcnt vmcnt(8)
	s_branch .Lqk_go_7
.Lqk_ni_7:
	s_cmp_gt_i32 s16, 8
	s_cbranch_scc0 .Lqk_nj_7
	s_waitcnt vmcnt(4)
	s_branch .Lqk_go_7

; __device__ __forceinline__ void dsa_unit(int wv, const Args& A, LAS unsigned char* lds, int s, int qt) {
;     ...
;         for (int kt = 0; kt < nt; ++kt) {
;             long k1[8];
;             DSA_LOADT(k1, kt + 1);
;             f32x4 a = {0.f, 0.f, 0.f, 0.f};
; #pragma unroll
;             for (int kk = 0; kk < 8; ++kk) a = __builtin_amdgcn_mfma_f32_16x16x32_fp8_fp8(kf[kk], qf[kk], a, 0, 0, 0);
;             if (fr < 8) {
; #pragma unroll
;                 for (int r = 0; r < 4; ++r) { const int e2 = kt * 16 + fq * 4 + r; const int key2 = lst[e2];
;                     Pw[e2 * 8 + fr] = (h16)(a[r] * 0.0625f + relb[rel_bucket(key2 - qpos) * 8 + fr]); } }
; #pragma unroll
;             for (int kk = 0; kk < 8; ++kk) kf[kk] = k1[kk];
;         }
.Lqk_go_7:
	v_mfma_f32_16x16x32_fp8_fp8 v[88:91], v[72:73], v[34:35], 0
	v_mfma_f32_16x16x32_fp8_fp8 v[88:91], v[74:75], v[32:33], v[88:91]
	v_mfma_f32_16x16x32_fp8_fp8 v[88:91], v[76:77], v[38:39], v[88:91]
	v_mfma_f32_16x16x32_fp8_fp8 v[88:91], v[78:79], v[36:37], v[88:91]
	v_mfma_f32_16x16x32_fp8_fp8 v[88:91], v[80:81], v[42:43], v[88:91]
	v_mfma_f32_16x16x32_fp8_fp8 v[88:91], v[82:83], v[40:41], v[88:91]
	v_mfma_f32_16x16x32_fp8_fp8 v[88:91], v[84:85], v[46:47], v[88:91]
	v_mfma_f32_16x16x32_fp8_fp8 v[88:91], v[86:87], v[44:45], v[88:91]
	s_and_saveexec_b64 s[12:13], s[8:9]
	s_waitcnt lgkmcnt(0)
	v_and_b32_e32 v145, 0xffff, v92
	v_lshrrev_b32_e32 v146, 16, v92
	v_and_b32_e32 v147, 0xffff, v93
	v_lshrrev_b32_e32 v148, 16, v93
	v_subrev_u32_e32 v145, s1, v145
	v_subrev_u32_e32 v146, s1, v146
	v_subrev_u32_e32 v147, s1, v147
	v_subrev_u32_e32 v148, s1, v148
	v_sub_u32_e32 v149, 0, v145
	v_sub_u32_e32 v158, 0, v146
	v_sub_u32_e32 v159, 0, v147
	v_sub_u32_e32 v160, 0, v148
	v_max_i32_e32 v149, v145, v149
	v_max_i32_e32 v158, v146, v158
	v_max_i32_e32 v159, v147, v159
	v_max_i32_e32 v160, v148, v160
	v_mul_u32_u24_e32 v161, v149, v149
	v_mul_u32_u24_e32 v162, v158, v158
	v_mul_u32_u24_e32 v163, v159, v159
	v_mul_u32_u24_e32 v164, v160, v160
	v_cvt_f32_u32_e32 v161, v161
	v_cvt_f32_u32_e32 v162, v162
	v_cvt_f32_u32_e32 v163, v163
	v_cvt_f32_u32_e32 v164, v164
	v_lshrrev_b32_e32 v161, 23, v161
	v_lshrrev_b32_e32 v162, 23, v162
	v_lshrrev_b32_e32 v163, 23, v163
	v_lshrrev_b32_e32 v164, 23, v164
	v_add_u32_e32 v161, 0xffffff83, v161
	v_add_u32_e32 v162, 0xffffff83, v162
	v_add_u32_e32 v163, 0xffffff83, v163
	v_add_u32_e32 v164, 0xffffff83, v164
	v_min_u32_e32 v161, 15, v161
	v_min_u32_e32 v162, 15, v162
	v_min_u32_e32 v163, 15, v163
	v_min_u32_e32 v164, 15, v164
	v_cmp_gt_u32_e32 vcc, 8, v149
	v_cmp_gt_u32_e64 s[26:27], 8, v158
	v_cmp_gt_u32_e64 s[36:37], 8, v159
	v_cmp_gt_u32_e64 s[38:39], 8, v160
	v_med3_i32 v165, v145, 0, 1
	v_med3_i32 v166, v146, 0, 1
	v_med3_i32 v167, v147, 0, 1
	v_med3_i32 v168, v148, 0, 1
	v_cndmask_b32_e64 v161, v161, v149, vcc
	v_cndmask_b32_e64 v162, v162, v158, s[26:27]
	v_cndmask_b32_e64 v163, v163, v159, s[36:37]
	v_cndmask_b32_e64 v164, v164, v160, s[38:39]
	v_lshl_add_u32 v161, v165, 4, v161
	v_lshl_add_u32 v162, v166, 4, v162
	v_lshl_add_u32 v163, v167, 4, v163
	v_lshl_add_u32 v164, v168, 4, v164
	v_lshl_add_u32 v165, v161, 5, v25
	v_lshl_add_u32 v166, v162, 5, v25
	v_lshl_add_u32 v167, v163, 5, v25
	v_lshl_add_u32 v168, v164, 5, v25
	ds_read_b32 v165, v165
	ds_read_b32 v166, v166
	ds_read_b32 v167, v167
	ds_read_b32 v168, v168
	s_waitcnt lgkmcnt(3)
	v_fma_mixlo_f16 v165, v88, s3, v165
	s_waitcnt lgkmcnt(2)
	v_fma_mixlo_f16 v166, v89, s3, v166
	s_waitcnt lgkmcnt(1)
	v_fma_mixlo_f16 v167, v90, s3, v167
	s_waitcnt lgkmcnt(0)
	v_fma_mixlo_f16 v168, v91, s3, v168
	ds_write_b16 v143, v165 offset:1792
	ds_write_b16 v143, v166 offset:1808
	ds_write_b16 v143, v167 offset:1824
	ds_write_b16 v143, v168 offset:1840
	s_mov_b64 exec, s[12:13]
	s_cmp_le_i32 s16, 8
	s_cbranch_scc1 .Lqk_done
	ds_read_b64 v[92:93], v142 offset:256
	s_cmp_gt_i32 s16, 10
	s_cbranch_scc0 .Lqk_ni_8
	v_add_lshl_u32 v117, s48, v117, 8
	v_add_u32_e32 v117, v144, v117
	global_load_dwordx4 v[72:75], v117, s[84:85]
	global_load_dwordx4 v[76:79], v117, s[84:85] offset:64
	global_load_dwordx4 v[80:83], v117, s[84:85] offset:128
	global_load_dwordx4 v[84:87], v117, s[84:85] offset:192
	s_waitcnt vmcnt(8)
	s_branch .Lqk_go_8
.Lqk_ni_8:
	s_cmp_gt_i32 s16, 9
	s_cbranch_scc0 .Lqk_nj_8
	s_waitcnt vmcnt(4)
	s_branch .Lqk_go_8

; __device__ __forceinline__ void dsa_unit(int wv, const Args& A, LAS unsigned char* lds, int s, int qt) {
;     ...
;         for (int kt = 0; kt < nt; ++kt) {
;             long k1[8];
;             DSA_LOADT(k1, kt + 1);
;             f32x4 a = {0.f, 0.f, 0.f, 0.f};
; #pragma unroll
;             for (int kk = 0; kk < 8; ++kk) a = __builtin_amdgcn_mfma_f32_16x16x32_fp8_fp8(kf[kk], qf[kk], a, 0, 0, 0);
;             if (fr < 8) {
; #pragma unroll
;                 for (int r = 0; r < 4; ++r) { const int e2 = kt * 16 + fq * 4 + r; const int key2 = lst[e2];
;                     Pw[e2 * 8 + fr] = (h16)(a[r] * 0.0625f + relb[rel_bucket(key2 - qpos) * 8 + fr]); } }
; #pragma unroll
;             for (int kk = 0; kk < 8; ++kk) kf[kk] = k1[kk];
;         }
.Lqk_go_8:
	v_mfma_f32_16x16x32_fp8_fp8 v[88:91], v[124:125], v[34:35], 0
	v_mfma_f32_16x16x32_fp8_fp8 v[88:91], v[126:127], v[32:33], v[88:91]
	v_mfma_f32_16x16x32_fp8_fp8 v[88:91], v[128:129], v[38:39], v[88:91]
	v_mfma_f32_16x16x32_fp8_fp8 v[88:91], v[130:131], v[36:37], v[88:91]
	v_mfma_f32_16x16x32_fp8_fp8 v[88:91], v[132:133], v[42:43], v[88:91]
	v_mfma_f32_16x16x32_fp8_fp8 v[88:91], v[134:135], v[40:41], v[88:91]
	v_mfma_f32_16x16x32_fp8_fp8 v[88:91], v[136:137], v[46:47], v[88:91]
	v_mfma_f32_16x16x32_fp8_fp8 v[88:91], v[138:139], v[44:45], v[88:91]
	s_and_saveexec_b64 s[12:13], s[8:9]
	s_waitcnt lgkmcnt(0)
	v_and_b32_e32 v145, 0xffff, v92
	v_lshrrev_b32_e32 v146, 16, v92
	v_and_b32_e32 v147, 0xffff, v93
	v_lshrrev_b32_e32 v148, 16, v93
	v_subrev_u32_e32 v145, s1, v145
	v_subrev_u32_e32 v146, s1, v146
	v_subrev_u32_e32 v147, s1, v147
	v_subrev_u32_e32 v148, s1, v148
	v_sub_u32_e32 v149, 0, v145
	v_sub_u32_e32 v158, 0, v146
	v_sub_u32_e32 v159, 0, v147
	v_sub_u32_e32 v160, 0, v148
	v_max_i32_e32 v149, v145, v149
	v_max_i32_e32 v158, v146, v158
	v_max_i32_e32 v159, v147, v159
	v_max_i32_e32 v160, v148, v160
	v_mul_u32_u24_e32 v161, v149, v149
	v_mul_u32_u24_e32 v162, v158, v158
	v_mul_u32_u24_e32 v163, v159, v159
	v_mul_u32_u24_e32 v164, v160, v160
	v_cvt_f32_u32_e32 v161, v161
	v_cvt_f32_u32_e32 v162, v162
	v_cvt_f32_u32_e32 v163, v163
	v_cvt_f32_u32_e32 v164, v164
	v_lshrrev_b32_e32 v161, 23, v161
	v_lshrrev_b32_e32 v162, 23, v162
	v_lshrrev_b32_e32 v163, 23, v163
	v_lshrrev_b32_e32 v164, 23, v164
	v_add_u32_e32 v161, 0xffffff83, v161
	v_add_u32_e32 v162, 0xffffff83, v162
	v_add_u32_e32 v163, 0xffffff83, v163
	v_add_u32_e32 v164, 0xffffff83, v164
	v_min_u32_e32 v161, 15, v161
	v_min_u32_e32 v162, 15, v162
	v_min_u32_e32 v163, 15, v163
	v_min_u32_e32 v164, 15, v164
	v_cmp_gt_u32_e32 vcc, 8, v149
	v_cmp_gt_u32_e64 s[26:27], 8, v158
	v_cmp_gt_u32_e64 s[36:37], 8, v159
	v_cmp_gt_u32_e64 s[38:39], 8, v160
	v_med3_i32 v165, v145, 0, 1
	v_med3_i32 v166, v146, 0, 1
	v_med3_i32 v167, v147, 0, 1
	v_med3_i32 v168, v148, 0, 1
	v_cndmask_b32_e64 v161, v161, v149, vcc
	v_cndmask_b32_e64 v162, v162, v158, s[26:27]
	v_cndmask_b32_e64 v163, v163, v159, s[36:37]
	v_cndmask_b32_e64 v164, v164, v160, s[38:39]
	v_lshl_add_u32 v161, v165, 4, v161
	v_lshl_add_u32 v162, v166, 4, v162
	v_lshl_add_u32 v163, v167, 4, v163
	v_lshl_add_u32 v164, v168, 4, v164
	v_lshl_add_u32 v165, v161, 5, v25
	v_lshl_add_u32 v166, v162, 5, v25
	v_lshl_add_u32 v167, v163, 5, v25
	v_lshl_add_u32 v168, v164, 5, v25
	ds_read_b32 v165, v165
	ds_read_b32 v166, v166
	ds_read_b32 v167, v167
	ds_read_b32 v168, v168
	s_waitcnt lgkmcnt(3)
	v_fma_mixlo_f16 v165, v88, s3, v165
	s_waitcnt lgkmcnt(2)
	v_fma_mixlo_f16 v166, v89, s3, v166
	s_waitcnt lgkmcnt(1)
	v_fma_mixlo_f16 v167, v90, s3, v167
	s_waitcnt lgkmcnt(0)
	v_fma_mixlo_f16 v168, v91, s3, v168
	ds_write_b16 v143, v165 offset:2048
	ds_write_b16 v143, v166 offset:2064
	ds_write_b16 v143, v167 offset:2080
	ds_write_b16 v143, v168 offset:2096
	s_mov_b64 exec, s[12:13]
	s_cmp_le_i32 s16, 9
	s_cbranch_scc1 .Lqk_done
	ds_read_b64 v[92:93], v142 offset:288
	s_cmp_gt_i32 s16, 11
	s_cbranch_scc0 .Lqk_ni_9
	v_add_lshl_u32 v118, s48, v118, 8
	v_add_u32_e32 v118, v144, v118
	global_load_dwordx4 v[124:127], v118, s[84:85]
	global_load_dwordx4 v[128:131], v118, s[84:85] offset:64
	global_load_dwordx4 v[132:135], v118, s[84:85] offset:128
	global_load_dwordx4 v[136:139], v118, s[84:85] offset:192
	s_waitcnt vmcnt(8)
	s_branch .Lqk_go_9
.Lqk_ni_9:
	s_cmp_gt_i32 s16, 10
	s_cbranch_scc0 .Lqk_nj_9
	s_waitcnt vmcnt(4)
	s_branch .Lqk_go_9

; __device__ __forceinline__ void dsa_unit(int wv, const Args& A, LAS unsigned char* lds, int s, int qt) {
;     ...
;         for (int kt = 0; kt < nt; ++kt) {
;             long k1[8];
;             DSA_LOADT(k1, kt + 1);
;             f32x4 a = {0.f, 0.f, 0.f, 0.f};
; #pragma unroll
;             for (int kk = 0; kk < 8; ++kk) a = __builtin_amdgcn_mfma_f32_16x16x32_fp8_fp8(kf[kk], qf[kk], a, 0, 0, 0);
;             if (fr < 8) {
; #pragma unroll
;                 for (int r = 0; r < 4; ++r) { const int e2 = kt * 16 + fq * 4 + r; const int key2 = lst[e2];
;                     Pw[e2 * 8 + fr] = (h16)(a[r] * 0.0625f + relb[rel_bucket(key2 - qpos) * 8 + fr]); } }
; #pragma unroll
;             for (int kk = 0; kk < 8; ++kk) kf[kk] = k1[kk];
;         }
.Lqk_go_9:
	v_mfma_f32_16x16x32_fp8_fp8 v[88:91], v[56:57], v[34:35], 0
	v_mfma_f32_16x16x32_fp8_fp8 v[88:91], v[58:59], v[32:33], v[88:91]
	v_mfma_f32_16x16x32_fp8_fp8 v[88:91], v[60:61], v[38:39], v[88:91]
	v_mfma_f32_16x16x32_fp8_fp8 v[88:91], v[62:63], v[36:37], v[88:91]
	v_mfma_f32_16x16x32_fp8_fp8 v[88:91], v[64:65], v[42:43], v[88:91]
	v_mfma_f32_16x16x32_fp8_fp8 v[88:91], v[66:67], v[40:41], v[88:91]
	v_mfma_f32_16x16x32_fp8_fp8 v[88:91], v[68:69], v[46:47], v[88:91]
	v_mfma_f32_16x16x32_fp8_fp8 v[88:91], v[70:71], v[44:45], v[88:91]
	s_and_saveexec_b64 s[12:13], s[8:9]
	s_waitcnt lgkmcnt(0)
	v_and_b32_e32 v145, 0xffff, v92
	v_lshrrev_b32_e32 v146, 16, v92
	v_and_b32_e32 v147, 0xffff, v93
	v_lshrrev_b32_e32 v148, 16, v93
	v_subrev_u32_e32 v145, s1, v145
	v_subrev_u32_e32 v146, s1, v146
	v_subrev_u32_e32 v147, s1, v147
	v_subrev_u32_e32 v148, s1, v148
	v_sub_u32_e32 v149, 0, v145
	v_sub_u32_e32 v158, 0, v146
	v_sub_u32_e32 v159, 0, v147
	v_sub_u32_e32 v160, 0, v148
	v_max_i32_e32 v149, v145, v149
	v_max_i32_e32 v158, v146, v158
	v_max_i32_e32 v159, v147, v159
	v_max_i32_e32 v160, v148, v160
	v_mul_u32_u24_e32 v161, v149, v149
	v_mul_u32_u24_e32 v162, v158, v158
	v_mul_u32_u24_e32 v163, v159, v159
	v_mul_u32_u24_e32 v164, v160, v160
	v_cvt_f32_u32_e32 v161, v161
	v_cvt_f32_u32_e32 v162, v162
	v_cvt_f32_u32_e32 v163, v163
	v_cvt_f32_u32_e32 v164, v164
	v_lshrrev_b32_e32 v161, 23, v161
	v_lshrrev_b32_e32 v162, 23, v162
	v_lshrrev_b32_e32 v163, 23, v163
	v_lshrrev_b32_e32 v164, 23, v164
	v_add_u32_e32 v161, 0xffffff83, v161
	v_add_u32_e32 v162, 0xffffff83, v162
	v_add_u32_e32 v163, 0xffffff83, v163
	v_add_u32_e32 v164, 0xffffff83, v164
	v_min_u32_e32 v161, 15, v161
	v_min_u32_e32 v162, 15, v162
	v_min_u32_e32 v163, 15, v163
	v_min_u32_e32 v164, 15, v164
	v_cmp_gt_u32_e32 vcc, 8, v149
	v_cmp_gt_u32_e64 s[26:27], 8, v158
	v_cmp_gt_u32_e64 s[36:37], 8, v159
	v_cmp_gt_u32_e64 s[38:39], 8, v160
	v_med3_i32 v165, v145, 0, 1
	v_med3_i32 v166, v146, 0, 1
	v_med3_i32 v167, v147, 0, 1
	v_med3_i32 v168, v148, 0, 1
	v_cndmask_b32_e64 v161, v161, v149, vcc
	v_cndmask_b32_e64 v162, v162, v158, s[26:27]
	v_cndmask_b32_e64 v163, v163, v159, s[36:37]
	v_cndmask_b32_e64 v164, v164, v160, s[38:39]
	v_lshl_add_u32 v161, v165, 4, v161
	v_lshl_add_u32 v162, v166, 4, v162
	v_lshl_add_u32 v163, v167, 4, v163
	v_lshl_add_u32 v164, v168, 4, v164
	v_lshl_add_u32 v165, v161, 5, v25
	v_lshl_add_u32 v166, v162, 5, v25
	v_lshl_add_u32 v167, v163, 5, v25
	v_lshl_add_u32 v168, v164, 5, v25
	ds_read_b32 v165, v165
	ds_read_b32 v166, v166
	ds_read_b32 v167, v167
	ds_read_b32 v168, v168
	s_waitcnt lgkmcnt(3)
	v_fma_mixlo_f16 v165, v88, s3, v165
	s_waitcnt lgkmcnt(2)
	v_fma_mixlo_f16 v166, v89, s3, v166
	s_waitcnt lgkmcnt(1)
	v_fma_mixlo_f16 v167, v90, s3, v167
	s_waitcnt lgkmcnt(0)
	v_fma_mixlo_f16 v168, v91, s3, v168
	ds_write_b16 v143, v165 offset:2304
	ds_write_b16 v143, v166 offset:2320
	ds_write_b16 v143, v167 offset:2336
	ds_write_b16 v143, v168 offset:2352
	s_mov_b64 exec, s[12:13]
	s_cmp_le_i32 s16, 10
	s_cbranch_scc1 .Lqk_done
	ds_read_b64 v[92:93], v142 offset:320
	s_cmp_gt_i32 s16, 12
	s_cbranch_scc0 .Lqk_ni_10
	v_add_lshl_u32 v119, s48, v119, 8
	v_add_u32_e32 v119, v144, v119
	global_load_dwordx4 v[56:59], v119, s[84:85]
	global_load_dwordx4 v[60:63], v119, s[84:85] offset:64
	global_load_dwordx4 v[64:67], v119, s[84:85] offset:128
	global_load_dwordx4 v[68:71], v119, s[84:85] offset:192
	s_waitcnt vmcnt(8)
	s_branch .Lqk_go_10
.Lqk_ni_10:
	s_cmp_gt_i32 s16, 11
	s_cbranch_scc0 .Lqk_nj_10
	s_waitcnt vmcnt(4)
	s_branch .Lqk_go_10

; __device__ __forceinline__ void dsa_unit(int wv, const Args& A, LAS unsigned char* lds, int s, int qt) {
;     ...
;         DSA_LOADT(kf, 0);
;         for (int kt = 0; kt < nt; ++kt) {
;             long k1[8];
;             DSA_LOADT(k1, kt + 1);
;             f32x4 a = {0.f, 0.f, 0.f, 0.f};
; #pragma unroll
;             for (int kk = 0; kk < 8; ++kk) a = __builtin_amdgcn_mfma_f32_16x16x32_fp8_fp8(kf[kk], qf[kk], a, 0, 0, 0);
;             if (fr < 8) {
; #pragma unroll
;                 for (int r = 0; r < 4; ++r) { const int e2 = kt * 16 + fq * 4 + r; const int key2 = lst[e2];
;                     Pw[e2 * 8 + fr] = (h16)(a[r] * 0.0625f + relb[rel_bucket(key2 - qpos) * 8 + fr]); } }
; #pragma unroll
;             for (int kk = 0; kk < 8; ++kk) kf[kk] = k1[kk];
;         }
.Lqk_go_10:
	v_mfma_f32_16x16x32_fp8_fp8 v[88:91], v[72:73], v[34:35], 0
	v_mfma_f32_16x16x32_fp8_fp8 v[88:91], v[74:75], v[32:33], v[88:91]
	v_mfma_f32_16x16x32_fp8_fp8 v[88:91], v[76:77], v[38:39], v[88:91]
	v_mfma_f32_16x16x32_fp8_fp8 v[88:91], v[78:79], v[36:37], v[88:91]
	v_mfma_f32_16x16x32_fp8_fp8 v[88:91], v[80:81], v[42:43], v[88:91]
	v_mfma_f32_16x16x32_fp8_fp8 v[88:91], v[82:83], v[40:41], v[88:91]
	v_mfma_f32_16x16x32_fp8_fp8 v[88:91], v[84:85], v[46:47], v[88:91]
	v_mfma_f32_16x16x32_fp8_fp8 v[88:91], v[86:87], v[44:45], v[88:91]
	s_and_saveexec_b64 s[12:13], s[8:9]
	s_waitcnt lgkmcnt(0)
	v_and_b32_e32 v145, 0xffff, v92
	v_lshrrev_b32_e32 v146, 16, v92
	v_and_b32_e32 v147, 0xffff, v93
	v_lshrrev_b32_e32 v148, 16, v93
	v_subrev_u32_e32 v145, s1, v145
	v_subrev_u32_e32 v146, s1, v146
	v_subrev_u32_e32 v147, s1, v147
	v_subrev_u32_e32 v148, s1, v148
	v_sub_u32_e32 v149, 0, v145
	v_sub_u32_e32 v158, 0, v146
	v_sub_u32_e32 v159, 0, v147
	v_sub_u32_e32 v160, 0, v148
	v_max_i32_e32 v149, v145, v149
	v_max_i32_e32 v158, v146, v158
	v_max_i32_e32 v159, v147, v159
	v_max_i32_e32 v160, v148, v160
	v_mul_u32_u24_e32 v161, v149, v149
	v_mul_u32_u24_e32 v162, v158, v158
	v_mul_u32_u24_e32 v163, v159, v159
	v_mul_u32_u24_e32 v164, v160, v160
	v_cvt_f32_u32_e32 v161, v161
	v_cvt_f32_u32_e32 v162, v162
	v_cvt_f32_u32_e32 v163, v163
	v_cvt_f32_u32_e32 v164, v164
	v_lshrrev_b32_e32 v161, 23, v161
	v_lshrrev_b32_e32 v162, 23, v162
	v_lshrrev_b32_e32 v163, 23, v163
	v_lshrrev_b32_e32 v164, 23, v164
	v_add_u32_e32 v161, 0xffffff83, v161
	v_add_u32_e32 v162, 0xffffff83, v162
	v_add_u32_e32 v163, 0xffffff83, v163
	v_add_u32_e32 v164, 0xffffff83, v164
	v_min_u32_e32 v161, 15, v161
	v_min_u32_e32 v162, 15, v162
	v_min_u32_e32 v163, 15, v163
	v_min_u32_e32 v164, 15, v164
	v_cmp_gt_u32_e32 vcc, 8, v149
	v_cmp_gt_u32_e64 s[26:27], 8, v158
	v_cmp_gt_u32_e64 s[36:37], 8, v159
	v_cmp_gt_u32_e64 s[38:39], 8, v160
	v_med3_i32 v165, v145, 0, 1
	v_med3_i32 v166, v146, 0, 1
	v_med3_i32 v167, v147, 0, 1
	v_med3_i32 v168, v148, 0, 1
	v_cndmask_b32_e64 v161, v161, v149, vcc
	v_cndmask_b32_e64 v162, v162, v158, s[26:27]
	v_cndmask_b32_e64 v163, v163, v159, s[36:37]
	v_cndmask_b32_e64 v164, v164, v160, s[38:39]
	v_lshl_add_u32 v161, v165, 4, v161
	v_lshl_add_u32 v162, v166, 4, v162
	v_lshl_add_u32 v163, v167, 4, v163
	v_lshl_add_u32 v164, v168, 4, v164
	v_lshl_add_u32 v165, v161, 5, v25
	v_lshl_add_u32 v166, v162, 5, v25
	v_lshl_add_u32 v167, v163, 5, v25
	v_lshl_add_u32 v168, v164, 5, v25
	ds_read_b32 v165, v165
	ds_read_b32 v166, v166
	ds_read_b32 v167, v167
	ds_read_b32 v168, v168
	s_waitcnt lgkmcnt(3)
	v_fma_mixlo_f16 v165, v88, s3, v165
	s_waitcnt lgkmcnt(2)
	v_fma_mixlo_f16 v166, v89, s3, v166
	s_waitcnt lgkmcnt(1)
	v_fma_mixlo_f16 v167, v90, s3, v167
	s_waitcnt lgkmcnt(0)
	v_fma_mixlo_f16 v168, v91, s3, v168
	ds_write_b16 v143, v165 offset:2560
	ds_write_b16 v143, v166 offset:2576
	ds_write_b16 v143, v167 offset:2592
	ds_write_b16 v143, v168 offset:2608
	s_mov_b64 exec, s[12:13]
	s_cmp_le_i32 s16, 11
	s_cbranch_scc1 .Lqk_done
	ds_read_b64 v[92:93], v142 offset:352
	s_cmp_gt_i32 s16, 13
	s_cbranch_scc0 .Lqk_ni_11
	v_add_lshl_u32 v120, s48, v120, 8
	v_add_u32_e32 v120, v144, v120
	global_load_dwordx4 v[72:75], v120, s[84:85]
	global_load_dwordx4 v[76:79], v120, s[84:85] offset:64
	global_load_dwordx4 v[80:83], v120, s[84:85] offset:128
	global_load_dwordx4 v[84:87], v120, s[84:85] offset:192
	s_waitcnt vmcnt(8)
	s_branch .Lqk_go_11
.Lqk_ni_11:
	s_cmp_gt_i32 s16, 12
	s_cbranch_scc0 .Lqk_nj_11
	s_waitcnt vmcnt(4)
	s_branch .Lqk_go_11

; __device__ __forceinline__ void dsa_unit(int wv, const Args& A, LAS unsigned char* lds, int s, int qt) {
;     ...
;         DSA_LOADT(kf, 0);
;         for (int kt = 0; kt < nt; ++kt) {
;             long k1[8];
;             DSA_LOADT(k1, kt + 1);
;             f32x4 a = {0.f, 0.f, 0.f, 0.f};
; #pragma unroll
;             for (int kk = 0; kk < 8; ++kk) a = __builtin_amdgcn_mfma_f32_16x16x32_fp8_fp8(kf[kk], qf[kk], a, 0, 0, 0);
;             if (fr < 8) {
; #pragma unroll
;                 for (int r = 0; r < 4; ++r) { const int e2 = kt * 16 + fq * 4 + r; const int key2 = lst[e2];
;                     Pw[e2 * 8 + fr] = (h16)(a[r] * 0.0625f + relb[rel_bucket(key2 - qpos) * 8 + fr]); } }
; #pragma unroll
;             for (int kk = 0; kk < 8; ++kk) kf[kk] = k1[kk];
;         }
.Lqk_go_11:
	v_mfma_f32_16x16x32_fp8_fp8 v[88:91], v[124:125], v[34:35], 0
	v_mfma_f32_16x16x32_fp8_fp8 v[88:91], v[126:127], v[32:33], v[88:91]
	v_mfma_f32_16x16x32_fp8_fp8 v[88:91], v[128:129], v[38:39], v[88:91]
	v_mfma_f32_16x16x32_fp8_fp8 v[88:91], v[130:131], v[36:37], v[88:91]
	v_mfma_f32_16x16x32_fp8_fp8 v[88:91], v[132:133], v[42:43], v[88:91]
	v_mfma_f32_16x16x32_fp8_fp8 v[88:91], v[134:135], v[40:41], v[88:91]
	v_mfma_f32_16x16x32_fp8_fp8 v[88:91], v[136:137], v[46:47], v[88:91]
	v_mfma_f32_16x16x32_fp8_fp8 v[88:91], v[138:139], v[44:45], v[88:91]
	s_and_saveexec_b64 s[12:13], s[8:9]
	s_waitcnt lgkmcnt(0)
	v_and_b32_e32 v145, 0xffff, v92
	v_lshrrev_b32_e32 v146, 16, v92
	v_and_b32_e32 v147, 0xffff, v93
	v_lshrrev_b32_e32 v148, 16, v93
	v_subrev_u32_e32 v145, s1, v145
	v_subrev_u32_e32 v146, s1, v146
	v_subrev_u32_e32 v147, s1, v147
	v_subrev_u32_e32 v148, s1, v148
	v_sub_u32_e32 v149, 0, v145
	v_sub_u32_e32 v158, 0, v146
	v_sub_u32_e32 v159, 0, v147
	v_sub_u32_e32 v160, 0, v148
	v_max_i32_e32 v149, v145, v149
	v_max_i32_e32 v158, v146, v158
	v_max_i32_e32 v159, v147, v159
	v_max_i32_e32 v160, v148, v160
	v_mul_u32_u24_e32 v161, v149, v149
	v_mul_u32_u24_e32 v162, v158, v158
	v_mul_u32_u24_e32 v163, v159, v159
	v_mul_u32_u24_e32 v164, v160, v160
	v_cvt_f32_u32_e32 v161, v161
	v_cvt_f32_u32_e32 v162, v162
	v_cvt_f32_u32_e32 v163, v163
	v_cvt_f32_u32_e32 v164, v164
	v_lshrrev_b32_e32 v161, 23, v161
	v_lshrrev_b32_e32 v162, 23, v162
	v_lshrrev_b32_e32 v163, 23, v163
	v_lshrrev_b32_e32 v164, 23, v164
	v_add_u32_e32 v161, 0xffffff83, v161
	v_add_u32_e32 v162, 0xffffff83, v162
	v_add_u32_e32 v163, 0xffffff83, v163
	v_add_u32_e32 v164, 0xffffff83, v164
	v_min_u32_e32 v161, 15, v161
	v_min_u32_e32 v162, 15, v162
	v_min_u32_e32 v163, 15, v163
	v_min_u32_e32 v164, 15, v164
	v_cmp_gt_u32_e32 vcc, 8, v149
	v_cmp_gt_u32_e64 s[26:27], 8, v158
	v_cmp_gt_u32_e64 s[36:37], 8, v159
	v_cmp_gt_u32_e64 s[38:39], 8, v160
	v_med3_i32 v165, v145, 0, 1
	v_med3_i32 v166, v146, 0, 1
	v_med3_i32 v167, v147, 0, 1
	v_med3_i32 v168, v148, 0, 1
	v_cndmask_b32_e64 v161, v161, v149, vcc
	v_cndmask_b32_e64 v162, v162, v158, s[26:27]
	v_cndmask_b32_e64 v163, v163, v159, s[36:37]
	v_cndmask_b32_e64 v164, v164, v160, s[38:39]
	v_lshl_add_u32 v161, v165, 4, v161
	v_lshl_add_u32 v162, v166, 4, v162
	v_lshl_add_u32 v163, v167, 4, v163
	v_lshl_add_u32 v164, v168, 4, v164
	v_lshl_add_u32 v165, v161, 5, v25
	v_lshl_add_u32 v166, v162, 5, v25
	v_lshl_add_u32 v167, v163, 5, v25
	v_lshl_add_u32 v168, v164, 5, v25
	ds_read_b32 v165, v165
	ds_read_b32 v166, v166
	ds_read_b32 v167, v167
	ds_read_b32 v168, v168
	s_waitcnt lgkmcnt(3)
	v_fma_mixlo_f16 v165, v88, s3, v165
	s_waitcnt lgkmcnt(2)
	v_fma_mixlo_f16 v166, v89, s3, v166
	s_waitcnt lgkmcnt(1)
	v_fma_mixlo_f16 v167, v90, s3, v167
	s_waitcnt lgkmcnt(0)
	v_fma_mixlo_f16 v168, v91, s3, v168
	ds_write_b16 v143, v165 offset:2816
	ds_write_b16 v143, v166 offset:2832
	ds_write_b16 v143, v167 offset:2848
	ds_write_b16 v143, v168 offset:2864
	s_mov_b64 exec, s[12:13]
	s_cmp_le_i32 s16, 12
	s_cbranch_scc1 .Lqk_done
	ds_read_b64 v[92:93], v142 offset:384
	s_cmp_gt_i32 s16, 14
	s_cbranch_scc0 .Lqk_ni_12
	v_add_lshl_u32 v121, s48, v121, 8
	v_add_u32_e32 v121, v144, v121
	global_load_dwordx4 v[124:127], v121, s[84:85]
	global_load_dwordx4 v[128:131], v121, s[84:85] offset:64
	global_load_dwordx4 v[132:135], v121, s[84:85] offset:128
	global_load_dwordx4 v[136:139], v121, s[84:85] offset:192
	s_waitcnt vmcnt(8)
	s_branch .Lqk_go_12
.Lqk_ni_12:
	s_cmp_gt_i32 s16, 13
	s_cbranch_scc0 .Lqk_nj_12
	s_waitcnt vmcnt(4)
	s_branch .Lqk_go_12

; __device__ __forceinline__ void dsa_unit(int wv, const Args& A, LAS unsigned char* lds, int s, int qt) {
;     ...
;         DSA_LOADT(kf, 0);
;         for (int kt = 0; kt < nt; ++kt) {
;             long k1[8];
;             DSA_LOADT(k1, kt + 1);
;             f32x4 a = {0.f, 0.f, 0.f, 0.f};
; #pragma unroll
;             for (int kk = 0; kk < 8; ++kk) a = __builtin_amdgcn_mfma_f32_16x16x32_fp8_fp8(kf[kk], qf[kk], a, 0, 0, 0);
;             if (fr < 8) {
; #pragma unroll
;                 for (int r = 0; r < 4; ++r) { const int e2 = kt * 16 + fq * 4 + r; const int key2 = lst[e2];
;                     Pw[e2 * 8 + fr] = (h16)(a[r] * 0.0625f + relb[rel_bucket(key2 - qpos) * 8 + fr]); } }
; #pragma unroll
;             for (int kk = 0; kk < 8; ++kk) kf[kk] = k1[kk];
;         }
.Lqk_go_12:
	v_mfma_f32_16x16x32_fp8_fp8 v[88:91], v[56:57], v[34:35], 0
	v_mfma_f32_16x16x32_fp8_fp8 v[88:91], v[58:59], v[32:33], v[88:91]
	v_mfma_f32_16x16x32_fp8_fp8 v[88:91], v[60:61], v[38:39], v[88:91]
	v_mfma_f32_16x16x32_fp8_fp8 v[88:91], v[62:63], v[36:37], v[88:91]
	v_mfma_f32_16x16x32_fp8_fp8 v[88:91], v[64:65], v[42:43], v[88:91]
	v_mfma_f32_16x16x32_fp8_fp8 v[88:91], v[66:67], v[40:41], v[88:91]
	v_mfma_f32_16x16x32_fp8_fp8 v[88:91], v[68:69], v[46:47], v[88:91]
	v_mfma_f32_16x16x32_fp8_fp8 v[88:91], v[70:71], v[44:45], v[88:91]
	s_and_saveexec_b64 s[12:13], s[8:9]
	s_waitcnt lgkmcnt(0)
	v_and_b32_e32 v145, 0xffff, v92
	v_lshrrev_b32_e32 v146, 16, v92
	v_and_b32_e32 v147, 0xffff, v93
	v_lshrrev_b32_e32 v148, 16, v93
	v_subrev_u32_e32 v145, s1, v145
	v_subrev_u32_e32 v146, s1, v146
	v_subrev_u32_e32 v147, s1, v147
	v_subrev_u32_e32 v148, s1, v148
	v_sub_u32_e32 v149, 0, v145
	v_sub_u32_e32 v158, 0, v146
	v_sub_u32_e32 v159, 0, v147
	v_sub_u32_e32 v160, 0, v148
	v_max_i32_e32 v149, v145, v149
	v_max_i32_e32 v158, v146, v158
	v_max_i32_e32 v159, v147, v159
	v_max_i32_e32 v160, v148, v160
	v_mul_u32_u24_e32 v161, v149, v149
	v_mul_u32_u24_e32 v162, v158, v158
	v_mul_u32_u24_e32 v163, v159, v159
	v_mul_u32_u24_e32 v164, v160, v160
	v_cvt_f32_u32_e32 v161, v161
	v_cvt_f32_u32_e32 v162, v162
	v_cvt_f32_u32_e32 v163, v163
	v_cvt_f32_u32_e32 v164, v164
	v_lshrrev_b32_e32 v161, 23, v161
	v_lshrrev_b32_e32 v162, 23, v162
	v_lshrrev_b32_e32 v163, 23, v163
	v_lshrrev_b32_e32 v164, 23, v164
	v_add_u32_e32 v161, 0xffffff83, v161
	v_add_u32_e32 v162, 0xffffff83, v162
	v_add_u32_e32 v163, 0xffffff83, v163
	v_add_u32_e32 v164, 0xffffff83, v164
	v_min_u32_e32 v161, 15, v161
	v_min_u32_e32 v162, 15, v162
	v_min_u32_e32 v163, 15, v163
	v_min_u32_e32 v164, 15, v164
	v_cmp_gt_u32_e32 vcc, 8, v149
	v_cmp_gt_u32_e64 s[26:27], 8, v158
	v_cmp_gt_u32_e64 s[36:37], 8, v159
	v_cmp_gt_u32_e64 s[38:39], 8, v160
	v_med3_i32 v165, v145, 0, 1
	v_med3_i32 v166, v146, 0, 1
	v_med3_i32 v167, v147, 0, 1
	v_med3_i32 v168, v148, 0, 1
	v_cndmask_b32_e64 v161, v161, v149, vcc
	v_cndmask_b32_e64 v162, v162, v158, s[26:27]
	v_cndmask_b32_e64 v163, v163, v159, s[36:37]
	v_cndmask_b32_e64 v164, v164, v160, s[38:39]
	v_lshl_add_u32 v161, v165, 4, v161
	v_lshl_add_u32 v162, v166, 4, v162
	v_lshl_add_u32 v163, v167, 4, v163
	v_lshl_add_u32 v164, v168, 4, v164
	v_lshl_add_u32 v165, v161, 5, v25
	v_lshl_add_u32 v166, v162, 5, v25
	v_lshl_add_u32 v167, v163, 5, v25
	v_lshl_add_u32 v168, v164, 5, v25
	ds_read_b32 v165, v165
	ds_read_b32 v166, v166
	ds_read_b32 v167, v167
	ds_read_b32 v168, v168
	s_waitcnt lgkmcnt(3)
	v_fma_mixlo_f16 v165, v88, s3, v165
	s_waitcnt lgkmcnt(2)
	v_fma_mixlo_f16 v166, v89, s3, v166
	s_waitcnt lgkmcnt(1)
	v_fma_mixlo_f16 v167, v90, s3, v167
	s_waitcnt lgkmcnt(0)
	v_fma_mixlo_f16 v168, v91, s3, v168
	ds_write_b16 v143, v165 offset:3072
	ds_write_b16 v143, v166 offset:3088
	ds_write_b16 v143, v167 offset:3104
	ds_write_b16 v143, v168 offset:3120
	s_mov_b64 exec, s[12:13]
	s_cmp_le_i32 s16, 13
	s_cbranch_scc1 .Lqk_done
	ds_read_b64 v[92:93], v142 offset:416
	s_cmp_gt_i32 s16, 15
	s_cbranch_scc0 .Lqk_ni_13
	v_add_lshl_u32 v122, s48, v122, 8
	v_add_u32_e32 v122, v144, v122
	global_load_dwordx4 v[56:59], v122, s[84:85]
	global_load_dwordx4 v[60:63], v122, s[84:85] offset:64
	global_load_dwordx4 v[64:67], v122, s[84:85] offset:128
	global_load_dwordx4 v[68:71], v122, s[84:85] offset:192
	s_waitcnt vmcnt(8)
	s_branch .Lqk_go_13
.Lqk_ni_13:
	s_cmp_gt_i32 s16, 14
	s_cbranch_scc0 .Lqk_nj_13
	s_waitcnt vmcnt(4)
	s_branch .Lqk_go_13

; __device__ __forceinline__ void dsa_unit(int wv, const Args& A, LAS unsigned char* lds, int s, int qt) {
;     ...
;         DSA_LOADT(kf, 0);
;         for (int kt = 0; kt < nt; ++kt) {
;             long k1[8];
;             DSA_LOADT(k1, kt + 1);
;             f32x4 a = {0.f, 0.f, 0.f, 0.f};
; #pragma unroll
;             for (int kk = 0; kk < 8; ++kk) a = __builtin_amdgcn_mfma_f32_16x16x32_fp8_fp8(kf[kk], qf[kk], a, 0, 0, 0);
;             if (fr < 8) {
; #pragma unroll
;                 for (int r = 0; r < 4; ++r) { const int e2 = kt * 16 + fq * 4 + r; const int key2 = lst[e2];
;                     Pw[e2 * 8 + fr] = (h16)(a[r] * 0.0625f + relb[rel_bucket(key2 - qpos) * 8 + fr]); } }
; #pragma unroll
;             for (int kk = 0; kk < 8; ++kk) kf[kk] = k1[kk];
;         }
.Lqk_go_13:
	v_mfma_f32_16x16x32_fp8_fp8 v[88:91], v[72:73], v[34:35], 0
	v_mfma_f32_16x16x32_fp8_fp8 v[88:91], v[74:75], v[32:33], v[88:91]
	v_mfma_f32_16x16x32_fp8_fp8 v[88:91], v[76:77], v[38:39], v[88:91]
	v_mfma_f32_16x16x32_fp8_fp8 v[88:91], v[78:79], v[36:37], v[88:91]
	v_mfma_f32_16x16x32_fp8_fp8 v[88:91], v[80:81], v[42:43], v[88:91]
	v_mfma_f32_16x16x32_fp8_fp8 v[88:91], v[82:83], v[40:41], v[88:91]
	v_mfma_f32_16x16x32_fp8_fp8 v[88:91], v[84:85], v[46:47], v[88:91]
	v_mfma_f32_16x16x32_fp8_fp8 v[88:91], v[86:87], v[44:45], v[88:91]
	s_and_saveexec_b64 s[12:13], s[8:9]
	s_waitcnt lgkmcnt(0)
	v_and_b32_e32 v145, 0xffff, v92
	v_lshrrev_b32_e32 v146, 16, v92
	v_and_b32_e32 v147, 0xffff, v93
	v_lshrrev_b32_e32 v148, 16, v93
	v_subrev_u32_e32 v145, s1, v145
	v_subrev_u32_e32 v146, s1, v146
	v_subrev_u32_e32 v147, s1, v147
	v_subrev_u32_e32 v148, s1, v148
	v_sub_u32_e32 v149, 0, v145
	v_sub_u32_e32 v158, 0, v146
	v_sub_u32_e32 v159, 0, v147
	v_sub_u32_e32 v160, 0, v148
	v_max_i32_e32 v149, v145, v149
	v_max_i32_e32 v158, v146, v158
	v_max_i32_e32 v159, v147, v159
	v_max_i32_e32 v160, v148, v160
	v_mul_u32_u24_e32 v161, v149, v149
	v_mul_u32_u24_e32 v162, v158, v158
	v_mul_u32_u24_e32 v163, v159, v159
	v_mul_u32_u24_e32 v164, v160, v160
	v_cvt_f32_u32_e32 v161, v161
	v_cvt_f32_u32_e32 v162, v162
	v_cvt_f32_u32_e32 v163, v163
	v_cvt_f32_u32_e32 v164, v164
	v_lshrrev_b32_e32 v161, 23, v161
	v_lshrrev_b32_e32 v162, 23, v162
	v_lshrrev_b32_e32 v163, 23, v163
	v_lshrrev_b32_e32 v164, 23, v164
	v_add_u32_e32 v161, 0xffffff83, v161
	v_add_u32_e32 v162, 0xffffff83, v162
	v_add_u32_e32 v163, 0xffffff83, v163
	v_add_u32_e32 v164, 0xffffff83, v164
	v_min_u32_e32 v161, 15, v161
	v_min_u32_e32 v162, 15, v162
	v_min_u32_e32 v163, 15, v163
	v_min_u32_e32 v164, 15, v164
	v_cmp_gt_u32_e32 vcc, 8, v149
	v_cmp_gt_u32_e64 s[26:27], 8, v158
	v_cmp_gt_u32_e64 s[36:37], 8, v159
	v_cmp_gt_u32_e64 s[38:39], 8, v160
	v_med3_i32 v165, v145, 0, 1
	v_med3_i32 v166, v146, 0, 1
	v_med3_i32 v167, v147, 0, 1
	v_med3_i32 v168, v148, 0, 1
	v_cndmask_b32_e64 v161, v161, v149, vcc
	v_cndmask_b32_e64 v162, v162, v158, s[26:27]
	v_cndmask_b32_e64 v163, v163, v159, s[36:37]
	v_cndmask_b32_e64 v164, v164, v160, s[38:39]
	v_lshl_add_u32 v161, v165, 4, v161
	v_lshl_add_u32 v162, v166, 4, v162
	v_lshl_add_u32 v163, v167, 4, v163
	v_lshl_add_u32 v164, v168, 4, v164
	v_lshl_add_u32 v165, v161, 5, v25
	v_lshl_add_u32 v166, v162, 5, v25
	v_lshl_add_u32 v167, v163, 5, v25
	v_lshl_add_u32 v168, v164, 5, v25
	ds_read_b32 v165, v165
	ds_read_b32 v166, v166
	ds_read_b32 v167, v167
	ds_read_b32 v168, v168
	s_waitcnt lgkmcnt(3)
	v_fma_mixlo_f16 v165, v88, s3, v165
	s_waitcnt lgkmcnt(2)
	v_fma_mixlo_f16 v166, v89, s3, v166
	s_waitcnt lgkmcnt(1)
	v_fma_mixlo_f16 v167, v90, s3, v167
	s_waitcnt lgkmcnt(0)
	v_fma_mixlo_f16 v168, v91, s3, v168
	ds_write_b16 v143, v165 offset:3328
	ds_write_b16 v143, v166 offset:3344
	ds_write_b16 v143, v167 offset:3360
	ds_write_b16 v143, v168 offset:3376
	s_mov_b64 exec, s[12:13]
	s_cmp_le_i32 s16, 14
	s_cbranch_scc1 .Lqk_done
	ds_read_b64 v[92:93], v142 offset:448
	s_cmp_gt_i32 s16, 15
	s_cbranch_scc0 .Lqk_nj_14
	s_waitcnt vmcnt(4)
	s_branch .Lqk_go_14

; __device__ __forceinline__ void dsa_unit(int wv, const Args& A, LAS unsigned char* lds, int s, int qt) {
;     ...
;         DSA_LOADT(kf, 0);
;         for (int kt = 0; kt < nt; ++kt) {
;             long k1[8];
;             DSA_LOADT(k1, kt + 1);
;             f32x4 a = {0.f, 0.f, 0.f, 0.f};
; #pragma unroll
;             for (int kk = 0; kk < 8; ++kk) a = __builtin_amdgcn_mfma_f32_16x16x32_fp8_fp8(kf[kk], qf[kk], a, 0, 0, 0);
;             if (fr < 8) {
; #pragma unroll
;                 for (int r = 0; r < 4; ++r) { const int e2 = kt * 16 + fq * 4 + r; const int key2 = lst[e2];
;                     Pw[e2 * 8 + fr] = (h16)(a[r] * 0.0625f + relb[rel_bucket(key2 - qpos) * 8 + fr]); } }
; #pragma unroll
;             for (int kk = 0; kk < 8; ++kk) kf[kk] = k1[kk];
;         }
.Lqk_go_14:
	v_mfma_f32_16x16x32_fp8_fp8 v[88:91], v[124:125], v[34:35], 0
	v_mfma_f32_16x16x32_fp8_fp8 v[88:91], v[126:127], v[32:33], v[88:91]
	v_mfma_f32_16x16x32_fp8_fp8 v[88:91], v[128:129], v[38:39], v[88:91]
	v_mfma_f32_16x16x32_fp8_fp8 v[88:91], v[130:131], v[36:37], v[88:91]
	v_mfma_f32_16x16x32_fp8_fp8 v[88:91], v[132:133], v[42:43], v[88:91]
	v_mfma_f32_16x16x32_fp8_fp8 v[88:91], v[134:135], v[40:41], v[88:91]
	v_mfma_f32_16x16x32_fp8_fp8 v[88:91], v[136:137], v[46:47], v[88:91]
	v_mfma_f32_16x16x32_fp8_fp8 v[88:91], v[138:139], v[44:45], v[88:91]
	s_and_saveexec_b64 s[12:13], s[8:9]
	s_waitcnt lgkmcnt(0)
	v_and_b32_e32 v145, 0xffff, v92
	v_lshrrev_b32_e32 v146, 16, v92
	v_and_b32_e32 v147, 0xffff, v93
	v_lshrrev_b32_e32 v148, 16, v93
	v_subrev_u32_e32 v145, s1, v145
	v_subrev_u32_e32 v146, s1, v146
	v_subrev_u32_e32 v147, s1, v147
	v_subrev_u32_e32 v148, s1, v148
	v_sub_u32_e32 v149, 0, v145
	v_sub_u32_e32 v158, 0, v146
	v_sub_u32_e32 v159, 0, v147
	v_sub_u32_e32 v160, 0, v148
	v_max_i32_e32 v149, v145, v149
	v_max_i32_e32 v158, v146, v158
	v_max_i32_e32 v159, v147, v159
	v_max_i32_e32 v160, v148, v160
	v_mul_u32_u24_e32 v161, v149, v149
	v_mul_u32_u24_e32 v162, v158, v158
	v_mul_u32_u24_e32 v163, v159, v159
	v_mul_u32_u24_e32 v164, v160, v160
	v_cvt_f32_u32_e32 v161, v161
	v_cvt_f32_u32_e32 v162, v162
	v_cvt_f32_u32_e32 v163, v163
	v_cvt_f32_u32_e32 v164, v164
	v_lshrrev_b32_e32 v161, 23, v161
	v_lshrrev_b32_e32 v162, 23, v162
	v_lshrrev_b32_e32 v163, 23, v163
	v_lshrrev_b32_e32 v164, 23, v164
	v_add_u32_e32 v161, 0xffffff83, v161
	v_add_u32_e32 v162, 0xffffff83, v162
	v_add_u32_e32 v163, 0xffffff83, v163
	v_add_u32_e32 v164, 0xffffff83, v164
	v_min_u32_e32 v161, 15, v161
	v_min_u32_e32 v162, 15, v162
	v_min_u32_e32 v163, 15, v163
	v_min_u32_e32 v164, 15, v164
	v_cmp_gt_u32_e32 vcc, 8, v149
	v_cmp_gt_u32_e64 s[26:27], 8, v158
	v_cmp_gt_u32_e64 s[36:37], 8, v159
	v_cmp_gt_u32_e64 s[38:39], 8, v160
	v_med3_i32 v165, v145, 0, 1
	v_med3_i32 v166, v146, 0, 1
	v_med3_i32 v167, v147, 0, 1
	v_med3_i32 v168, v148, 0, 1
	v_cndmask_b32_e64 v161, v161, v149, vcc
	v_cndmask_b32_e64 v162, v162, v158, s[26:27]
	v_cndmask_b32_e64 v163, v163, v159, s[36:37]
	v_cndmask_b32_e64 v164, v164, v160, s[38:39]
	v_lshl_add_u32 v161, v165, 4, v161
	v_lshl_add_u32 v162, v166, 4, v162
	v_lshl_add_u32 v163, v167, 4, v163
	v_lshl_add_u32 v164, v168, 4, v164
	v_lshl_add_u32 v165, v161, 5, v25
	v_lshl_add_u32 v166, v162, 5, v25
	v_lshl_add_u32 v167, v163, 5, v25
	v_lshl_add_u32 v168, v164, 5, v25
	ds_read_b32 v165, v165
	ds_read_b32 v166, v166
	ds_read_b32 v167, v167
	ds_read_b32 v168, v168
	s_waitcnt lgkmcnt(3)
	v_fma_mixlo_f16 v165, v88, s3, v165
	s_waitcnt lgkmcnt(2)
	v_fma_mixlo_f16 v166, v89, s3, v166
	s_waitcnt lgkmcnt(1)
	v_fma_mixlo_f16 v167, v90, s3, v167
	s_waitcnt lgkmcnt(0)
	v_fma_mixlo_f16 v168, v91, s3, v168
	ds_write_b16 v143, v165 offset:3584
	ds_write_b16 v143, v166 offset:3600
	ds_write_b16 v143, v167 offset:3616
	ds_write_b16 v143, v168 offset:3632
	s_mov_b64 exec, s[12:13]
	s_cmp_le_i32 s16, 15
	s_cbranch_scc1 .Lqk_done
	ds_read_b64 v[92:93], v142 offset:480
	s_waitcnt vmcnt(0)
.Lqk_go_15:
	v_mfma_f32_16x16x32_fp8_fp8 v[88:91], v[56:57], v[34:35], 0
	v_mfma_f32_16x16x32_fp8_fp8 v[88:91], v[58:59], v[32:33], v[88:91]
	v_mfma_f32_16x16x32_fp8_fp8 v[88:91], v[60:61], v[38:39], v[88:91]
	v_mfma_f32_16x16x32_fp8_fp8 v[88:91], v[62:63], v[36:37], v[88:91]
	v_mfma_f32_16x16x32_fp8_fp8 v[88:91], v[64:65], v[42:43], v[88:91]
	v_mfma_f32_16x16x32_fp8_fp8 v[88:91], v[66:67], v[40:41], v[88:91]
	v_mfma_f32_16x16x32_fp8_fp8 v[88:91], v[68:69], v[46:47], v[88:91]
	v_mfma_f32_16x16x32_fp8_fp8 v[88:91], v[70:71], v[44:45], v[88:91]
	s_and_saveexec_b64 s[12:13], s[8:9]
	s_waitcnt lgkmcnt(0)
	v_and_b32_e32 v145, 0xffff, v92
	v_lshrrev_b32_e32 v146, 16, v92
	v_and_b32_e32 v147, 0xffff, v93
	v_lshrrev_b32_e32 v148, 16, v93
	v_subrev_u32_e32 v145, s1, v145
	v_subrev_u32_e32 v146, s1, v146
	v_subrev_u32_e32 v147, s1, v147
	v_subrev_u32_e32 v148, s1, v148
	v_sub_u32_e32 v149, 0, v145
	v_sub_u32_e32 v158, 0, v146
	v_sub_u32_e32 v159, 0, v147
	v_sub_u32_e32 v160, 0, v148
	v_max_i32_e32 v149, v145, v149
	v_max_i32_e32 v158, v146, v158
	v_max_i32_e32 v159, v147, v159
	v_max_i32_e32 v160, v148, v160
	v_mul_u32_u24_e32 v161, v149, v149
	v_mul_u32_u24_e32 v162, v158, v158
	v_mul_u32_u24_e32 v163, v159, v159
	v_mul_u32_u24_e32 v164, v160, v160
	v_cvt_f32_u32_e32 v161, v161
	v_cvt_f32_u32_e32 v162, v162
	v_cvt_f32_u32_e32 v163, v163
	v_cvt_f32_u32_e32 v164, v164
	v_lshrrev_b32_e32 v161, 23, v161
	v_lshrrev_b32_e32 v162, 23, v162
	v_lshrrev_b32_e32 v163, 23, v163
	v_lshrrev_b32_e32 v164, 23, v164
	v_add_u32_e32 v161, 0xffffff83, v161
	v_add_u32_e32 v162, 0xffffff83, v162
	v_add_u32_e32 v163, 0xffffff83, v163
	v_add_u32_e32 v164, 0xffffff83, v164
	v_min_u32_e32 v161, 15, v161
	v_min_u32_e32 v162, 15, v162
	v_min_u32_e32 v163, 15, v163
	v_min_u32_e32 v164, 15, v164
	v_cmp_gt_u32_e32 vcc, 8, v149
	v_cmp_gt_u32_e64 s[26:27], 8, v158
	v_cmp_gt_u32_e64 s[36:37], 8, v159
	v_cmp_gt_u32_e64 s[38:39], 8, v160
	v_med3_i32 v165, v145, 0, 1
	v_med3_i32 v166, v146, 0, 1
	v_med3_i32 v167, v147, 0, 1
	v_med3_i32 v168, v148, 0, 1
	v_cndmask_b32_e64 v161, v161, v149, vcc
	v_cndmask_b32_e64 v162, v162, v158, s[26:27]
	v_cndmask_b32_e64 v163, v163, v159, s[36:37]
	v_cndmask_b32_e64 v164, v164, v160, s[38:39]
	v_lshl_add_u32 v161, v165, 4, v161
	v_lshl_add_u32 v162, v166, 4, v162
	v_lshl_add_u32 v163, v167, 4, v163
	v_lshl_add_u32 v164, v168, 4, v164
	v_lshl_add_u32 v165, v161, 5, v25
	v_lshl_add_u32 v166, v162, 5, v25
	v_lshl_add_u32 v167, v163, 5, v25
	v_lshl_add_u32 v168, v164, 5, v25
	ds_read_b32 v165, v165
	ds_read_b32 v166, v166
	ds_read_b32 v167, v167
	ds_read_b32 v168, v168
	s_waitcnt lgkmcnt(3)
	v_fma_mixlo_f16 v165, v88, s3, v165
	s_waitcnt lgkmcnt(2)
	v_fma_mixlo_f16 v166, v89, s3, v166
	s_waitcnt lgkmcnt(1)
	v_fma_mixlo_f16 v167, v90, s3, v167
	s_waitcnt lgkmcnt(0)
	v_fma_mixlo_f16 v168, v91, s3, v168
	ds_write_b16 v143, v165 offset:3840
	ds_write_b16 v143, v166 offset:3856
	ds_write_b16 v143, v167 offset:3872
	ds_write_b16 v143, v168 offset:3888
	s_mov_b64 exec, s[12:13]
; #define LAS __attribute__((address_space(3)))
; __device__ __forceinline__ void dsa_unit(int wv, const Args& A, LAS unsigned char* lds, int s, int qt) {
;     ...
;         { float v[4][8]; float m[8];
; #pragma unroll
;             for (int hh = 0; hh < 8; ++hh) m[hh] = -INFINITY;
; #pragma unroll
;             for (int i = 0; i < 4; ++i) { const int e = lane * 4 + i; const h16x8 hv = e < n ? *(const LAS h16x8*)(Pw + e * 8) : (h16x8){0, 0, 0, 0, 0, 0, 0, 0};
; #pragma unroll
;                 for (int j = 0; j < 8; ++j) { v[i][j] = e < n ? (float)hv[j] : -INFINITY; m[j] = fmaxf(m[j], v[i][j]); } }
;             float sm[8];
; #pragma unroll
;             for (int hh = 0; hh < 8; ++hh) { m[hh] = wave_max(m[hh]); sm[hh] = 0.f; }
.Lqk_done:
.LBB0_1458:
	v_cmp_gt_i32_e64 s[18:19], s29, v95
	v_mov_b32_e32 v10, 0
	v_mov_b32_e32 v14, 0
	v_mov_b32_e32 v15, 0
	v_mov_b32_e32 v16, 0
	v_mov_b32_e32 v17, 0
	s_and_saveexec_b64 s[12:13], s[18:19]
	v_add_u32_e32 v0, s28, v96
	ds_read_b128 v[14:17], v0
	s_or_b64 exec, exec, s[12:13]
	v_cmp_gt_i32_e64 s[16:17], s29, v97
	v_mov_b32_e32 v11, 0
	v_mov_b32_e32 v12, 0
	v_mov_b32_e32 v13, 0
	s_and_saveexec_b64 s[12:13], s[16:17]
	v_add_u32_e32 v0, s28, v98
	ds_read_b128 v[10:13], v0
	s_or_b64 exec, exec, s[12:13]
	v_cmp_gt_i32_e64 s[14:15], s29, v99
	v_mov_b32_e32 v2, 0
	v_mov_b32_e32 v6, 0
	v_mov_b32_e32 v7, 0
	v_mov_b32_e32 v8, 0
	v_mov_b32_e32 v9, 0
	s_and_saveexec_b64 s[12:13], s[14:15]
	v_add_u32_e32 v0, s28, v100
	ds_read_b128 v[6:9], v0
	s_or_b64 exec, exec, s[12:13]
	v_cmp_gt_i32_e64 s[12:13], s29, v101
	v_mov_b32_e32 v3, 0
	v_mov_b32_e32 v4, 0
	v_mov_b32_e32 v5, 0
	s_and_saveexec_b64 s[26:27], s[12:13]
	v_add_u32_e32 v0, s28, v102
	ds_read_b128 v[2:5], v0
	s_or_b64 exec, exec, s[26:27]
	s_waitcnt lgkmcnt(0)
	v_cvt_f32_f16_e32 v39, v6
	v_cvt_f32_f16_sdwa v6, v6 dst_sel:DWORD dst_unused:UNUSED_PAD src0_sel:WORD_1
	v_cvt_f32_f16_e32 v0, v14
	v_cvt_f32_f16_e32 v21, v10
	v_cndmask_b32_e64 v39, v151, v39, s[14:15]
	v_cndmask_b32_e64 v40, v151, v6, s[14:15]
	v_cvt_f32_f16_e32 v6, v7
	v_cndmask_b32_e64 v0, v151, v0, s[18:19]
	v_cndmask_b32_e64 v21, v151, v21, s[16:17]
	v_max3_f32 v44, v0, s53, v21
	v_cndmask_b32_e64 v42, v151, v6, s[14:15]
	v_cvt_f32_f16_sdwa v6, v7 dst_sel:DWORD dst_unused:UNUSED_PAD src0_sel:WORD_1
	v_cvt_f32_f16_sdwa v14, v14 dst_sel:DWORD dst_unused:UNUSED_PAD src0_sel:WORD_1
	v_cvt_f32_f16_sdwa v10, v10 dst_sel:DWORD dst_unused:UNUSED_PAD src0_sel:WORD_1
	v_cvt_f32_f16_e32 v18, v15
	v_cndmask_b32_e64 v43, v151, v6, s[14:15]
	v_cvt_f32_f16_e32 v6, v8
	v_cndmask_b32_e64 v14, v151, v14, s[18:19]
	v_cndmask_b32_e64 v32, v151, v10, s[16:17]
	v_max3_f32 v10, v14, s53, v32
	v_cndmask_b32_e64 v46, v151, v6, s[14:15]
	v_cvt_f32_f16_sdwa v6, v8 dst_sel:DWORD dst_unused:UNUSED_PAD src0_sel:WORD_1
	v_cvt_f32_f16_e32 v33, v11
	v_cndmask_b32_e64 v18, v151, v18, s[18:19]
	v_cvt_f32_f16_sdwa v15, v15 dst_sel:DWORD dst_unused:UNUSED_PAD src0_sel:WORD_1
	v_cndmask_b32_e64 v52, v151, v6, s[14:15]
	v_cvt_f32_f16_e32 v6, v9
	v_cndmask_b32_e64 v33, v151, v33, s[16:17]
	v_max3_f32 v45, v18, s53, v33
	v_cvt_f32_f16_sdwa v11, v11 dst_sel:DWORD dst_unused:UNUSED_PAD src0_sel:WORD_1
	v_cndmask_b32_e64 v53, v151, v6, s[14:15]
	v_cvt_f32_f16_sdwa v6, v9 dst_sel:DWORD dst_unused:UNUSED_PAD src0_sel:WORD_1
	v_cndmask_b32_e64 v15, v151, v15, s[18:19]
	v_cndmask_b32_e64 v34, v151, v11, s[16:17]
	v_max3_f32 v11, v15, s53, v34
	v_cndmask_b32_e64 v54, v151, v6, s[14:15]
	v_cvt_f32_f16_e32 v6, v2
	v_cvt_f32_f16_sdwa v2, v2 dst_sel:DWORD dst_unused:UNUSED_PAD src0_sel:WORD_1
	v_cvt_f32_f16_e32 v19, v16
	v_cvt_f32_f16_e32 v35, v12
	v_cndmask_b32_e64 v41, v151, v6, s[12:13]
	v_cndmask_b32_e64 v47, v151, v2, s[12:13]
	v_cvt_f32_f16_e32 v2, v3
	v_max3_f32 v6, v44, v39, v41
	v_max3_f32 v7, v10, v40, v47
	v_cndmask_b32_e64 v19, v151, v19, s[18:19]
	v_cndmask_b32_e64 v55, v151, v2, s[12:13]
	v_cvt_f32_f16_sdwa v2, v3 dst_sel:DWORD dst_unused:UNUSED_PAD src0_sel:WORD_1
	v_max3_f32 v8, v45, v42, v55
	v_cndmask_b32_e64 v35, v151, v35, s[16:17]
	v_max3_f32 v48, v19, s53, v35
	v_cndmask_b32_e64 v56, v151, v2, s[12:13]
	v_cvt_f32_f16_e32 v2, v4
	v_max3_f32 v9, v11, v43, v56
	v_cvt_f32_f16_sdwa v16, v16 dst_sel:DWORD dst_unused:UNUSED_PAD src0_sel:WORD_1
	v_cvt_f32_f16_sdwa v12, v12 dst_sel:DWORD dst_unused:UNUSED_PAD src0_sel:WORD_1
	v_cndmask_b32_e64 v57, v151, v2, s[12:13]
	v_cvt_f32_f16_sdwa v2, v4 dst_sel:DWORD dst_unused:UNUSED_PAD src0_sel:WORD_1
	v_max3_f32 v10, v48, v46, v57
	v_cndmask_b32_e64 v16, v151, v16, s[18:19]
	v_cndmask_b32_e64 v36, v151, v12, s[16:17]
	v_cndmask_b32_e64 v58, v151, v2, s[12:13]
	v_cvt_f32_f16_e32 v2, v5
	v_max3_f32 v12, v16, s53, v36
	v_max3_f32 v4, v12, v52, v58
	v_cvt_f32_f16_e32 v20, v17
	v_cndmask_b32_e64 v59, v151, v2, s[12:13]
	v_cvt_f32_f16_sdwa v2, v5 dst_sel:DWORD dst_unused:UNUSED_PAD src0_sel:WORD_1
	ds_bpermute_b32 v5, v171, v6
	v_cvt_f32_f16_e32 v37, v13
	v_cndmask_b32_e64 v20, v151, v20, s[18:19]
	v_cvt_f32_f16_sdwa v17, v17 dst_sel:DWORD dst_unused:UNUSED_PAD src0_sel:WORD_1
	v_cvt_f32_f16_sdwa v13, v13 dst_sel:DWORD dst_unused:UNUSED_PAD src0_sel:WORD_1
	s_waitcnt lgkmcnt(0)
	v_max_f32_e32 v5, v5, v5
	v_max_f32_e32 v5, v6, v5
	ds_bpermute_b32 v6, v172, v5
	v_cndmask_b32_e64 v37, v151, v37, s[16:17]
	v_max3_f32 v49, v20, s53, v37
	v_max3_f32 v3, v49, v53, v59
	v_cndmask_b32_e64 v17, v151, v17, s[18:19]
	s_waitcnt lgkmcnt(0)
	v_max_f32_e32 v6, v6, v6
	v_max_f32_e32 v5, v5, v6
	ds_bpermute_b32 v6, v173, v5
	v_cndmask_b32_e64 v38, v151, v13, s[16:17]
	v_max3_f32 v13, v17, s53, v38
	v_cndmask_b32_e64 v60, v151, v2, s[12:13]
	v_max3_f32 v2, v13, v54, v60
	s_waitcnt lgkmcnt(0)
	v_max_f32_e32 v6, v6, v6
	v_max_f32_e32 v5, v5, v6
	ds_bpermute_b32 v6, v174, v5
	s_waitcnt lgkmcnt(0)
	v_max_f32_e32 v6, v6, v6
	v_max_f32_e32 v5, v5, v6
	ds_bpermute_b32 v6, v175, v5
	s_waitcnt lgkmcnt(0)
	v_max_f32_e32 v6, v6, v6
	v_max_f32_e32 v5, v5, v6
	ds_bpermute_b32 v6, v176, v5
	s_waitcnt lgkmcnt(0)
	v_max_f32_e32 v6, v6, v6
	v_max_f32_e32 v61, v5, v6
	ds_bpermute_b32 v5, v171, v7
	v_sub_f32_e32 v0, v0, v61
	v_mul_f32_e32 v0, 0x3fb8aa3b, v0
	s_waitcnt lgkmcnt(0)
	v_max_f32_e32 v5, v5, v5
	v_max_f32_e32 v5, v7, v5
	ds_bpermute_b32 v6, v172, v5
	s_waitcnt lgkmcnt(0)
	v_max_f32_e32 v6, v6, v6
	v_max_f32_e32 v5, v5, v6
	ds_bpermute_b32 v6, v173, v5
	s_waitcnt lgkmcnt(0)
	v_max_f32_e32 v6, v6, v6
	v_max_f32_e32 v5, v5, v6
	ds_bpermute_b32 v6, v174, v5
	s_waitcnt lgkmcnt(0)
; __device__ __forceinline__ void dsa_unit(int wv, const Args& A, LAS unsigned char* lds, int s, int qt) {
;     ...
;             for (int hh = 0; hh < 8; ++hh) { m[hh] = wave_max(m[hh]); sm[hh] = 0.f; }
; #pragma unroll
;             for (int i = 0; i < 4; ++i)
; #pragma unroll
;                 for (int j = 0; j < 8; ++j) { const float p = __expf(v[i][j] - m[j]); v[i][j] = p; sm[j] += p; }
	v_max_f32_e32 v6, v6, v6
	v_max_f32_e32 v5, v5, v6
	ds_bpermute_b32 v6, v175, v5
	s_waitcnt lgkmcnt(0)
	v_max_f32_e32 v6, v6, v6
	v_max_f32_e32 v5, v5, v6
	ds_bpermute_b32 v6, v176, v5
	s_waitcnt lgkmcnt(0)
	v_max_f32_e32 v6, v6, v6
	v_max_f32_e32 v62, v5, v6
	ds_bpermute_b32 v5, v171, v8
	s_waitcnt lgkmcnt(0)
	v_max_f32_e32 v5, v5, v5
	v_max_f32_e32 v5, v8, v5
	ds_bpermute_b32 v6, v172, v5
	s_waitcnt lgkmcnt(0)
	v_max_f32_e32 v6, v6, v6
	v_max_f32_e32 v5, v5, v6
	ds_bpermute_b32 v6, v173, v5
	s_waitcnt lgkmcnt(0)
	v_max_f32_e32 v6, v6, v6
	v_max_f32_e32 v5, v5, v6
	ds_bpermute_b32 v6, v174, v5
	s_waitcnt lgkmcnt(0)
	v_max_f32_e32 v6, v6, v6
	v_max_f32_e32 v5, v5, v6
	ds_bpermute_b32 v6, v175, v5
	s_waitcnt lgkmcnt(0)
	v_max_f32_e32 v6, v6, v6
	v_max_f32_e32 v5, v5, v6
	ds_bpermute_b32 v6, v176, v5
	s_waitcnt lgkmcnt(0)
	v_max_f32_e32 v6, v6, v6
	v_max_f32_e32 v63, v5, v6
	ds_bpermute_b32 v5, v171, v9
	s_waitcnt lgkmcnt(0)
	v_max_f32_e32 v5, v5, v5
	v_max_f32_e32 v5, v9, v5
	ds_bpermute_b32 v6, v172, v5
	s_waitcnt lgkmcnt(0)
	v_max_f32_e32 v6, v6, v6
	v_max_f32_e32 v5, v5, v6
	ds_bpermute_b32 v6, v173, v5
	s_waitcnt lgkmcnt(0)
	v_max_f32_e32 v6, v6, v6
	v_max_f32_e32 v5, v5, v6
	ds_bpermute_b32 v6, v174, v5
	s_waitcnt lgkmcnt(0)
	v_max_f32_e32 v6, v6, v6
	v_max_f32_e32 v5, v5, v6
	ds_bpermute_b32 v6, v175, v5
	s_waitcnt lgkmcnt(0)
	v_max_f32_e32 v6, v6, v6
	v_max_f32_e32 v5, v5, v6
	ds_bpermute_b32 v6, v176, v5
	s_waitcnt lgkmcnt(0)
	v_max_f32_e32 v6, v6, v6
	v_max_f32_e32 v64, v5, v6
	ds_bpermute_b32 v5, v171, v10
	s_waitcnt lgkmcnt(0)
	v_max_f32_e32 v5, v5, v5
	v_max_f32_e32 v5, v10, v5
	ds_bpermute_b32 v6, v172, v5
	v_exp_f32_e32 v10, v0
	v_sub_f32_e32 v0, v14, v62
	v_mul_f32_e32 v0, 0x3fb8aa3b, v0
	v_exp_f32_e32 v11, v0
	s_waitcnt lgkmcnt(0)
	v_max_f32_e32 v6, v6, v6
	v_max_f32_e32 v5, v5, v6
	ds_bpermute_b32 v6, v173, v5
	v_sub_f32_e32 v0, v18, v63
	v_mul_f32_e32 v0, 0x3fb8aa3b, v0
	v_exp_f32_e32 v8, v0
	v_sub_f32_e32 v0, v15, v64
	s_waitcnt lgkmcnt(0)
	v_max_f32_e32 v6, v6, v6
	v_max_f32_e32 v5, v5, v6
	ds_bpermute_b32 v6, v174, v5
	v_mul_f32_e32 v0, 0x3fb8aa3b, v0
	v_exp_f32_e32 v9, v0
	v_pk_add_f32 v[12:13], v[10:11], 0 op_sel_hi:[1,0]
	s_waitcnt lgkmcnt(0)
	v_max_f32_e32 v6, v6, v6
	v_max_f32_e32 v5, v5, v6
	ds_bpermute_b32 v6, v175, v5
	v_pk_add_f32 v[14:15], v[8:9], 0 op_sel_hi:[1,0]
	s_waitcnt lgkmcnt(0)
	v_max_f32_e32 v6, v6, v6
	v_max_f32_e32 v5, v5, v6
	ds_bpermute_b32 v6, v176, v5
	s_waitcnt lgkmcnt(0)
	v_max_f32_e32 v6, v6, v6
	v_max_f32_e32 v65, v5, v6
	ds_bpermute_b32 v5, v171, v4
	v_sub_f32_e32 v0, v19, v65
	v_mul_f32_e32 v0, 0x3fb8aa3b, v0
	v_exp_f32_e32 v6, v0
	s_waitcnt lgkmcnt(0)
	v_max_f32_e32 v5, v5, v5
	v_max_f32_e32 v4, v4, v5
	ds_bpermute_b32 v5, v172, v4
	s_waitcnt lgkmcnt(0)
	v_max_f32_e32 v5, v5, v5
	v_max_f32_e32 v4, v4, v5
	ds_bpermute_b32 v5, v173, v4
	s_waitcnt lgkmcnt(0)
	v_max_f32_e32 v5, v5, v5
	v_max_f32_e32 v4, v4, v5
	ds_bpermute_b32 v5, v174, v4
	s_waitcnt lgkmcnt(0)
	v_max_f32_e32 v5, v5, v5
	v_max_f32_e32 v4, v4, v5
	ds_bpermute_b32 v5, v175, v4
	s_waitcnt lgkmcnt(0)
	v_max_f32_e32 v5, v5, v5
	v_max_f32_e32 v4, v4, v5
	ds_bpermute_b32 v5, v176, v4
	s_waitcnt lgkmcnt(0)
	v_max_f32_e32 v5, v5, v5
	v_max_f32_e32 v68, v4, v5
	ds_bpermute_b32 v4, v171, v3
	v_sub_f32_e32 v0, v16, v68
	v_mul_f32_e32 v0, 0x3fb8aa3b, v0
	v_exp_f32_e32 v7, v0
	s_waitcnt lgkmcnt(0)
	v_max_f32_e32 v4, v4, v4
	v_max_f32_e32 v3, v3, v4
	ds_bpermute_b32 v4, v172, v3
	s_waitcnt lgkmcnt(0)
	v_max_f32_e32 v4, v4, v4
	v_max_f32_e32 v3, v3, v4
	ds_bpermute_b32 v4, v173, v3
	s_waitcnt lgkmcnt(0)
	v_max_f32_e32 v4, v4, v4
	v_max_f32_e32 v3, v3, v4
	ds_bpermute_b32 v4, v174, v3
	s_waitcnt lgkmcnt(0)
	v_max_f32_e32 v4, v4, v4
	v_max_f32_e32 v3, v3, v4
	ds_bpermute_b32 v4, v175, v3
	s_waitcnt lgkmcnt(0)
	v_max_f32_e32 v4, v4, v4
	v_max_f32_e32 v3, v3, v4
	ds_bpermute_b32 v4, v176, v3
	s_waitcnt lgkmcnt(0)
	v_max_f32_e32 v4, v4, v4
	v_max_f32_e32 v69, v3, v4
	ds_bpermute_b32 v3, v171, v2
	v_sub_f32_e32 v0, v20, v69
	v_mul_f32_e32 v0, 0x3fb8aa3b, v0
	v_exp_f32_e32 v4, v0
	s_waitcnt lgkmcnt(0)
	v_max_f32_e32 v3, v3, v3
	v_max_f32_e32 v2, v2, v3
	ds_bpermute_b32 v3, v172, v2
	s_waitcnt lgkmcnt(0)
	v_max_f32_e32 v3, v3, v3
	v_max_f32_e32 v2, v2, v3
	ds_bpermute_b32 v3, v173, v2
	s_waitcnt lgkmcnt(0)
	v_max_f32_e32 v3, v3, v3
	v_max_f32_e32 v2, v2, v3
	ds_bpermute_b32 v3, v174, v2
	s_waitcnt lgkmcnt(0)
	v_max_f32_e32 v3, v3, v3
	v_max_f32_e32 v2, v2, v3
	ds_bpermute_b32 v3, v175, v2
	s_waitcnt lgkmcnt(0)
	v_max_f32_e32 v3, v3, v3
	v_max_f32_e32 v2, v2, v3
	ds_bpermute_b32 v3, v176, v2
	s_waitcnt lgkmcnt(0)
; __device__ __forceinline__ void dsa_unit(int wv, const Args& A, LAS unsigned char* lds, int s, int qt) {
;     ...
;                 for (int j = 0; j < 8; ++j) { const float p = __expf(v[i][j] - m[j]); v[i][j] = p; sm[j] += p; }
; #pragma unroll
;             for (int hh = 0; hh < 8; ++hh) sm[hh] = 1.f / wave_sum(sm[hh]);
	v_max_f32_e32 v3, v3, v3
	v_max_f32_e32 v70, v2, v3
	v_sub_f32_e32 v0, v17, v70
	v_mul_f32_e32 v0, 0x3fb8aa3b, v0
	v_exp_f32_e32 v5, v0
	v_sub_f32_e32 v0, v21, v61
	v_mul_f32_e32 v0, 0x3fb8aa3b, v0
	v_exp_f32_e32 v2, v0
	v_sub_f32_e32 v0, v32, v62
	v_mul_f32_e32 v0, 0x3fb8aa3b, v0
	v_exp_f32_e32 v3, v0
	v_sub_f32_e32 v0, v33, v63
	v_mul_f32_e32 v0, 0x3fb8aa3b, v0
	v_pk_add_f32 v[16:17], v[6:7], 0 op_sel_hi:[1,0]
	v_pk_add_f32 v[66:67], v[2:3], v[12:13]
	v_exp_f32_e32 v12, v0
	v_sub_f32_e32 v0, v34, v64
	v_mul_f32_e32 v0, 0x3fb8aa3b, v0
	v_exp_f32_e32 v13, v0
	v_sub_f32_e32 v0, v35, v65
	v_mul_f32_e32 v0, 0x3fb8aa3b, v0
	v_pk_add_f32 v[18:19], v[4:5], 0 op_sel_hi:[1,0]
	v_pk_add_f32 v[50:51], v[12:13], v[14:15]
	v_exp_f32_e32 v14, v0
	v_sub_f32_e32 v0, v36, v68
	v_mul_f32_e32 v0, 0x3fb8aa3b, v0
	v_exp_f32_e32 v15, v0
	v_sub_f32_e32 v0, v37, v69
	v_mul_f32_e32 v0, 0x3fb8aa3b, v0
	v_pk_add_f32 v[48:49], v[14:15], v[16:17]
	v_exp_f32_e32 v16, v0
	v_sub_f32_e32 v0, v38, v70
	v_mul_f32_e32 v0, 0x3fb8aa3b, v0
	v_exp_f32_e32 v17, v0
	v_sub_f32_e32 v0, v39, v61
	v_mul_f32_e32 v0, 0x3fb8aa3b, v0
	v_exp_f32_e32 v34, v0
	v_sub_f32_e32 v0, v40, v62
	v_mul_f32_e32 v0, 0x3fb8aa3b, v0
	v_exp_f32_e32 v35, v0
	v_sub_f32_e32 v0, v42, v63
	v_mul_f32_e32 v0, 0x3fb8aa3b, v0
	v_exp_f32_e32 v32, v0
	v_sub_f32_e32 v0, v43, v64
	v_mul_f32_e32 v0, 0x3fb8aa3b, v0
	v_exp_f32_e32 v33, v0
	v_sub_f32_e32 v0, v46, v65
	v_mul_f32_e32 v0, 0x3fb8aa3b, v0
	v_exp_f32_e32 v20, v0
	v_sub_f32_e32 v0, v52, v68
	v_mul_f32_e32 v0, 0x3fb8aa3b, v0
	v_exp_f32_e32 v21, v0
	v_sub_f32_e32 v0, v53, v69
	v_mul_f32_e32 v0, 0x3fb8aa3b, v0
	v_pk_add_f32 v[44:45], v[16:17], v[18:19]
	v_exp_f32_e32 v18, v0
	v_sub_f32_e32 v0, v54, v70
	v_mul_f32_e32 v0, 0x3fb8aa3b, v0
	v_exp_f32_e32 v19, v0
	v_sub_f32_e32 v0, v41, v61
	v_mul_f32_e32 v0, 0x3fb8aa3b, v0
	v_exp_f32_e32 v36, v0
	v_sub_f32_e32 v0, v47, v62
	v_mul_f32_e32 v0, 0x3fb8aa3b, v0
	v_exp_f32_e32 v37, v0
	v_pk_add_f32 v[46:47], v[34:35], v[66:67]
	v_sub_f32_e32 v0, v55, v63
	v_mul_f32_e32 v0, 0x3fb8aa3b, v0
	v_pk_add_f32 v[46:47], v[36:37], v[46:47]
	ds_bpermute_b32 v52, v171, v46
	ds_bpermute_b32 v53, v171, v47
	v_exp_f32_e32 v38, v0
	v_sub_f32_e32 v0, v56, v64
	v_mul_f32_e32 v0, 0x3fb8aa3b, v0
	v_exp_f32_e32 v39, v0
	s_waitcnt lgkmcnt(0)
	v_pk_add_f32 v[46:47], v[46:47], v[52:53]
	ds_bpermute_b32 v52, v172, v46
	ds_bpermute_b32 v53, v172, v47
	v_sub_f32_e32 v0, v57, v65
	v_mul_f32_e32 v0, 0x3fb8aa3b, v0
	v_exp_f32_e32 v40, v0
	v_sub_f32_e32 v0, v58, v68
	s_waitcnt lgkmcnt(0)
	v_pk_add_f32 v[46:47], v[46:47], v[52:53]
	ds_bpermute_b32 v52, v173, v46
	ds_bpermute_b32 v53, v173, v47
	v_mul_f32_e32 v0, 0x3fb8aa3b, v0
	v_exp_f32_e32 v41, v0
	v_sub_f32_e32 v0, v59, v69
	v_mul_f32_e32 v0, 0x3fb8aa3b, v0
	s_waitcnt lgkmcnt(0)
	v_pk_add_f32 v[46:47], v[46:47], v[52:53]
	ds_bpermute_b32 v52, v174, v46
	ds_bpermute_b32 v53, v174, v47
	v_exp_f32_e32 v42, v0
	v_sub_f32_e32 v0, v60, v70
	v_mul_f32_e32 v0, 0x3fb8aa3b, v0
	v_exp_f32_e32 v43, v0
	s_waitcnt lgkmcnt(0)
	v_pk_add_f32 v[46:47], v[46:47], v[52:53]
	ds_bpermute_b32 v52, v175, v46
	ds_bpermute_b32 v53, v175, v47
	v_pk_add_f32 v[50:51], v[32:33], v[50:51]
	v_pk_add_f32 v[48:49], v[20:21], v[48:49]
	v_pk_add_f32 v[50:51], v[38:39], v[50:51]
	v_pk_add_f32 v[48:49], v[40:41], v[48:49]
	s_waitcnt lgkmcnt(0)
	v_pk_add_f32 v[46:47], v[46:47], v[52:53]
	ds_bpermute_b32 v52, v176, v46
	ds_bpermute_b32 v53, v176, v47
	v_pk_add_f32 v[44:45], v[18:19], v[44:45]
	s_waitcnt lgkmcnt(0)
	v_pk_add_f32 v[46:47], v[46:47], v[52:53]
	s_nop 0
	v_div_scale_f32 v0, s[26:27], v47, v47, 1.0
	v_rcp_f32_e32 v52, v0
	v_pk_add_f32 v[44:45], v[42:43], v[44:45]
	v_fma_f32 v53, -v0, v52, 1.0
	v_fmac_f32_e32 v52, v53, v52
	v_div_scale_f32 v53, vcc, 1.0, v47, 1.0
	v_mul_f32_e32 v54, v53, v52
	v_fma_f32 v55, -v0, v54, v53
	v_fmac_f32_e32 v54, v55, v52
	v_fma_f32 v0, -v0, v54, v53
	v_div_fmas_f32 v0, v0, v52, v54
	v_div_fixup_f32 v47, v0, v47, 1.0
	v_div_scale_f32 v0, s[26:27], v46, v46, 1.0
	v_rcp_f32_e32 v52, v0
	s_nop 0
	v_fma_f32 v53, -v0, v52, 1.0
	v_fmac_f32_e32 v52, v53, v52
	v_div_scale_f32 v53, vcc, 1.0, v46, 1.0
	v_mul_f32_e32 v54, v53, v52
	v_fma_f32 v55, -v0, v54, v53
	v_fmac_f32_e32 v54, v55, v52
	v_fma_f32 v0, -v0, v54, v53
	v_div_fmas_f32 v0, v0, v52, v54
	ds_bpermute_b32 v52, v171, v50
	ds_bpermute_b32 v53, v171, v51
	v_div_fixup_f32 v46, v0, v46, 1.0
	s_waitcnt lgkmcnt(0)
	v_pk_add_f32 v[50:51], v[50:51], v[52:53]
	ds_bpermute_b32 v52, v172, v50
	ds_bpermute_b32 v53, v172, v51
	s_waitcnt lgkmcnt(0)
	v_pk_add_f32 v[50:51], v[50:51], v[52:53]
	ds_bpermute_b32 v52, v173, v50
	ds_bpermute_b32 v53, v173, v51
	s_waitcnt lgkmcnt(0)
	v_pk_add_f32 v[50:51], v[50:51], v[52:53]
	ds_bpermute_b32 v52, v174, v50
	ds_bpermute_b32 v53, v174, v51
	s_waitcnt lgkmcnt(0)
	v_pk_add_f32 v[50:51], v[50:51], v[52:53]
	ds_bpermute_b32 v52, v175, v50
	ds_bpermute_b32 v53, v175, v51
	s_waitcnt lgkmcnt(0)
; #define LAS __attribute__((address_space(3)))
; __device__ __forceinline__ void dsa_unit(int wv, const Args& A, LAS unsigned char* lds, int s, int qt) {
;     ...
;             for (int hh = 0; hh < 8; ++hh) sm[hh] = 1.f / wave_sum(sm[hh]);
; #pragma unroll
;             for (int i = 0; i < 4; ++i) { const int e = lane * 4 + i;
;                 if (e < n) { h16x8 o;
; #pragma unroll
;                     for (int j = 0; j < 8; ++j) o[j] = (h16)(v[i][j] * sm[j]);
;                     *(LAS h16x8*)(Pw + e * 8) = o; } } }
	v_pk_add_f32 v[50:51], v[50:51], v[52:53]
	ds_bpermute_b32 v52, v176, v50
	ds_bpermute_b32 v53, v176, v51
	s_waitcnt lgkmcnt(0)
	v_pk_add_f32 v[50:51], v[50:51], v[52:53]
	s_nop 0
	v_div_scale_f32 v0, s[26:27], v51, v51, 1.0
	v_rcp_f32_e32 v52, v0
	s_nop 0
	v_fma_f32 v53, -v0, v52, 1.0
	v_fmac_f32_e32 v52, v53, v52
	v_div_scale_f32 v53, vcc, 1.0, v51, 1.0
	v_mul_f32_e32 v54, v53, v52
	v_fma_f32 v55, -v0, v54, v53
	v_fmac_f32_e32 v54, v55, v52
	v_fma_f32 v0, -v0, v54, v53
	v_div_fmas_f32 v0, v0, v52, v54
	v_div_fixup_f32 v51, v0, v51, 1.0
	v_div_scale_f32 v0, s[26:27], v50, v50, 1.0
	v_rcp_f32_e32 v52, v0
	s_nop 0
	v_fma_f32 v53, -v0, v52, 1.0
	v_fmac_f32_e32 v52, v53, v52
	v_div_scale_f32 v53, vcc, 1.0, v50, 1.0
	v_mul_f32_e32 v54, v53, v52
	v_fma_f32 v55, -v0, v54, v53
	v_fmac_f32_e32 v54, v55, v52
	v_fma_f32 v0, -v0, v54, v53
	v_div_fmas_f32 v0, v0, v52, v54
	ds_bpermute_b32 v52, v171, v48
	ds_bpermute_b32 v53, v171, v49
	v_div_fixup_f32 v50, v0, v50, 1.0
	s_waitcnt lgkmcnt(0)
	v_pk_add_f32 v[48:49], v[48:49], v[52:53]
	ds_bpermute_b32 v52, v172, v48
	ds_bpermute_b32 v53, v172, v49
	s_waitcnt lgkmcnt(0)
	v_pk_add_f32 v[48:49], v[48:49], v[52:53]
	ds_bpermute_b32 v52, v173, v48
	ds_bpermute_b32 v53, v173, v49
	s_waitcnt lgkmcnt(0)
	v_pk_add_f32 v[48:49], v[48:49], v[52:53]
	ds_bpermute_b32 v52, v174, v48
	ds_bpermute_b32 v53, v174, v49
	s_waitcnt lgkmcnt(0)
	v_pk_add_f32 v[48:49], v[48:49], v[52:53]
	ds_bpermute_b32 v52, v175, v48
	ds_bpermute_b32 v53, v175, v49
	s_waitcnt lgkmcnt(0)
	v_pk_add_f32 v[48:49], v[48:49], v[52:53]
	ds_bpermute_b32 v52, v176, v48
	ds_bpermute_b32 v53, v176, v49
	s_waitcnt lgkmcnt(0)
	v_pk_add_f32 v[48:49], v[48:49], v[52:53]
	s_nop 0
	v_div_scale_f32 v0, s[26:27], v49, v49, 1.0
	v_rcp_f32_e32 v52, v0
	s_nop 0
	v_fma_f32 v53, -v0, v52, 1.0
	v_fmac_f32_e32 v52, v53, v52
	v_div_scale_f32 v53, vcc, 1.0, v49, 1.0
	v_mul_f32_e32 v54, v53, v52
	v_fma_f32 v55, -v0, v54, v53
	v_fmac_f32_e32 v54, v55, v52
	v_fma_f32 v0, -v0, v54, v53
	v_div_fmas_f32 v0, v0, v52, v54
	v_div_fixup_f32 v49, v0, v49, 1.0
	v_div_scale_f32 v0, s[26:27], v48, v48, 1.0
	v_rcp_f32_e32 v52, v0
	s_nop 0
	v_fma_f32 v53, -v0, v52, 1.0
	v_fmac_f32_e32 v52, v53, v52
	v_div_scale_f32 v53, vcc, 1.0, v48, 1.0
	v_mul_f32_e32 v54, v53, v52
	v_fma_f32 v55, -v0, v54, v53
	v_fmac_f32_e32 v54, v55, v52
	v_fma_f32 v0, -v0, v54, v53
	v_div_fmas_f32 v0, v0, v52, v54
	ds_bpermute_b32 v52, v171, v44
	ds_bpermute_b32 v53, v171, v45
	v_div_fixup_f32 v48, v0, v48, 1.0
	s_waitcnt lgkmcnt(0)
	v_pk_add_f32 v[44:45], v[44:45], v[52:53]
	ds_bpermute_b32 v52, v172, v44
	ds_bpermute_b32 v53, v172, v45
	s_waitcnt lgkmcnt(0)
	v_pk_add_f32 v[44:45], v[44:45], v[52:53]
	ds_bpermute_b32 v52, v173, v44
	ds_bpermute_b32 v53, v173, v45
	s_waitcnt lgkmcnt(0)
	v_pk_add_f32 v[44:45], v[44:45], v[52:53]
	ds_bpermute_b32 v52, v174, v44
	ds_bpermute_b32 v53, v174, v45
	s_waitcnt lgkmcnt(0)
	v_pk_add_f32 v[44:45], v[44:45], v[52:53]
	ds_bpermute_b32 v52, v175, v44
	ds_bpermute_b32 v53, v175, v45
	s_waitcnt lgkmcnt(0)
	v_pk_add_f32 v[44:45], v[44:45], v[52:53]
	ds_bpermute_b32 v52, v176, v44
	ds_bpermute_b32 v53, v176, v45
	s_waitcnt lgkmcnt(0)
	v_pk_add_f32 v[44:45], v[44:45], v[52:53]
	s_nop 0
	v_div_scale_f32 v0, s[26:27], v45, v45, 1.0
	v_rcp_f32_e32 v52, v0
	s_nop 0
	v_fma_f32 v53, -v0, v52, 1.0
	v_fmac_f32_e32 v52, v53, v52
	v_div_scale_f32 v53, vcc, 1.0, v45, 1.0
	v_mul_f32_e32 v54, v53, v52
	v_fma_f32 v55, -v0, v54, v53
	v_fmac_f32_e32 v54, v55, v52
	v_fma_f32 v0, -v0, v54, v53
	v_div_fmas_f32 v0, v0, v52, v54
	v_div_fixup_f32 v45, v0, v45, 1.0
	v_div_scale_f32 v0, s[26:27], v44, v44, 1.0
	v_rcp_f32_e32 v52, v0
	s_nop 0
	v_fma_f32 v53, -v0, v52, 1.0
	v_fmac_f32_e32 v52, v53, v52
	v_div_scale_f32 v53, vcc, 1.0, v44, 1.0
	v_mul_f32_e32 v54, v53, v52
	v_fma_f32 v55, -v0, v54, v53
	v_fmac_f32_e32 v54, v55, v52
	v_fma_f32 v0, -v0, v54, v53
	v_div_fmas_f32 v0, v0, v52, v54
	v_div_fixup_f32 v44, v0, v44, 1.0
	s_and_saveexec_b64 s[26:27], s[18:19]
	s_cbranch_execz .LBB0_1473
	v_fma_mixlo_f16 v0, v10, v46, 0
	v_mov_b32_e32 v10, v11
	v_mov_b32_e32 v11, v8
	v_pk_mov_b32 v[52:53], v[46:47], v[50:51] op_sel:[1,0]
	s_nop 0
	v_pk_mul_f32 v[10:11], v[10:11], v[52:53]
	v_pk_mov_b32 v[52:53], v[50:51], v[48:49] op_sel:[1,0]
	v_cvt_pk_f16_f32 v54, v10, v11
	v_mov_b32_e32 v10, v9
	v_mov_b32_e32 v11, v6
	v_pk_mul_f32 v[10:11], v[10:11], v[52:53]
	v_pack_b32_f16 v8, v0, v54
	v_cvt_pk_f16_f32 v0, v10, v11
	v_mov_b32_e32 v6, v7
	v_mov_b32_e32 v7, v4
	v_pk_mov_b32 v[10:11], v[48:49], v[44:45] op_sel:[1,0]
	v_alignbit_b32 v9, v0, v54, 16
	v_pk_mul_f32 v[6:7], v[6:7], v[10:11]
	s_nop 0
	v_cvt_pk_f16_f32 v4, v6, v7
	v_lshrrev_b32_e32 v11, 16, v4
	v_alignbit_b32 v10, v4, v0, 16
	v_fma_mixhi_f16 v11, v5, v45, 0
	v_add_u32_e32 v0, s28, v96
	ds_write_b128 v0, v[8:11]
	s_or_b64 exec, exec, s[26:27]
	s_and_saveexec_b64 s[18:19], s[16:17]
	s_cbranch_execnz .LBB0_1474
